# v54 + hyena complex-multiply peephole: 71 x (two pk_fma + mov) merged into one pk_fma with per-half neg modifiers
# speedup vs baseline: 1.0148x; 1.0043x over previous
; #define LAS __attribute__((address_space(3)))
; #define SINCOSPI(x, s, c) do { const float hx_ = 0.5f * (x); *(s) = __builtin_amdgcn_sinf(hx_); *(c) = __builtin_amdgcn_cosf(hx_); } while (0)
; #define OPAQUE_I(x) asm volatile("" : "+v"(x))
; template <int R, bool INV> DEV void dft_regs(cf (&v)[R]) {
; #pragma unroll
;     for (int s = R; s >= 2; s >>= 1) {
;         const int h = s >> 1;
; #pragma unroll
;         for (int b = 0; b < R; b += s) {
; #pragma unroll
;             for (int k = 0; k < h; ++k) {
;                 const cf a = v[b + k], c = v[b + k + h];
;                 v[b + k] = a + c;
;                 const cf d = a - c;
;                 const int m = k * (32 / s);
;                 const float wr = tw_cos(m), wi = INV ? tw_sin(m) : -tw_sin(m);
;                 v[b + k + h] = cf{d.x * wr - d.y * wi, d.x * wi + d.y * wr};
;             }
;         }
;     }
; }
; DEV void fft_i1x2(LAS cf* buf0, LAS cf* buf1, cf (&y0)[8], cf (&y1)[8], int tid) {
;     OPAQUE_I(tid);
;     float sn, cs; SINCOSPI(-(float)tid * (2.0f / 8192.0f), &sn, &cs);
;     const cf w = cf{cs, sn}; cf wp = cf{1.f, 0.f};
;     cf v[16], u[16];
;     const LAS cf* p0 = buf0 + PADI(tid); const LAS cf* p1 = buf1 + PADI(tid);
; #pragma unroll
;     for (int p = 0; p < 16; ++p) { v[p] = cmulc(p0[544 * p], wp); u[p] = cmulc(p1[544 * p], wp); wp = cmul(wp, w); }
;     dft_regs<16, true>(v); dft_regs<16, true>(u);
; #pragma unroll
;     for (int q = 0; q < 8; ++q) { y0[q] = v[BR16[q]]; y1[q] = u[BR16[q]]; }
.LBB0_518:
	v_pk_add_f32 v[126:127], v[76:77], v[100:101]
	v_pk_add_f32 v[76:77], v[76:77], v[100:101] neg_lo:[0,1] neg_hi:[0,1]
	s_mov_b32 s10, s85
	s_mov_b32 s8, s97
	v_mov_b32_e32 v164, v76
	v_mov_b32_e32 v165, v77
	s_xor_b64 s[2:3], s[22:23], -1
	v_pk_add_f32 v[76:77], v[78:79], v[112:113]
	v_pk_add_f32 v[78:79], v[78:79], v[112:113] neg_lo:[0,1] neg_hi:[0,1]
	s_lshl_b64 s[6:7], s[6:7], 2
	v_pk_mul_f32 v[100:101], v[78:79], s[84:85] op_sel_hi:[1,0]
	s_add_u32 s22, s76, s6
	v_pk_fma_f32 v[112:113], v[78:79], s[10:11], v[100:101] op_sel:[0,0,1] op_sel_hi:[1,0,0] neg_lo:[0,0,1]
	s_addc_u32 s23, s77, s7
	v_pk_add_f32 v[78:79], v[82:83], v[116:117]
	v_pk_add_f32 v[82:83], v[82:83], v[116:117] neg_lo:[0,1] neg_hi:[0,1]
	s_add_u32 s6, s74, s6
	v_pk_mul_f32 v[100:101], v[82:83], s[8:9] op_sel_hi:[1,0]
	s_waitcnt lgkmcnt(0)
	v_pk_fma_f32 v[116:117], v[82:83], s[8:9], v[100:101] op_sel:[0,0,1] op_sel_hi:[1,0,0] neg_lo:[0,0,1] neg_hi:[0,0,1]
	v_pk_fma_f32 v[82:83], v[82:83], s[8:9], v[100:101] op_sel_hi:[1,0,0]
	v_pk_add_f32 v[100:101], v[84:85], v[118:119]
	v_pk_add_f32 v[84:85], v[84:85], v[118:119] neg_lo:[0,1] neg_hi:[0,1]
	v_mov_b32_e32 v117, v83
	v_pk_mul_f32 v[118:119], v[84:85], s[10:11] op_sel_hi:[1,0]
	s_barrier
	v_pk_fma_f32 v[166:167], v[84:85], s[84:85], v[118:119] op_sel:[0,0,1] op_sel_hi:[1,0,0] neg_lo:[0,0,1]
	v_pk_add_f32 v[84:85], v[86:87], v[120:121]
	v_pk_add_f32 v[86:87], v[86:87], v[120:121] neg_lo:[0,1] neg_hi:[0,1]
	s_addc_u32 s7, s75, s7
	v_pk_add_f32 v[118:119], v[86:87], 0 op_sel:[1,0] op_sel_hi:[0,0] neg_lo:[1,0]
	s_mov_b32 s19, 1
	v_pk_add_f32 v[86:87], v[90:91], v[122:123]
	v_pk_add_f32 v[90:91], v[90:91], v[122:123] neg_lo:[0,1] neg_hi:[0,1]
	v_pk_add_f32 v[122:123], v[98:99], v[92:93]
	v_pk_add_f32 v[92:93], v[98:99], v[92:93] neg_lo:[0,1] neg_hi:[0,1]
	v_pk_mul_f32 v[120:121], v[90:91], s[24:25] op_sel:[1,0]
	v_pk_mul_f32 v[98:99], v[92:93], s[84:85] op_sel:[1,0]
	v_pk_fma_f32 v[90:91], v[90:91], s[0:1], v[120:121] op_sel_hi:[0,1,1] neg_lo:[0,0,1] neg_hi:[0,0,1]
	v_pk_fma_f32 v[92:93], v[92:93], s[88:89], v[98:99] op_sel_hi:[0,1,1] neg_lo:[0,0,1] neg_hi:[0,0,1]
	v_pk_add_f32 v[98:99], v[126:127], v[84:85]
	v_pk_add_f32 v[84:85], v[126:127], v[84:85] neg_lo:[0,1] neg_hi:[0,1]
	v_pk_add_f32 v[120:121], v[94:95], v[124:125]
	v_pk_add_f32 v[94:95], v[94:95], v[124:125] neg_lo:[0,1] neg_hi:[0,1]
	v_mul_f32_e32 v82, 0x3f3504f3, v95
	v_mov_b32_e32 v126, v84
	v_mov_b32_e32 v127, v85
	v_pk_fma_f32 v[94:95], v[94:95], s[96:97], v[82:83] op_sel_hi:[0,1,0] neg_lo:[0,0,1] neg_hi:[0,0,1]
	v_pk_add_f32 v[84:85], v[76:77], v[86:87]
	v_pk_add_f32 v[76:77], v[76:77], v[86:87] neg_lo:[0,1] neg_hi:[0,1]
	v_pk_add_f32 v[82:83], v[116:117], v[94:95]
	v_pk_mul_f32 v[86:87], v[76:77], s[8:9] op_sel_hi:[1,0]
	s_mov_b64 s[26:27], -1
	v_pk_fma_f32 v[124:125], v[76:77], s[8:9], v[86:87] op_sel:[0,0,1] op_sel_hi:[1,0,0] neg_lo:[0,0,1] neg_hi:[0,0,1]
	v_pk_fma_f32 v[76:77], v[76:77], s[8:9], v[86:87] op_sel_hi:[1,0,0]
	v_pk_add_f32 v[86:87], v[78:79], v[120:121]
	v_pk_add_f32 v[78:79], v[78:79], v[120:121] neg_lo:[0,1] neg_hi:[0,1]
	v_mov_b32_e32 v125, v77
	v_pk_add_f32 v[120:121], v[78:79], 0 op_sel:[1,0] op_sel_hi:[0,0] neg_lo:[1,0]
	v_pk_add_f32 v[78:79], v[100:101], v[122:123]
	v_pk_add_f32 v[100:101], v[100:101], v[122:123] neg_lo:[0,1] neg_hi:[0,1]
	v_pk_add_f32 v[122:123], v[164:165], v[118:119]
	v_pk_add_f32 v[118:119], v[164:165], v[118:119] neg_lo:[0,1] neg_hi:[0,1]
	v_mul_f32_e32 v76, 0x3f3504f3, v101
	v_pk_fma_f32 v[100:101], v[100:101], s[96:97], v[76:77] op_sel_hi:[0,1,0] neg_lo:[0,0,1] neg_hi:[0,0,1]
	v_mov_b32_e32 v168, v118
	v_mov_b32_e32 v169, v119
	v_pk_add_f32 v[118:119], v[112:113], v[90:91]
	v_pk_add_f32 v[90:91], v[112:113], v[90:91] neg_lo:[0,1] neg_hi:[0,1]
	v_pk_mul_f32 v[112:113], v[90:91], s[8:9] op_sel_hi:[1,0]
	v_pk_fma_f32 v[164:165], v[90:91], s[8:9], v[112:113] op_sel:[0,0,1] op_sel_hi:[1,0,0] neg_lo:[0,0,1]
	v_pk_add_f32 v[112:113], v[98:99], v[86:87]
	v_pk_add_f32 v[86:87], v[98:99], v[86:87] neg_lo:[0,1] neg_hi:[0,1]
	v_pk_add_f32 v[90:91], v[116:117], v[94:95] neg_lo:[0,1] neg_hi:[0,1]
	v_mov_b32_e32 v116, v86
	v_mov_b32_e32 v117, v87
	v_pk_add_f32 v[98:99], v[126:127], v[120:121] neg_lo:[0,1] neg_hi:[0,1]
	v_pk_add_f32 v[86:87], v[84:85], v[78:79]
	v_pk_add_f32 v[78:79], v[84:85], v[78:79] neg_lo:[0,1] neg_hi:[0,1]
	v_pk_add_f32 v[94:95], v[90:91], 0 op_sel:[1,0] op_sel_hi:[0,0] neg_lo:[1,0]
	v_pk_add_f32 v[84:85], v[78:79], 0 op_sel:[1,0] op_sel_hi:[0,0] neg_lo:[1,0]
	v_pk_add_f32 v[78:79], v[126:127], v[120:121]
	v_pk_add_f32 v[90:91], v[166:167], v[92:93]
	v_pk_add_f32 v[92:93], v[166:167], v[92:93] neg_lo:[0,1] neg_hi:[0,1]
	v_mov_b32_e32 v126, v98
	v_mov_b32_e32 v127, v99
	v_mul_f32_e32 v76, 0x3f3504f3, v93
	v_pk_add_f32 v[98:99], v[124:125], v[100:101] neg_lo:[0,1] neg_hi:[0,1]
	v_pk_fma_f32 v[92:93], v[92:93], s[96:97], v[76:77] op_sel_hi:[0,1,0] neg_lo:[0,0,1] neg_hi:[0,0,1]
	v_pk_add_f32 v[76:77], v[124:125], v[100:101]
	v_pk_add_f32 v[100:101], v[98:99], 0 op_sel:[1,0] op_sel_hi:[0,0] neg_lo:[1,0]
	v_pk_add_f32 v[120:121], v[122:123], v[82:83]
	v_pk_add_f32 v[82:83], v[122:123], v[82:83] neg_lo:[0,1] neg_hi:[0,1]
	v_pk_add_f32 v[124:125], v[168:169], v[94:95]
	v_mov_b32_e32 v122, v82
	v_mov_b32_e32 v123, v83
	v_pk_add_f32 v[98:99], v[78:79], v[76:77]
	v_pk_add_f32 v[82:83], v[118:119], v[90:91]
	v_pk_add_f32 v[90:91], v[118:119], v[90:91] neg_lo:[0,1] neg_hi:[0,1]
	v_pk_add_f32 v[76:77], v[16:17], v[88:89]
	v_pk_add_f32 v[118:119], v[90:91], 0 op_sel:[1,0] op_sel_hi:[0,0] neg_lo:[1,0]
	v_pk_add_f32 v[16:17], v[16:17], v[88:89] neg_lo:[0,1] neg_hi:[0,1]
	v_pk_add_f32 v[90:91], v[168:169], v[94:95] neg_lo:[0,1] neg_hi:[0,1]
; #define LAS __attribute__((address_space(3)))
; #define U2F(x) __uint_as_float(x)
; template <int R, bool INV> DEV void dft_regs(cf (&v)[R]) {
; #pragma unroll
;     for (int s = R; s >= 2; s >>= 1) {
;         const int h = s >> 1;
; #pragma unroll
;         for (int b = 0; b < R; b += s) {
; #pragma unroll
;             for (int k = 0; k < h; ++k) {
;                 const cf a = v[b + k], c = v[b + k + h];
;                 v[b + k] = a + c;
;                 const cf d = a - c;
;                 const int m = k * (32 / s);
;                 const float wr = tw_cos(m), wi = INV ? tw_sin(m) : -tw_sin(m);
;                 v[b + k + h] = cf{d.x * wr - d.y * wi, d.x * wi + d.y * wr};
;             }
;         }
;     }
; }
; template <int MODE> DEV void hyena_conv_rows(const LAS unsigned char* lds, int slot0, float w0, float w1, float w2, float bs, cf (&z)[2][8], const cf (&y)[2][8], float hb, int tid) {
; #pragma unroll
;     for (int b = 0; b < 4; ++b) {
;         const LAS bf16_t* row = (const LAS bf16_t*)(lds + (slot0 + b) * 8192);
; #pragma unroll
;         for (int i = 0; i < 8; ++i) {
;             const int t = tid + 512 * i, par = tid & 1, d0 = (tid >> 1) + par;
;             const LAS unsigned* rw = (const LAS unsigned*)row + d0;
;             const unsigned dw0 = (i == 0) ? rw[d0 > 0 ? -1 : 0] : rw[256 * i - 1], dw1 = rw[256 * i];
;             float um = par ? U2F(dw0 << 16) : U2F(dw0 & 0xffff0000u);
;             const float u0 = par ? U2F(dw0 & 0xffff0000u) : U2F(dw1 << 16);
;             float up = par ? U2F(dw1 << 16) : U2F(dw1 & 0xffff0000u);
;             um = (t > 0) ? um : 0.f; up = (t < 4095) ? up : 0.f;
;             const float r = um * w0 + u0 * w1 + up * w2 + bs;
;             if (MODE == 0) { if (b & 1) z[b >> 1][i].y = r; else z[b >> 1][i].x = r; }
;             else { if (b & 1) z[b >> 1][i].y = r * (y[b >> 1][i].y + hb * z[b >> 1][i].y); else z[b >> 1][i].x = r * (y[b >> 1][i].x + hb * z[b >> 1][i].x); }
	v_pk_add_f32 v[112:113], v[112:113], v[86:87]
	v_mov_b32_e32 v166, v90
	v_mov_b32_e32 v167, v91
	v_pk_add_f32 v[94:95], v[164:165], v[92:93]
	v_pk_add_f32 v[90:91], v[164:165], v[92:93] neg_lo:[0,1] neg_hi:[0,1]
	v_pk_add_f32 v[92:93], v[116:117], v[84:85]
	v_mov_b32_e32 v84, v16
	v_mov_b32_e32 v85, v17
	v_pk_add_f32 v[164:165], v[90:91], 0 op_sel:[1,0] op_sel_hi:[0,0] neg_lo:[1,0]
	v_pk_add_f32 v[16:17], v[18:19], v[96:97]
	v_pk_add_f32 v[18:19], v[18:19], v[96:97] neg_lo:[0,1] neg_hi:[0,1]
	v_pk_mul_f32 v[78:79], v[18:19], s[84:85] op_sel_hi:[1,0]
	v_pk_fma_f32 v[88:89], v[18:19], s[10:11], v[78:79] op_sel:[0,0,1] op_sel_hi:[1,0,0] neg_lo:[0,0,1]
	v_pk_add_f32 v[90:91], v[122:123], v[118:119]
	v_pk_add_f32 v[18:19], v[66:67], v[102:103]
	v_pk_add_f32 v[66:67], v[66:67], v[102:103] neg_lo:[0,1] neg_hi:[0,1]
	v_pk_add_f32 v[86:87], v[126:127], v[100:101]
	v_pk_mul_f32 v[78:79], v[66:67], s[8:9] op_sel_hi:[1,0]
	v_pk_add_f32 v[100:101], v[120:121], v[82:83]
	v_pk_fma_f32 v[96:97], v[66:67], s[8:9], v[78:79] op_sel:[0,0,1] op_sel_hi:[1,0,0] neg_lo:[0,0,1]
	v_pk_add_f32 v[94:95], v[124:125], v[94:95]
	v_pk_add_f32 v[66:67], v[68:69], v[104:105]
	v_pk_add_f32 v[68:69], v[68:69], v[104:105] neg_lo:[0,1] neg_hi:[0,1]
	v_pk_add_f32 v[82:83], v[166:167], v[164:165]
	v_pk_mul_f32 v[78:79], v[68:69], s[10:11] op_sel_hi:[1,0]
	v_pk_fma_f32 v[102:103], v[68:69], s[84:85], v[78:79] op_sel:[0,0,1] op_sel_hi:[1,0,0] neg_lo:[0,0,1]
	v_pk_add_f32 v[68:69], v[70:71], v[106:107]
	v_pk_add_f32 v[70:71], v[70:71], v[106:107] neg_lo:[0,1] neg_hi:[0,1]
	v_pk_add_f32 v[78:79], v[70:71], 0 op_sel:[1,0] op_sel_hi:[0,0] neg_lo:[1,0]
	v_pk_add_f32 v[70:71], v[72:73], v[108:109]
	v_pk_add_f32 v[72:73], v[72:73], v[108:109] neg_lo:[0,1] neg_hi:[0,1]
	v_pk_add_f32 v[120:121], v[84:85], v[78:79]
	v_pk_mul_f32 v[104:105], v[72:73], s[24:25] op_sel:[1,0]
	v_pk_fma_f32 v[72:73], v[72:73], s[0:1], v[104:105] op_sel_hi:[0,1,1] neg_lo:[0,0,1] neg_hi:[0,0,1]
	v_pk_add_f32 v[104:105], v[74:75], v[110:111]
	v_pk_add_f32 v[74:75], v[74:75], v[110:111] neg_lo:[0,1] neg_hi:[0,1]
	v_pk_add_f32 v[116:117], v[18:19], v[104:105]
	v_mul_f32_e32 v106, 0x3f3504f3, v75
	v_pk_fma_f32 v[74:75], v[74:75], s[96:97], v[106:107] op_sel_hi:[0,1,0] neg_lo:[0,0,1] neg_hi:[0,0,1]
	v_pk_add_f32 v[106:107], v[80:81], v[114:115]
	v_pk_add_f32 v[80:81], v[80:81], v[114:115] neg_lo:[0,1] neg_hi:[0,1]
	v_pk_add_f32 v[118:119], v[66:67], v[106:107]
	v_pk_mul_f32 v[108:109], v[80:81], s[84:85] op_sel:[1,0]
	v_pk_fma_f32 v[80:81], v[80:81], s[88:89], v[108:109] op_sel_hi:[0,1,1] neg_lo:[0,0,1] neg_hi:[0,0,1]
	v_pk_add_f32 v[108:109], v[76:77], v[68:69]
	v_pk_add_f32 v[68:69], v[76:77], v[68:69] neg_lo:[0,1] neg_hi:[0,1]
	v_mov_b32_e32 v110, v68
	v_mov_b32_e32 v111, v69
	v_pk_add_f32 v[76:77], v[16:17], v[70:71]
	v_pk_add_f32 v[16:17], v[16:17], v[70:71] neg_lo:[0,1] neg_hi:[0,1]
	v_pk_mul_f32 v[68:69], v[16:17], s[8:9] op_sel_hi:[1,0]
	v_pk_fma_f32 v[114:115], v[16:17], s[8:9], v[68:69] op_sel:[0,0,1] op_sel_hi:[1,0,0] neg_lo:[0,0,1]
	v_pk_add_f32 v[16:17], v[18:19], v[104:105] neg_lo:[0,1] neg_hi:[0,1]
	v_pk_add_f32 v[104:105], v[16:17], 0 op_sel:[1,0] op_sel_hi:[0,0] neg_lo:[1,0]
	v_pk_add_f32 v[16:17], v[66:67], v[106:107] neg_lo:[0,1] neg_hi:[0,1]
	v_mul_f32_e32 v18, 0x3f3504f3, v17
	v_pk_fma_f32 v[106:107], v[16:17], s[96:97], v[18:19] op_sel_hi:[0,1,0] neg_lo:[0,0,1] neg_hi:[0,0,1]
	v_pk_add_f32 v[16:17], v[84:85], v[78:79] neg_lo:[0,1] neg_hi:[0,1]
	v_pk_add_f32 v[84:85], v[88:89], v[72:73]
	v_mov_b32_e32 v78, v16
	v_mov_b32_e32 v79, v17
	v_pk_add_f32 v[16:17], v[88:89], v[72:73] neg_lo:[0,1] neg_hi:[0,1]
	v_pk_add_f32 v[88:89], v[96:97], v[74:75]
	v_pk_mul_f32 v[18:19], v[16:17], s[8:9] op_sel_hi:[1,0]
	v_pk_fma_f32 v[72:73], v[16:17], s[8:9], v[18:19] op_sel:[0,0,1] op_sel_hi:[1,0,0] neg_lo:[0,0,1]
	v_pk_add_f32 v[16:17], v[96:97], v[74:75] neg_lo:[0,1] neg_hi:[0,1]
	v_pk_add_f32 v[96:97], v[102:103], v[80:81]
	v_pk_fma_f32 v[74:75], v[16:17], 0, v[16:17] op_sel:[0,0,1] op_sel_hi:[1,0,0] neg_lo:[0,0,1] neg_hi:[0,0,1]
	v_pk_fma_f32 v[16:17], v[16:17], 0, v[16:17] op_sel:[0,0,1] op_sel_hi:[1,0,0]
	global_load_dword v18, v20, s[22:23]
	global_load_dword v66, v245, s[22:23]
	global_load_dword v16, v206, s[22:23]
	s_add_i32 s22, s5, s78
	s_ashr_i32 s23, s22, 31
	s_lshl_b64 s[22:23], s[22:23], 2
	s_add_u32 s22, s72, s22
	s_addc_u32 s23, s73, s23
	global_load_dword v68, v20, s[6:7]
	global_load_dword v70, v20, s[22:23]
	v_pk_add_f32 v[80:81], v[102:103], v[80:81] neg_lo:[0,1] neg_hi:[0,1]
	v_mov_b32_e32 v75, v17
	v_mul_f32_e32 v102, 0x3f3504f3, v81
	v_pk_fma_f32 v[80:81], v[80:81], s[96:97], v[102:103] op_sel_hi:[0,1,0] neg_lo:[0,0,1] neg_hi:[0,0,1]
	v_pk_add_f32 v[102:103], v[108:109], v[116:117]
	v_pk_add_f32 v[108:109], v[108:109], v[116:117] neg_lo:[0,1] neg_hi:[0,1]
	v_pk_add_f32 v[124:125], v[78:79], v[74:75]
	v_pk_add_f32 v[74:75], v[78:79], v[74:75] neg_lo:[0,1] neg_hi:[0,1]
	v_mov_b32_e32 v122, v108
	v_mov_b32_e32 v123, v109
	v_pk_add_f32 v[108:109], v[76:77], v[118:119]
	v_pk_add_f32 v[76:77], v[76:77], v[118:119] neg_lo:[0,1] neg_hi:[0,1]
	v_mov_b32_e32 v126, v74
	v_mov_b32_e32 v127, v75
	v_pk_add_f32 v[116:117], v[76:77], 0 op_sel:[1,0] op_sel_hi:[0,0] neg_lo:[1,0]
	v_pk_add_f32 v[76:77], v[110:111], v[104:105]
	v_pk_add_f32 v[104:105], v[110:111], v[104:105] neg_lo:[0,1] neg_hi:[0,1]
	v_pk_add_f32 v[78:79], v[122:123], v[116:117]
	v_mov_b32_e32 v118, v104
	v_mov_b32_e32 v119, v105
	v_pk_add_f32 v[164:165], v[72:73], v[80:81]
	v_pk_add_f32 v[104:105], v[114:115], v[106:107]
	v_pk_add_f32 v[106:107], v[114:115], v[106:107] neg_lo:[0,1] neg_hi:[0,1]
	v_pk_add_f32 v[72:73], v[72:73], v[80:81] neg_lo:[0,1] neg_hi:[0,1]
	v_pk_add_f32 v[110:111], v[106:107], 0 op_sel:[1,0] op_sel_hi:[0,0] neg_lo:[1,0]
	v_pk_add_f32 v[80:81], v[124:125], v[164:165]
	v_pk_add_f32 v[106:107], v[120:121], v[88:89]
	v_pk_add_f32 v[88:89], v[120:121], v[88:89] neg_lo:[0,1] neg_hi:[0,1]
	v_pk_add_f32 v[74:75], v[118:119], v[110:111]
	v_pk_fma_f32 v[166:167], v[72:73], 0, v[72:73] op_sel:[0,0,1] op_sel_hi:[1,0,0] neg_lo:[0,0,1]
	v_mov_b32_e32 v120, v88
	v_mov_b32_e32 v121, v89
	v_pk_add_f32 v[88:89], v[84:85], v[96:97]
	v_pk_add_f32 v[84:85], v[84:85], v[96:97] neg_lo:[0,1] neg_hi:[0,1]
	v_pk_add_f32 v[96:97], v[102:103], v[108:109]
	ds_read2st64_b32 v[102:103], v130 offset1:32
	v_pk_add_f32 v[114:115], v[84:85], 0 op_sel:[1,0] op_sel_hi:[0,0] neg_lo:[1,0]
	v_pk_add_f32 v[88:89], v[106:107], v[88:89]
	v_pk_add_f32 v[84:85], v[76:77], v[104:105]
	ds_read2st64_b32 v[104:105], v129 offset1:32
	s_waitcnt lgkmcnt(1)
; #define LAS __attribute__((address_space(3)))
; #define U2F(x) __uint_as_float(x)
; template <int MODE> DEV void hyena_conv_rows(const LAS unsigned char* lds, int slot0, float w0, float w1, float w2, float bs, cf (&z)[2][8], const cf (&y)[2][8], float hb, int tid) {
; #pragma unroll
;     for (int b = 0; b < 4; ++b) {
;         const LAS bf16_t* row = (const LAS bf16_t*)(lds + (slot0 + b) * 8192);
; #pragma unroll
;         for (int i = 0; i < 8; ++i) {
;             const int t = tid + 512 * i, par = tid & 1, d0 = (tid >> 1) + par;
;             const LAS unsigned* rw = (const LAS unsigned*)row + d0;
;             const unsigned dw0 = (i == 0) ? rw[d0 > 0 ? -1 : 0] : rw[256 * i - 1], dw1 = rw[256 * i];
;             float um = par ? U2F(dw0 << 16) : U2F(dw0 & 0xffff0000u);
;             const float u0 = par ? U2F(dw0 & 0xffff0000u) : U2F(dw1 << 16);
;             float up = par ? U2F(dw1 << 16) : U2F(dw1 & 0xffff0000u);
;             um = (t > 0) ? um : 0.f; up = (t < 4095) ? up : 0.f;
;             const float r = um * w0 + u0 * w1 + up * w2 + bs;
;             if (MODE == 0) { if (b & 1) z[b >> 1][i].y = r; else z[b >> 1][i].x = r; }
;             else { if (b & 1) z[b >> 1][i].y = r * (y[b >> 1][i].y + hb * z[b >> 1][i].y); else z[b >> 1][i].x = r * (y[b >> 1][i].x + hb * z[b >> 1][i].x); }
;         }
;     }
; }
	v_and_b32_e32 v17, 0xffff0000, v103
	v_and_b32_e32 v19, 0xffff0000, v102
	v_lshlrev_b32_e32 v67, 16, v103
	v_lshlrev_b32_e32 v69, 16, v102
	v_cndmask_b32_e64 v69, v69, v19, s[38:39]
	v_cndmask_b32_e64 v67, v67, v17, s[38:39]
	v_cndmask_b32_e64 v103, 0, v67, s[40:41]
	v_cndmask_b32_e64 v102, 0, v69, s[40:41]
	s_waitcnt lgkmcnt(0)
	v_lshlrev_b32_e32 v67, 16, v104
	v_lshlrev_b32_e32 v69, 16, v105
	v_cndmask_b32_e64 v107, v17, v69, s[38:39]
	v_cndmask_b32_e64 v106, v19, v67, s[38:39]
	v_and_b32_e32 v17, 0xffff0000, v105
	v_cndmask_b32_e64 v17, v69, v17, s[38:39]
	v_cndmask_b32_e64 v105, 0, v17, s[42:43]
	v_pk_add_f32 v[76:77], v[120:121], v[114:115]
	s_waitcnt vmcnt(3)
	v_pk_mul_f32 v[106:107], v[66:67], v[106:107] op_sel_hi:[0,1]
	v_pk_fma_f32 v[102:103], v[18:19], v[102:103], v[106:107] op_sel_hi:[0,1,1]
	v_and_b32_e32 v19, 0xffff0000, v104
	v_cndmask_b32_e64 v19, v67, v19, s[38:39]
	v_cndmask_b32_e64 v104, 0, v19, s[42:43]
	s_waitcnt vmcnt(2)
	v_pk_fma_f32 v[102:103], v[16:17], v[104:105], v[102:103] op_sel_hi:[0,1,1]
	s_waitcnt vmcnt(1)
	v_pk_add_f32 v[102:103], v[68:69], v[102:103] op_sel_hi:[0,1]
	s_waitcnt vmcnt(0)
	v_pk_fma_f32 v[24:25], v[24:25], v[70:71], v[112:113] op_sel_hi:[1,0,1]
	v_pk_fma_f32 v[30:31], v[30:31], v[70:71], v[100:101] op_sel_hi:[1,0,1]
	v_pk_mul_f32 v[24:25], v[24:25], v[102:103]
	ds_read2_b32 v[106:107], v138 offset1:1
	ds_read2_b32 v[108:109], v131 offset1:1
	ds_read2_b32 v[110:111], v135 offset1:1
	ds_read2_b32 v[102:103], v136 offset1:1
	ds_read2_b32 v[104:105], v137 offset1:1
	s_waitcnt lgkmcnt(4)
	v_and_b32_e32 v17, 0xffff0000, v106
	s_waitcnt lgkmcnt(3)
	v_and_b32_e32 v19, 0xffff0000, v108
	v_lshlrev_b32_e32 v67, 16, v106
	v_lshlrev_b32_e32 v69, 16, v108
	v_cndmask_b32_e64 v69, v69, v19, s[38:39]
	v_cndmask_b32_e64 v67, v67, v17, s[38:39]
	v_cndmask_b32_e64 v119, 0, v67, s[44:45]
	v_cndmask_b32_e64 v118, 0, v69, s[44:45]
	v_lshlrev_b32_e32 v67, 16, v109
	v_lshlrev_b32_e32 v69, 16, v107
	v_cndmask_b32_e64 v121, v17, v69, s[38:39]
	v_cndmask_b32_e64 v120, v19, v67, s[38:39]
	ds_read2_b32 v[112:113], v132 offset1:1
	ds_read2_b32 v[114:115], v133 offset1:1
	ds_read2_b32 v[116:117], v134 offset1:1
	v_pk_mul_f32 v[120:121], v[66:67], v[120:121] op_sel_hi:[0,1]
	ds_read2_b32 v[100:101], v139 offset1:1
	v_pk_fma_f32 v[118:119], v[18:19], v[118:119], v[120:121] op_sel_hi:[0,1,1]
	v_and_b32_e32 v17, 0xffff0000, v107
	v_and_b32_e32 v19, 0xffff0000, v109
	v_cndmask_b32_e64 v19, v67, v19, s[38:39]
	v_cndmask_b32_e64 v17, v69, v17, s[38:39]
	v_cndmask_b32_e64 v107, 0, v17, s[46:47]
	v_cndmask_b32_e64 v106, 0, v19, s[46:47]
	v_pk_fma_f32 v[106:107], v[16:17], v[106:107], v[118:119] op_sel_hi:[0,1,1]
	v_pk_add_f32 v[106:107], v[68:69], v[106:107] op_sel_hi:[0,1]
	s_waitcnt lgkmcnt(0)
	v_and_b32_e32 v17, 0xffff0000, v100
	v_and_b32_e32 v19, 0xffff0000, v112
	v_lshlrev_b32_e32 v67, 16, v100
	v_lshlrev_b32_e32 v69, 16, v112
	v_cndmask_b32_e64 v69, v69, v19, s[38:39]
	v_cndmask_b32_e64 v67, v67, v17, s[38:39]
	v_cndmask_b32_e64 v121, 0, v67, s[48:49]
	v_cndmask_b32_e64 v120, 0, v69, s[48:49]
	v_lshlrev_b32_e32 v67, 16, v113
	v_lshlrev_b32_e32 v69, 16, v101
	v_cndmask_b32_e64 v123, v17, v69, s[38:39]
	v_cndmask_b32_e64 v122, v19, v67, s[38:39]
	v_pk_mul_f32 v[122:123], v[66:67], v[122:123] op_sel_hi:[0,1]
	v_pk_fma_f32 v[120:121], v[18:19], v[120:121], v[122:123] op_sel_hi:[0,1,1]
	v_and_b32_e32 v17, 0xffff0000, v101
	v_and_b32_e32 v19, 0xffff0000, v113
	v_pk_mul_f32 v[30:31], v[30:31], v[106:107]
	ds_read2_b32 v[106:107], v140 offset1:1
	ds_read2_b32 v[108:109], v141 offset1:1
	ds_read2_b32 v[118:119], v142 offset1:1
	v_cndmask_b32_e64 v19, v67, v19, s[38:39]
	v_cndmask_b32_e64 v17, v69, v17, s[38:39]
	v_cndmask_b32_e64 v101, 0, v17, s[50:51]
	v_cndmask_b32_e64 v100, 0, v19, s[50:51]
	v_pk_fma_f32 v[100:101], v[16:17], v[100:101], v[120:121] op_sel_hi:[0,1,1]
	v_pk_add_f32 v[100:101], v[68:69], v[100:101] op_sel_hi:[0,1]
	s_waitcnt lgkmcnt(2)
	v_and_b32_e32 v17, 0xffff0000, v106
	v_and_b32_e32 v19, 0xffff0000, v114
	v_lshlrev_b32_e32 v67, 16, v106
	v_lshlrev_b32_e32 v69, 16, v114
	v_cndmask_b32_e64 v69, v69, v19, s[38:39]
	v_cndmask_b32_e64 v67, v67, v17, s[38:39]
	v_pk_fma_f32 v[28:29], v[28:29], v[70:71], v[98:99] op_sel_hi:[1,0,1]
	v_cndmask_b32_e64 v99, 0, v67, s[52:53]
	v_cndmask_b32_e64 v98, 0, v69, s[52:53]
	v_lshlrev_b32_e32 v67, 16, v115
	v_lshlrev_b32_e32 v69, 16, v107
	v_pk_mul_f32 v[28:29], v[28:29], v[100:101]
	v_cndmask_b32_e64 v101, v17, v69, s[38:39]
	v_cndmask_b32_e64 v100, v19, v67, s[38:39]
	v_pk_mul_f32 v[100:101], v[66:67], v[100:101] op_sel_hi:[0,1]
	v_pk_fma_f32 v[98:99], v[18:19], v[98:99], v[100:101] op_sel_hi:[0,1,1]
	v_and_b32_e32 v17, 0xffff0000, v107
	v_and_b32_e32 v19, 0xffff0000, v115
	v_cndmask_b32_e64 v19, v67, v19, s[38:39]
	v_cndmask_b32_e64 v17, v69, v17, s[38:39]
	v_cndmask_b32_e64 v101, 0, v17, s[54:55]
	v_cndmask_b32_e64 v100, 0, v19, s[54:55]
	v_pk_fma_f32 v[98:99], v[16:17], v[100:101], v[98:99] op_sel_hi:[0,1,1]
	v_pk_add_f32 v[98:99], v[68:69], v[98:99] op_sel_hi:[0,1]
	s_waitcnt lgkmcnt(1)
	v_and_b32_e32 v17, 0xffff0000, v108
	v_and_b32_e32 v19, 0xffff0000, v116
	v_lshlrev_b32_e32 v67, 16, v108
	v_lshlrev_b32_e32 v69, 16, v116
	v_cndmask_b32_e64 v69, v69, v19, s[38:39]
	v_cndmask_b32_e64 v67, v67, v17, s[38:39]
	v_pk_fma_f32 v[26:27], v[26:27], v[70:71], v[94:95] op_sel_hi:[1,0,1]
	v_cndmask_b32_e64 v95, 0, v67, s[56:57]
	v_cndmask_b32_e64 v94, 0, v69, s[56:57]
	v_lshlrev_b32_e32 v67, 16, v117
	v_lshlrev_b32_e32 v69, 16, v109
	v_pk_mul_f32 v[26:27], v[26:27], v[98:99]
	v_cndmask_b32_e64 v99, v17, v69, s[38:39]
	v_cndmask_b32_e64 v98, v19, v67, s[38:39]
	v_pk_mul_f32 v[98:99], v[66:67], v[98:99] op_sel_hi:[0,1]
	v_pk_fma_f32 v[94:95], v[18:19], v[94:95], v[98:99] op_sel_hi:[0,1,1]
	v_and_b32_e32 v17, 0xffff0000, v109
	v_and_b32_e32 v19, 0xffff0000, v117
	v_cndmask_b32_e64 v19, v67, v19, s[38:39]
	v_cndmask_b32_e64 v17, v69, v17, s[38:39]
	v_cndmask_b32_e64 v99, 0, v17, s[58:59]
	v_cndmask_b32_e64 v98, 0, v19, s[58:59]
	v_pk_fma_f32 v[94:95], v[16:17], v[98:99], v[94:95] op_sel_hi:[0,1,1]
	v_pk_add_f32 v[94:95], v[68:69], v[94:95] op_sel_hi:[0,1]
	s_waitcnt lgkmcnt(0)
; #define LAS __attribute__((address_space(3)))
; #define U2F(x) __uint_as_float(x)
; template <int MODE> DEV void hyena_conv_rows(const LAS unsigned char* lds, int slot0, float w0, float w1, float w2, float bs, cf (&z)[2][8], const cf (&y)[2][8], float hb, int tid) {
; #pragma unroll
;     for (int b = 0; b < 4; ++b) {
;         const LAS bf16_t* row = (const LAS bf16_t*)(lds + (slot0 + b) * 8192);
; #pragma unroll
;         for (int i = 0; i < 8; ++i) {
;             const int t = tid + 512 * i, par = tid & 1, d0 = (tid >> 1) + par;
;             const LAS unsigned* rw = (const LAS unsigned*)row + d0;
;             const unsigned dw0 = (i == 0) ? rw[d0 > 0 ? -1 : 0] : rw[256 * i - 1], dw1 = rw[256 * i];
;             float um = par ? U2F(dw0 << 16) : U2F(dw0 & 0xffff0000u);
;             const float u0 = par ? U2F(dw0 & 0xffff0000u) : U2F(dw1 << 16);
;             float up = par ? U2F(dw1 << 16) : U2F(dw1 & 0xffff0000u);
;             um = (t > 0) ? um : 0.f; up = (t < 4095) ? up : 0.f;
;             const float r = um * w0 + u0 * w1 + up * w2 + bs;
;             if (MODE == 0) { if (b & 1) z[b >> 1][i].y = r; else z[b >> 1][i].x = r; }
;             else { if (b & 1) z[b >> 1][i].y = r * (y[b >> 1][i].y + hb * z[b >> 1][i].y); else z[b >> 1][i].x = r * (y[b >> 1][i].x + hb * z[b >> 1][i].x); }
;         }
;     }
; }
	v_and_b32_e32 v17, 0xffff0000, v118
	v_and_b32_e32 v19, 0xffff0000, v110
	v_lshlrev_b32_e32 v67, 16, v118
	v_lshlrev_b32_e32 v69, 16, v110
	v_cndmask_b32_e64 v69, v69, v19, s[38:39]
	v_cndmask_b32_e64 v67, v67, v17, s[38:39]
	v_pk_fma_f32 v[22:23], v[22:23], v[70:71], v[92:93] op_sel_hi:[1,0,1]
	v_cndmask_b32_e64 v93, 0, v67, s[60:61]
	v_cndmask_b32_e64 v92, 0, v69, s[60:61]
	v_lshlrev_b32_e32 v67, 16, v111
	v_lshlrev_b32_e32 v69, 16, v119
	v_pk_mul_f32 v[22:23], v[22:23], v[94:95]
	v_cndmask_b32_e64 v95, v17, v69, s[38:39]
	v_cndmask_b32_e64 v94, v19, v67, s[38:39]
	v_pk_mul_f32 v[94:95], v[66:67], v[94:95] op_sel_hi:[0,1]
	v_pk_fma_f32 v[92:93], v[18:19], v[92:93], v[94:95] op_sel_hi:[0,1,1]
	v_and_b32_e32 v17, 0xffff0000, v119
	v_and_b32_e32 v19, 0xffff0000, v111
	v_cndmask_b32_e64 v19, v67, v19, s[38:39]
	v_cndmask_b32_e64 v17, v69, v17, s[38:39]
	v_cndmask_b32_e64 v95, 0, v17, s[62:63]
	v_cndmask_b32_e64 v94, 0, v19, s[62:63]
	v_pk_fma_f32 v[92:93], v[16:17], v[94:95], v[92:93] op_sel_hi:[0,1,1]
	ds_read2_b32 v[94:95], v143 offset1:1
	v_pk_add_f32 v[92:93], v[68:69], v[92:93] op_sel_hi:[0,1]
	v_and_b32_e32 v19, 0xffff0000, v102
	v_lshlrev_b32_e32 v69, 16, v102
	v_cndmask_b32_e64 v69, v69, v19, s[38:39]
	s_waitcnt lgkmcnt(0)
	v_and_b32_e32 v17, 0xffff0000, v94
	v_lshlrev_b32_e32 v67, 16, v94
	v_cndmask_b32_e64 v67, v67, v17, s[38:39]
	v_cndmask_b32_e64 v101, 0, v67, s[64:65]
	v_cndmask_b32_e64 v100, 0, v69, s[64:65]
	v_lshlrev_b32_e32 v67, 16, v103
	v_lshlrev_b32_e32 v69, 16, v95
	v_cndmask_b32_e64 v107, v17, v69, s[38:39]
	v_cndmask_b32_e64 v106, v19, v67, s[38:39]
	v_pk_mul_f32 v[106:107], v[66:67], v[106:107] op_sel_hi:[0,1]
	v_pk_fma_f32 v[32:33], v[32:33], v[70:71], v[90:91] op_sel_hi:[1,0,1]
	v_pk_fma_f32 v[100:101], v[18:19], v[100:101], v[106:107] op_sel_hi:[0,1,1]
	v_and_b32_e32 v17, 0xffff0000, v95
	v_and_b32_e32 v19, 0xffff0000, v103
	v_pk_mul_f32 v[32:33], v[32:33], v[92:93]
	ds_read2_b32 v[98:99], v144 offset1:1
	ds_read2_b32 v[90:91], v145 offset1:1
	ds_read2_b32 v[92:93], v146 offset1:1
	v_cndmask_b32_e64 v19, v67, v19, s[38:39]
	v_cndmask_b32_e64 v17, v69, v17, s[38:39]
	v_cndmask_b32_e64 v95, 0, v17, s[66:67]
	v_cndmask_b32_e64 v94, 0, v19, s[66:67]
	v_pk_fma_f32 v[94:95], v[16:17], v[94:95], v[100:101] op_sel_hi:[0,1,1]
	v_pk_add_f32 v[94:95], v[68:69], v[94:95] op_sel_hi:[0,1]
	s_waitcnt lgkmcnt(2)
	v_and_b32_e32 v17, 0xffff0000, v98
	v_and_b32_e32 v19, 0xffff0000, v104
	v_lshlrev_b32_e32 v67, 16, v98
	v_lshlrev_b32_e32 v69, 16, v104
	v_cndmask_b32_e64 v69, v69, v19, s[38:39]
	v_cndmask_b32_e64 v67, v67, v17, s[38:39]
	v_pk_fma_f32 v[34:35], v[34:35], v[70:71], v[86:87] op_sel_hi:[1,0,1]
	v_cndmask_b32_e64 v87, 0, v67, s[68:69]
	v_cndmask_b32_e64 v86, 0, v69, s[68:69]
	v_lshlrev_b32_e32 v67, 16, v105
	v_lshlrev_b32_e32 v69, 16, v99
	v_pk_mul_f32 v[34:35], v[34:35], v[94:95]
	v_cndmask_b32_e64 v95, v17, v69, s[38:39]
	v_cndmask_b32_e64 v94, v19, v67, s[38:39]
	v_pk_mul_f32 v[94:95], v[66:67], v[94:95] op_sel_hi:[0,1]
	v_pk_fma_f32 v[86:87], v[18:19], v[86:87], v[94:95] op_sel_hi:[0,1,1]
	v_and_b32_e32 v17, 0xffff0000, v99
	v_and_b32_e32 v19, 0xffff0000, v105
	v_cndmask_b32_e64 v19, v67, v19, s[38:39]
	v_cndmask_b32_e64 v17, v69, v17, s[38:39]
	v_cndmask_b32_e64 v95, 0, v17, s[70:71]
	v_cndmask_b32_e64 v94, 0, v19, s[70:71]
	v_pk_fma_f32 v[86:87], v[16:17], v[94:95], v[86:87] op_sel_hi:[0,1,1]
	ds_read2st64_b32 v[94:95], v130 offset0:64 offset1:96
	v_pk_fma_f32 v[36:37], v[36:37], v[70:71], v[82:83] op_sel_hi:[1,0,1]
	ds_read2st64_b32 v[82:83], v129 offset0:64 offset1:96
	v_pk_add_f32 v[86:87], v[68:69], v[86:87] op_sel_hi:[0,1]
	v_pk_mul_f32 v[36:37], v[36:37], v[86:87]
	s_waitcnt lgkmcnt(1)
	v_and_b32_e32 v17, 0xffff0000, v95
	v_and_b32_e32 v19, 0xffff0000, v94
	v_lshlrev_b32_e32 v67, 16, v95
	v_lshlrev_b32_e32 v69, 16, v94
	v_cndmask_b32_e64 v69, v69, v19, s[38:39]
	v_cndmask_b32_e64 v67, v67, v17, s[38:39]
	v_cndmask_b32_e64 v87, 0, v67, s[40:41]
	v_cndmask_b32_e64 v86, 0, v69, s[40:41]
	s_waitcnt lgkmcnt(0)
	v_lshlrev_b32_e32 v67, 16, v82
	v_lshlrev_b32_e32 v69, 16, v83
	v_cndmask_b32_e64 v95, v17, v69, s[38:39]
	v_cndmask_b32_e64 v94, v19, v67, s[38:39]
	v_pk_mul_f32 v[94:95], v[66:67], v[94:95] op_sel_hi:[0,1]
	v_pk_fma_f32 v[86:87], v[18:19], v[86:87], v[94:95] op_sel_hi:[0,1,1]
	v_and_b32_e32 v17, 0xffff0000, v83
	v_and_b32_e32 v19, 0xffff0000, v82
	v_cndmask_b32_e64 v19, v67, v19, s[38:39]
	v_cndmask_b32_e64 v17, v69, v17, s[38:39]
	v_cndmask_b32_e64 v83, 0, v17, s[42:43]
	v_cndmask_b32_e64 v82, 0, v19, s[42:43]
	v_pk_fma_f32 v[82:83], v[16:17], v[82:83], v[86:87] op_sel_hi:[0,1,1]
	ds_read2_b32 v[86:87], v152 offset1:1
	v_pk_add_f32 v[82:83], v[68:69], v[82:83] op_sel_hi:[0,1]
	v_and_b32_e32 v19, 0xffff0000, v90
	v_lshlrev_b32_e32 v69, 16, v90
	v_cndmask_b32_e64 v69, v69, v19, s[38:39]
	s_waitcnt lgkmcnt(0)
	v_and_b32_e32 v17, 0xffff0000, v86
	v_lshlrev_b32_e32 v67, 16, v86
	v_cndmask_b32_e64 v67, v67, v17, s[38:39]
	v_cndmask_b32_e64 v99, 0, v67, s[44:45]
	v_cndmask_b32_e64 v98, 0, v69, s[44:45]
	v_lshlrev_b32_e32 v67, 16, v91
	v_lshlrev_b32_e32 v69, 16, v87
	v_cndmask_b32_e64 v101, v17, v69, s[38:39]
	v_cndmask_b32_e64 v100, v19, v67, s[38:39]
	v_pk_mul_f32 v[100:101], v[66:67], v[100:101] op_sel_hi:[0,1]
	v_pk_fma_f32 v[38:39], v[38:39], v[70:71], v[96:97] op_sel_hi:[1,0,1]
	v_pk_fma_f32 v[98:99], v[18:19], v[98:99], v[100:101] op_sel_hi:[0,1,1]
	v_and_b32_e32 v17, 0xffff0000, v87
	v_and_b32_e32 v19, 0xffff0000, v91
	v_pk_mul_f32 v[38:39], v[38:39], v[82:83]
	ds_read2_b32 v[82:83], v153 offset1:1
	ds_read2_b32 v[94:95], v154 offset1:1
	ds_read2_b32 v[96:97], v151 offset1:1
	v_cndmask_b32_e64 v19, v67, v19, s[38:39]
	v_cndmask_b32_e64 v17, v69, v17, s[38:39]
	v_cndmask_b32_e64 v87, 0, v17, s[46:47]
	v_cndmask_b32_e64 v86, 0, v19, s[46:47]
	v_pk_fma_f32 v[86:87], v[16:17], v[86:87], v[98:99] op_sel_hi:[0,1,1]
	v_pk_add_f32 v[86:87], v[68:69], v[86:87] op_sel_hi:[0,1]
	s_waitcnt lgkmcnt(2)
; #define LAS __attribute__((address_space(3)))
; #define U2F(x) __uint_as_float(x)
; template <int MODE> DEV void hyena_conv_rows(const LAS unsigned char* lds, int slot0, float w0, float w1, float w2, float bs, cf (&z)[2][8], const cf (&y)[2][8], float hb, int tid) {
; #pragma unroll
;     for (int b = 0; b < 4; ++b) {
;         const LAS bf16_t* row = (const LAS bf16_t*)(lds + (slot0 + b) * 8192);
; #pragma unroll
;         for (int i = 0; i < 8; ++i) {
;             const int t = tid + 512 * i, par = tid & 1, d0 = (tid >> 1) + par;
;             const LAS unsigned* rw = (const LAS unsigned*)row + d0;
;             const unsigned dw0 = (i == 0) ? rw[d0 > 0 ? -1 : 0] : rw[256 * i - 1], dw1 = rw[256 * i];
;             float um = par ? U2F(dw0 << 16) : U2F(dw0 & 0xffff0000u);
;             const float u0 = par ? U2F(dw0 & 0xffff0000u) : U2F(dw1 << 16);
;             float up = par ? U2F(dw1 << 16) : U2F(dw1 & 0xffff0000u);
;             um = (t > 0) ? um : 0.f; up = (t < 4095) ? up : 0.f;
;             const float r = um * w0 + u0 * w1 + up * w2 + bs;
;             if (MODE == 0) { if (b & 1) z[b >> 1][i].y = r; else z[b >> 1][i].x = r; }
;             else { if (b & 1) z[b >> 1][i].y = r * (y[b >> 1][i].y + hb * z[b >> 1][i].y); else z[b >> 1][i].x = r * (y[b >> 1][i].x + hb * z[b >> 1][i].x); }
;         }
;     }
; }
	v_and_b32_e32 v17, 0xffff0000, v82
	v_and_b32_e32 v19, 0xffff0000, v92
	v_lshlrev_b32_e32 v67, 16, v82
	v_lshlrev_b32_e32 v69, 16, v92
	v_pk_fma_f32 v[42:43], v[42:43], v[70:71], v[88:89] op_sel_hi:[1,0,1]
	v_cndmask_b32_e64 v69, v69, v19, s[38:39]
	v_cndmask_b32_e64 v67, v67, v17, s[38:39]
	v_pk_mul_f32 v[42:43], v[42:43], v[86:87]
	v_cndmask_b32_e64 v87, 0, v67, s[48:49]
	v_cndmask_b32_e64 v86, 0, v69, s[48:49]
	v_lshlrev_b32_e32 v67, 16, v93
	v_lshlrev_b32_e32 v69, 16, v83
	v_cndmask_b32_e64 v89, v17, v69, s[38:39]
	v_cndmask_b32_e64 v88, v19, v67, s[38:39]
	v_pk_mul_f32 v[88:89], v[66:67], v[88:89] op_sel_hi:[0,1]
	v_pk_fma_f32 v[86:87], v[18:19], v[86:87], v[88:89] op_sel_hi:[0,1,1]
	v_and_b32_e32 v17, 0xffff0000, v83
	v_and_b32_e32 v19, 0xffff0000, v93
	v_cndmask_b32_e64 v19, v67, v19, s[38:39]
	v_cndmask_b32_e64 v17, v69, v17, s[38:39]
	v_cndmask_b32_e64 v83, 0, v17, s[50:51]
	v_cndmask_b32_e64 v82, 0, v19, s[50:51]
	v_pk_fma_f32 v[82:83], v[16:17], v[82:83], v[86:87] op_sel_hi:[0,1,1]
	v_pk_add_f32 v[82:83], v[68:69], v[82:83] op_sel_hi:[0,1]
	v_pk_fma_f32 v[44:45], v[44:45], v[70:71], v[84:85] op_sel_hi:[1,0,1]
	s_waitcnt lgkmcnt(1)
	v_and_b32_e32 v17, 0xffff0000, v94
	v_pk_mul_f32 v[44:45], v[44:45], v[82:83]
	ds_read2_b32 v[82:83], v147 offset1:1
	v_lshlrev_b32_e32 v67, 16, v94
	v_cndmask_b32_e64 v67, v67, v17, s[38:39]
	v_cndmask_b32_e64 v91, 0, v67, s[52:53]
	ds_read2_b32 v[84:85], v148 offset1:1
	ds_read2_b32 v[86:87], v149 offset1:1
	ds_read2_b32 v[88:89], v150 offset1:1
	s_waitcnt lgkmcnt(3)
	v_and_b32_e32 v19, 0xffff0000, v82
	v_lshlrev_b32_e32 v69, 16, v82
	v_cndmask_b32_e64 v69, v69, v19, s[38:39]
	v_cndmask_b32_e64 v90, 0, v69, s[52:53]
	v_lshlrev_b32_e32 v67, 16, v83
	v_lshlrev_b32_e32 v69, 16, v95
	v_cndmask_b32_e64 v93, v17, v69, s[38:39]
	v_cndmask_b32_e64 v92, v19, v67, s[38:39]
	v_pk_mul_f32 v[92:93], v[66:67], v[92:93] op_sel_hi:[0,1]
	v_pk_fma_f32 v[50:51], v[50:51], v[70:71], v[80:81] op_sel_hi:[1,0,1]
	ds_read2_b32 v[80:81], v155 offset1:1
	v_pk_fma_f32 v[90:91], v[18:19], v[90:91], v[92:93] op_sel_hi:[0,1,1]
	v_and_b32_e32 v17, 0xffff0000, v95
	v_and_b32_e32 v19, 0xffff0000, v83
	v_cndmask_b32_e64 v19, v67, v19, s[38:39]
	v_cndmask_b32_e64 v17, v69, v17, s[38:39]
	v_cndmask_b32_e64 v83, 0, v17, s[54:55]
	v_cndmask_b32_e64 v82, 0, v19, s[54:55]
	v_pk_fma_f32 v[82:83], v[16:17], v[82:83], v[90:91] op_sel_hi:[0,1,1]
	v_pk_add_f32 v[82:83], v[68:69], v[82:83] op_sel_hi:[0,1]
	s_waitcnt lgkmcnt(0)
	v_and_b32_e32 v17, 0xffff0000, v80
	v_and_b32_e32 v19, 0xffff0000, v84
	v_lshlrev_b32_e32 v67, 16, v80
	v_lshlrev_b32_e32 v69, 16, v84
	v_cndmask_b32_e64 v69, v69, v19, s[38:39]
	v_cndmask_b32_e64 v67, v67, v17, s[38:39]
	v_cndmask_b32_e64 v95, 0, v67, s[56:57]
	v_cndmask_b32_e64 v94, 0, v69, s[56:57]
	v_lshlrev_b32_e32 v67, 16, v85
	v_lshlrev_b32_e32 v69, 16, v81
	v_cndmask_b32_e64 v99, v17, v69, s[38:39]
	v_cndmask_b32_e64 v98, v19, v67, s[38:39]
	v_pk_mul_f32 v[98:99], v[66:67], v[98:99] op_sel_hi:[0,1]
	v_pk_fma_f32 v[94:95], v[18:19], v[94:95], v[98:99] op_sel_hi:[0,1,1]
	v_and_b32_e32 v17, 0xffff0000, v81
	v_and_b32_e32 v19, 0xffff0000, v85
	v_pk_mul_f32 v[50:51], v[50:51], v[82:83]
	ds_read2_b32 v[82:83], v156 offset1:1
	ds_read2_b32 v[90:91], v157 offset1:1
	ds_read2_b32 v[92:93], v158 offset1:1
	v_cndmask_b32_e64 v19, v67, v19, s[38:39]
	v_cndmask_b32_e64 v17, v69, v17, s[38:39]
	v_cndmask_b32_e64 v81, 0, v17, s[58:59]
	v_cndmask_b32_e64 v80, 0, v19, s[58:59]
	v_pk_fma_f32 v[80:81], v[16:17], v[80:81], v[94:95] op_sel_hi:[0,1,1]
	v_pk_add_f32 v[80:81], v[68:69], v[80:81] op_sel_hi:[0,1]
	s_waitcnt lgkmcnt(2)
	v_and_b32_e32 v17, 0xffff0000, v82
	v_and_b32_e32 v19, 0xffff0000, v86
	v_lshlrev_b32_e32 v67, 16, v82
	v_lshlrev_b32_e32 v69, 16, v86
	v_cndmask_b32_e64 v69, v69, v19, s[38:39]
	v_cndmask_b32_e64 v67, v67, v17, s[38:39]
	v_pk_fma_f32 v[46:47], v[46:47], v[70:71], v[78:79] op_sel_hi:[1,0,1]
	v_cndmask_b32_e64 v79, 0, v67, s[60:61]
	v_cndmask_b32_e64 v78, 0, v69, s[60:61]
	v_lshlrev_b32_e32 v67, 16, v87
	v_lshlrev_b32_e32 v69, 16, v83
	v_pk_mul_f32 v[46:47], v[46:47], v[80:81]
	v_cndmask_b32_e64 v81, v17, v69, s[38:39]
	v_cndmask_b32_e64 v80, v19, v67, s[38:39]
	v_pk_mul_f32 v[80:81], v[66:67], v[80:81] op_sel_hi:[0,1]
	v_pk_fma_f32 v[78:79], v[18:19], v[78:79], v[80:81] op_sel_hi:[0,1,1]
	v_and_b32_e32 v17, 0xffff0000, v83
	v_and_b32_e32 v19, 0xffff0000, v87
	v_cndmask_b32_e64 v19, v67, v19, s[38:39]
	v_cndmask_b32_e64 v17, v69, v17, s[38:39]
	v_cndmask_b32_e64 v81, 0, v17, s[62:63]
	v_cndmask_b32_e64 v80, 0, v19, s[62:63]
	v_pk_fma_f32 v[78:79], v[16:17], v[80:81], v[78:79] op_sel_hi:[0,1,1]
	v_pk_add_f32 v[78:79], v[68:69], v[78:79] op_sel_hi:[0,1]
	s_waitcnt lgkmcnt(1)
	v_and_b32_e32 v17, 0xffff0000, v90
	v_and_b32_e32 v19, 0xffff0000, v88
	v_lshlrev_b32_e32 v67, 16, v90
	v_lshlrev_b32_e32 v69, 16, v88
	v_cndmask_b32_e64 v69, v69, v19, s[38:39]
	v_cndmask_b32_e64 v67, v67, v17, s[38:39]
	v_pk_fma_f32 v[48:49], v[48:49], v[70:71], v[76:77] op_sel_hi:[1,0,1]
	v_cndmask_b32_e64 v77, 0, v67, s[64:65]
	v_cndmask_b32_e64 v76, 0, v69, s[64:65]
	v_lshlrev_b32_e32 v67, 16, v89
	v_lshlrev_b32_e32 v69, 16, v91
	v_pk_mul_f32 v[48:49], v[48:49], v[78:79]
	v_cndmask_b32_e64 v79, v17, v69, s[38:39]
	v_cndmask_b32_e64 v78, v19, v67, s[38:39]
	v_pk_mul_f32 v[78:79], v[66:67], v[78:79] op_sel_hi:[0,1]
	v_pk_fma_f32 v[76:77], v[18:19], v[76:77], v[78:79] op_sel_hi:[0,1,1]
	v_and_b32_e32 v17, 0xffff0000, v91
	v_and_b32_e32 v19, 0xffff0000, v89
	v_cndmask_b32_e64 v19, v67, v19, s[38:39]
	v_cndmask_b32_e64 v17, v69, v17, s[38:39]
	v_cndmask_b32_e64 v79, 0, v17, s[66:67]
	v_cndmask_b32_e64 v78, 0, v19, s[66:67]
	v_pk_fma_f32 v[76:77], v[16:17], v[78:79], v[76:77] op_sel_hi:[0,1,1]
	v_pk_add_f32 v[76:77], v[68:69], v[76:77] op_sel_hi:[0,1]
	v_and_b32_e32 v19, 0xffff0000, v96
	v_lshlrev_b32_e32 v69, 16, v96
	v_cndmask_b32_e64 v69, v69, v19, s[38:39]
	v_pk_fma_f32 v[52:53], v[52:53], v[70:71], v[74:75] op_sel_hi:[1,0,1]
	s_waitcnt lgkmcnt(0)
; #define LAS __attribute__((address_space(3)))
; #define OPAQUE_I(x) asm volatile("" : "+v"(x))
; template <int R, bool INV> DEV void dft_regs(cf (&v)[R]) {
; #pragma unroll
;     for (int s = R; s >= 2; s >>= 1) {
;         const int h = s >> 1;
; #pragma unroll
;         for (int b = 0; b < R; b += s) {
; #pragma unroll
;             for (int k = 0; k < h; ++k) {
;                 const cf a = v[b + k], c = v[b + k + h];
;                 v[b + k] = a + c;
;                 const cf d = a - c;
;                 const int m = k * (32 / s);
;                 const float wr = tw_cos(m), wi = INV ? tw_sin(m) : -tw_sin(m);
;                 v[b + k + h] = cf{d.x * wr - d.y * wi, d.x * wi + d.y * wr};
;             }
;         }
;     }
; }
; DEV void fft_f1x2(LAS cf* buf0, LAS cf* buf1, const cf (&z0)[8], const cf (&z1)[8], int tid) {
;     OPAQUE_I(tid);
;     cf v[16], u[16];
; #pragma unroll
;     for (int q = 0; q < 8; ++q) { v[q] = z0[q]; v[q + 8] = cf{0.f, 0.f}; u[q] = z1[q]; u[q + 8] = cf{0.f, 0.f}; }
;     dft_regs<16, false>(v); dft_regs<16, false>(u);
	v_and_b32_e32 v17, 0xffff0000, v92
	v_lshlrev_b32_e32 v67, 16, v92
	v_cndmask_b32_e64 v74, 0, v69, s[68:69]
	v_lshlrev_b32_e32 v69, 16, v97
	v_lshlrev_b32_e32 v71, 16, v93
	v_pk_mul_f32 v[52:53], v[52:53], v[76:77]
	v_cndmask_b32_e64 v67, v67, v17, s[38:39]
	v_cndmask_b32_e64 v77, v17, v71, s[38:39]
	v_cndmask_b32_e64 v76, v19, v69, s[38:39]
	v_cndmask_b32_e64 v75, 0, v67, s[68:69]
	v_pk_mul_f32 v[66:67], v[66:67], v[76:77] op_sel_hi:[0,1]
	v_pk_fma_f32 v[18:19], v[18:19], v[74:75], v[66:67] op_sel_hi:[0,1,1]
	v_and_b32_e32 v17, 0xffff0000, v93
	v_and_b32_e32 v66, 0xffff0000, v97
	v_cndmask_b32_e64 v66, v69, v66, s[38:39]
	v_cndmask_b32_e64 v17, v71, v17, s[38:39]
	v_cndmask_b32_e64 v67, 0, v17, s[70:71]
	v_cndmask_b32_e64 v66, 0, v66, s[70:71]
	v_pk_add_f32 v[72:73], v[126:127], v[166:167]
	v_pk_fma_f32 v[16:17], v[16:17], v[66:67], v[18:19] op_sel_hi:[0,1,1]
	v_pk_add_f32 v[16:17], v[68:69], v[16:17] op_sel_hi:[0,1]
	v_pk_fma_f32 v[18:19], v[40:41], v[70:71], v[72:73] op_sel_hi:[1,0,1]
	s_mov_b64 s[22:23], 0
	v_pk_mul_f32 v[40:41], v[18:19], v[16:17]
	s_and_b64 vcc, exec, s[2:3]
	s_barrier
	s_cbranch_vccnz .LBB0_522
.LBB0_519:
	v_pk_mul_f32 v[16:17], v[26:27], s[16:17] op_sel_hi:[1,0]
	v_pk_add_f32 v[0:1], v[24:25], 0 op_sel_hi:[1,0]
	v_pk_fma_f32 v[18:19], v[26:27], s[84:85], v[16:17] op_sel:[0,0,1] op_sel_hi:[1,0,0] neg_hi:[0,0,1]
	v_pk_add_f32 v[16:17], v[22:23], 0 op_sel_hi:[1,0]
	v_mov_b32_e32 v4, v24
	v_mov_b32_e32 v5, v25
	v_pk_add_f32 v[80:81], v[0:1], v[16:17]
	v_pk_add_f32 v[0:1], v[0:1], v[16:17] neg_lo:[0,1] neg_hi:[0,1]
	v_mov_b32_e32 v2, v24
	v_mov_b32_e32 v3, v25
	v_pk_fma_f32 v[66:67], v[22:23], 0, v[22:23] op_sel:[0,0,1] op_sel_hi:[1,0,0] neg_hi:[0,0,1]
	v_mov_b32_e32 v5, v3
	v_pk_add_f32 v[2:3], v[30:31], 0 op_sel_hi:[1,0]
	v_pk_mul_f32 v[6:7], v[30:31], s[84:85] op_sel_hi:[1,0]
	v_pk_add_f32 v[68:69], v[32:33], 0 op_sel_hi:[1,0]
	v_mov_b32_e32 v82, v0
	v_mov_b32_e32 v83, v1
	v_pk_fma_f32 v[8:9], v[30:31], s[16:17], v[6:7] op_sel:[0,0,1] op_sel_hi:[1,0,0] neg_hi:[0,0,1]
	v_pk_add_f32 v[0:1], v[2:3], v[68:69]
	v_pk_add_f32 v[2:3], v[2:3], v[68:69] neg_lo:[0,1] neg_hi:[0,1]
	v_pk_add_f32 v[6:7], v[28:29], 0 op_sel_hi:[1,0]
	v_pk_add_f32 v[72:73], v[34:35], 0 op_sel_hi:[1,0]
	v_pk_mul_f32 v[16:17], v[2:3], s[18:19] op_sel_hi:[1,0]
	v_pk_mul_f32 v[10:11], v[28:29], s[18:19] op_sel_hi:[1,0]
	v_pk_fma_f32 v[68:69], v[2:3], s[18:19], v[16:17] op_sel:[0,0,1] op_sel_hi:[1,0,0]
	v_pk_fma_f32 v[2:3], v[2:3], s[18:19], v[16:17] op_sel_hi:[1,0,0] neg_lo:[0,0,1] neg_hi:[0,0,1]
	v_pk_add_f32 v[16:17], v[6:7], v[72:73]
	v_pk_add_f32 v[6:7], v[6:7], v[72:73] neg_lo:[0,1] neg_hi:[0,1]
	v_pk_add_f32 v[14:15], v[26:27], 0 op_sel_hi:[1,0]
	v_pk_add_f32 v[76:77], v[36:37], 0 op_sel_hi:[1,0]
	v_pk_add_f32 v[72:73], v[6:7], 0 op_sel:[1,0] op_sel_hi:[0,0] neg_hi:[1,0]
	v_pk_fma_f32 v[12:13], v[28:29], s[18:19], v[10:11] op_sel:[0,0,1] op_sel_hi:[1,0,0]
	v_pk_fma_f32 v[10:11], v[28:29], s[18:19], v[10:11] op_sel_hi:[1,0,0] neg_lo:[0,0,1] neg_hi:[0,0,1]
	v_pk_add_f32 v[6:7], v[14:15], v[76:77]
	v_pk_add_f32 v[14:15], v[14:15], v[76:77] neg_lo:[0,1] neg_hi:[0,1]
	v_pk_add_f32 v[76:77], v[4:5], v[66:67]
	v_pk_add_f32 v[4:5], v[4:5], v[66:67] neg_lo:[0,1] neg_hi:[0,1]
	v_mov_b32_e32 v10, v33
	s_mov_b32 s30, s85
	s_mov_b32 s31, s0
	v_pk_mul_f32 v[70:71], v[32:33], s[84:85] op_sel_hi:[0,1]
	v_pk_fma_f32 v[70:71], v[10:11], s[30:31], v[70:71] op_sel_hi:[0,1,1] neg_lo:[0,0,1] neg_hi:[0,0,1]
	v_mov_b32_e32 v84, v4
	v_mov_b32_e32 v85, v5
	v_mul_f32_e32 v10, 0x3f3504f3, v34
	v_mov_b32_e32 v74, v35
	s_mov_b32 s28, s97
	s_mov_b32 s29, s96
	s_mov_b32 s24, s85
	s_mov_b32 s25, s84
	v_pk_add_f32 v[4:5], v[8:9], v[70:71]
	v_pk_add_f32 v[8:9], v[8:9], v[70:71] neg_lo:[0,1] neg_hi:[0,1]
	v_pk_fma_f32 v[74:75], v[74:75], s[28:29], v[10:11] op_sel_hi:[0,1,0] neg_lo:[0,0,1] neg_hi:[0,0,1]
	v_mov_b32_e32 v10, v37
	s_mov_b32 s34, s84
	s_mov_b32 s35, s88
	v_pk_mul_f32 v[78:79], v[36:37], s[24:25] op_sel_hi:[0,1]
	v_pk_mul_f32 v[66:67], v[8:9], s[18:19] op_sel_hi:[1,0]
	v_mov_b32_e32 v13, v11
	v_pk_fma_f32 v[78:79], v[10:11], s[34:35], v[78:79] op_sel_hi:[0,1,1] neg_lo:[0,0,1] neg_hi:[0,0,1]
	v_pk_fma_f32 v[70:71], v[8:9], s[18:19], v[66:67] op_sel:[0,0,1] op_sel_hi:[1,0,0] neg_hi:[0,0,1]
	v_pk_add_f32 v[10:11], v[12:13], v[74:75] neg_lo:[0,1] neg_hi:[0,1]
	v_pk_add_f32 v[66:67], v[80:81], v[16:17]
	v_pk_add_f32 v[16:17], v[80:81], v[16:17] neg_lo:[0,1] neg_hi:[0,1]
	v_pk_add_f32 v[8:9], v[12:13], v[74:75]
	v_pk_add_f32 v[12:13], v[10:11], 0 op_sel:[1,0] op_sel_hi:[0,0] neg_hi:[1,0]
	v_pk_add_f32 v[10:11], v[18:19], v[78:79]
	v_pk_add_f32 v[18:19], v[18:19], v[78:79] neg_lo:[0,1] neg_hi:[0,1]
	v_mov_b32_e32 v78, v16
	v_mov_b32_e32 v79, v17
	v_mul_f32_e32 v2, 0x3f3504f3, v14
	v_pk_add_f32 v[16:17], v[0:1], v[6:7]
	v_pk_add_f32 v[0:1], v[0:1], v[6:7] neg_lo:[0,1] neg_hi:[0,1]
	v_pk_add_f32 v[74:75], v[82:83], v[72:73]
	v_pk_add_f32 v[6:7], v[0:1], 0 op_sel:[1,0] op_sel_hi:[0,0] neg_hi:[1,0]
	v_pk_fma_f32 v[14:15], v[14:15], s[28:29], v[2:3] op_sel:[1,0,0] op_sel_hi:[1,1,0] neg_lo:[0,0,1] neg_hi:[0,0,1]
	v_pk_add_f32 v[0:1], v[82:83], v[72:73] neg_lo:[0,1] neg_hi:[0,1]
	v_mov_b32_e32 v69, v3
	v_mul_f32_e32 v2, 0x3f3504f3, v18
	v_mov_b32_e32 v80, v0
	v_mov_b32_e32 v81, v1
	v_pk_fma_f32 v[18:19], v[18:19], s[28:29], v[2:3] op_sel:[1,0,0] op_sel_hi:[1,1,0] neg_lo:[0,0,1] neg_hi:[0,0,1]
	v_pk_add_f32 v[0:1], v[68:69], v[14:15] neg_lo:[0,1] neg_hi:[0,1]
	v_pk_add_f32 v[2:3], v[68:69], v[14:15]
	v_pk_add_f32 v[14:15], v[0:1], 0 op_sel:[1,0] op_sel_hi:[0,0] neg_hi:[1,0]
	v_pk_add_f32 v[72:73], v[76:77], v[8:9]
	v_pk_add_f32 v[0:1], v[76:77], v[8:9] neg_lo:[0,1] neg_hi:[0,1]
; #define LAS __attribute__((address_space(3)))
; #define OPAQUE_I(x) asm volatile("" : "+v"(x))
; template <int R, bool INV> DEV void dft_regs(cf (&v)[R]) {
; #pragma unroll
;     for (int s = R; s >= 2; s >>= 1) {
;         const int h = s >> 1;
; #pragma unroll
;         for (int b = 0; b < R; b += s) {
; #pragma unroll
;             for (int k = 0; k < h; ++k) {
;                 const cf a = v[b + k], c = v[b + k + h];
;                 v[b + k] = a + c;
;                 const cf d = a - c;
;                 const int m = k * (32 / s);
;                 const float wr = tw_cos(m), wi = INV ? tw_sin(m) : -tw_sin(m);
;                 v[b + k + h] = cf{d.x * wr - d.y * wi, d.x * wi + d.y * wr};
;             }
;         }
;     }
; }
; DEV void fft_f1x2(LAS cf* buf0, LAS cf* buf1, const cf (&z0)[8], const cf (&z1)[8], int tid) {
;     OPAQUE_I(tid);
;     cf v[16], u[16];
; #pragma unroll
;     for (int q = 0; q < 8; ++q) { v[q] = z0[q]; v[q + 8] = cf{0.f, 0.f}; u[q] = z1[q]; u[q + 8] = cf{0.f, 0.f}; }
;     dft_regs<16, false>(v); dft_regs<16, false>(u);
	v_pk_add_f32 v[86:87], v[84:85], v[12:13]
	v_pk_add_f32 v[68:69], v[66:67], v[16:17]
	v_mov_b32_e32 v82, v0
	v_mov_b32_e32 v83, v1
	v_pk_add_f32 v[8:9], v[4:5], v[10:11]
	v_pk_add_f32 v[0:1], v[4:5], v[10:11] neg_lo:[0,1] neg_hi:[0,1]
	v_pk_add_f32 v[88:89], v[70:71], v[18:19]
	v_pk_add_f32 v[10:11], v[0:1], 0 op_sel:[1,0] op_sel_hi:[0,0] neg_hi:[1,0]
	v_pk_add_f32 v[76:77], v[72:73], v[8:9]
	v_pk_add_f32 v[0:1], v[84:85], v[12:13] neg_lo:[0,1] neg_hi:[0,1]
	v_pk_add_f32 v[8:9], v[72:73], v[8:9] neg_lo:[0,1] neg_hi:[0,1]
	v_pk_add_f32 v[72:73], v[82:83], v[10:11]
	v_mov_b32_e32 v84, v0
	v_mov_b32_e32 v85, v1
	v_pk_add_f32 v[10:11], v[82:83], v[10:11] neg_lo:[0,1] neg_hi:[0,1]
	v_pk_add_f32 v[0:1], v[70:71], v[18:19] neg_lo:[0,1] neg_hi:[0,1]
	v_pk_add_f32 v[70:71], v[74:75], v[2:3]
	v_pk_add_f32 v[90:91], v[0:1], 0 op_sel:[1,0] op_sel_hi:[0,0] neg_hi:[1,0]
	v_pk_add_f32 v[2:3], v[74:75], v[2:3] neg_lo:[0,1] neg_hi:[0,1]
	v_pk_add_f32 v[0:1], v[66:67], v[16:17] neg_lo:[0,1] neg_hi:[0,1]
	v_pk_add_f32 v[16:17], v[78:79], v[6:7]
	v_pk_add_f32 v[6:7], v[78:79], v[6:7] neg_lo:[0,1] neg_hi:[0,1]
	v_mov_b32_e32 v4, v0
	v_mov_b32_e32 v5, v1
	v_mov_b32_e32 v0, v6
	v_mov_b32_e32 v1, v7
	v_mov_b32_e32 v6, v2
	v_mov_b32_e32 v7, v3
	v_pk_add_f32 v[12:13], v[80:81], v[14:15] neg_lo:[0,1] neg_hi:[0,1]
	v_pk_add_f32 v[18:19], v[80:81], v[14:15]
	v_mov_b32_e32 v2, v12
	v_mov_b32_e32 v3, v13
	v_mov_b32_e32 v12, v8
	v_mov_b32_e32 v13, v9
	v_mov_b32_e32 v8, v10
	v_mov_b32_e32 v9, v11
	v_pk_mul_f32 v[92:93], v[50:51], s[16:17] op_sel_hi:[1,0]
	v_pk_add_f32 v[10:11], v[86:87], v[88:89] neg_lo:[0,1] neg_hi:[0,1]
	v_pk_fma_f32 v[94:95], v[50:51], s[84:85], v[92:93] op_sel:[0,0,1] op_sel_hi:[1,0,0] neg_hi:[0,0,1]
	v_mov_b32_e32 v14, v10
	v_mov_b32_e32 v15, v11
	v_pk_add_f32 v[66:67], v[84:85], v[90:91] neg_lo:[0,1] neg_hi:[0,1]
	v_mov_b32_e32 v10, v66
	v_mov_b32_e32 v11, v67
	v_pk_add_f32 v[92:93], v[46:47], 0 op_sel_hi:[1,0]
	v_pk_add_f32 v[66:67], v[38:39], 0 op_sel_hi:[1,0]
	v_mov_b32_e32 v108, v41
	v_pk_mul_f32 v[110:111], v[40:41], s[24:25] op_sel_hi:[0,1]
	v_pk_fma_f32 v[108:109], v[108:109], s[34:35], v[110:111] op_sel_hi:[0,1,1] neg_lo:[0,0,1] neg_hi:[0,0,1]
	v_pk_add_f32 v[110:111], v[66:67], v[92:93]
	v_pk_add_f32 v[66:67], v[66:67], v[92:93] neg_lo:[0,1] neg_hi:[0,1]
	v_mov_b32_e32 v82, v38
	v_mov_b32_e32 v83, v39
	v_mov_b32_e32 v80, v38
	v_mov_b32_e32 v81, v39
	v_pk_fma_f32 v[96:97], v[46:47], 0, v[46:47] op_sel:[0,0,1] op_sel_hi:[1,0,0] neg_hi:[0,0,1]
	v_mov_b32_e32 v83, v81
	v_pk_add_f32 v[80:81], v[42:43], 0 op_sel_hi:[1,0]
	v_pk_add_f32 v[98:99], v[48:49], 0 op_sel_hi:[1,0]
	v_mov_b32_e32 v112, v66
	v_mov_b32_e32 v113, v67
	v_pk_add_f32 v[74:75], v[84:85], v[90:91]
	v_pk_mul_f32 v[84:85], v[42:43], s[84:85] op_sel_hi:[1,0]
	v_pk_add_f32 v[66:67], v[80:81], v[98:99]
	v_pk_add_f32 v[80:81], v[80:81], v[98:99] neg_lo:[0,1] neg_hi:[0,1]
	v_pk_add_f32 v[78:79], v[86:87], v[88:89]
	v_pk_fma_f32 v[86:87], v[42:43], s[16:17], v[84:85] op_sel:[0,0,1] op_sel_hi:[1,0,0] neg_hi:[0,0,1]
	v_mov_b32_e32 v100, v49
	v_pk_mul_f32 v[102:103], v[48:49], s[84:85] op_sel_hi:[0,1]
	v_pk_mul_f32 v[92:93], v[80:81], s[18:19] op_sel_hi:[1,0]
	v_pk_add_f32 v[84:85], v[44:45], 0 op_sel_hi:[1,0]
	v_pk_mul_f32 v[88:89], v[44:45], s[18:19] op_sel_hi:[1,0]
	v_pk_fma_f32 v[100:101], v[100:101], s[30:31], v[102:103] op_sel_hi:[0,1,1] neg_lo:[0,0,1] neg_hi:[0,0,1]
	v_pk_add_f32 v[102:103], v[52:53], 0 op_sel_hi:[1,0]
	v_pk_fma_f32 v[98:99], v[80:81], s[18:19], v[92:93] op_sel:[0,0,1] op_sel_hi:[1,0,0] neg_hi:[0,0,1]
	v_pk_fma_f32 v[90:91], v[44:45], s[18:19], v[88:89] op_sel:[0,0,1] op_sel_hi:[1,0,0] neg_hi:[0,0,1]
	v_mul_f32_e32 v104, 0x3f3504f3, v52
	v_mov_b32_e32 v106, v53
	v_pk_add_f32 v[80:81], v[84:85], v[102:103]
	v_pk_add_f32 v[84:85], v[84:85], v[102:103] neg_lo:[0,1] neg_hi:[0,1]
	v_pk_add_f32 v[88:89], v[50:51], 0 op_sel_hi:[1,0]
	v_pk_fma_f32 v[104:105], v[106:107], s[28:29], v[104:105] op_sel_hi:[0,1,0] neg_lo:[0,0,1] neg_hi:[0,0,1]
	v_pk_add_f32 v[106:107], v[40:41], 0 op_sel_hi:[1,0]
	v_pk_add_f32 v[92:93], v[84:85], 0 op_sel:[1,0] op_sel_hi:[0,0] neg_hi:[1,0]
	v_mov_b32_e32 v114, v21
	v_pk_add_f32 v[84:85], v[88:89], v[106:107]
	v_pk_add_f32 v[88:89], v[88:89], v[106:107] neg_lo:[0,1] neg_hi:[0,1]
	s_mov_b32 s2, s86
	v_mul_f32_e32 v102, 0x3f3504f3, v88
	v_pk_fma_f32 v[88:89], v[88:89], s[28:29], v[102:103] op_sel:[1,0,0] op_sel_hi:[1,1,0] neg_lo:[0,0,1] neg_hi:[0,0,1]
	v_pk_add_f32 v[102:103], v[82:83], v[96:97]
	v_pk_add_f32 v[82:83], v[82:83], v[96:97] neg_lo:[0,1] neg_hi:[0,1]
	s_mov_b32 s3, s4
	s_mov_b32 s10, s4
	v_mov_b32_e32 v106, v82
	v_mov_b32_e32 v107, v83
	s_mov_b32 s6, s94
	v_pk_add_f32 v[82:83], v[86:87], v[100:101]
	v_pk_add_f32 v[86:87], v[86:87], v[100:101] neg_lo:[0,1] neg_hi:[0,1]
	s_mov_b32 s7, s82
	v_pk_mul_f32 v[96:97], v[86:87], s[18:19] op_sel_hi:[1,0]
	s_mov_b32 s8, s82
	v_pk_fma_f32 v[100:101], v[86:87], s[18:19], v[96:97] op_sel:[0,0,1] op_sel_hi:[1,0,0] neg_hi:[0,0,1]
	s_lshl_b32 s92, s19, 13
	v_lshl_add_u64 v[232:233], s[92:93], 2, v[54:55]
	global_load_dwordx4 v[170:173], v[232:233], off offset:48
	global_load_dwordx4 v[174:177], v[232:233], off offset:32
	global_load_dwordx4 v[178:181], v[232:233], off offset:16
	global_load_dwordx4 v[182:185], v[232:233], off
	v_pk_add_f32 v[86:87], v[90:91], v[104:105]
	v_pk_add_f32 v[90:91], v[90:91], v[104:105] neg_lo:[0,1] neg_hi:[0,1]
	s_mov_b32 s1, s85
	v_pk_add_f32 v[96:97], v[90:91], 0 op_sel:[1,0] op_sel_hi:[0,0] neg_hi:[1,0]
	s_mov_b32 s89, s84
	v_pk_add_f32 v[90:91], v[94:95], v[108:109]
	v_pk_add_f32 v[94:95], v[94:95], v[108:109] neg_lo:[0,1] neg_hi:[0,1]
	v_mul_f32_e32 v104, 0x3f3504f3, v94
; #define LAS __attribute__((address_space(3)))
; #define SINCOSPI(x, s, c) do { const float hx_ = 0.5f * (x); *(s) = __builtin_amdgcn_sinf(hx_); *(c) = __builtin_amdgcn_cosf(hx_); } while (0)
; #define OPAQUE_I(x) asm volatile("" : "+v"(x))
; DEV void fft_f1x2(LAS cf* buf0, LAS cf* buf1, const cf (&z0)[8], const cf (&z1)[8], int tid) {
;     OPAQUE_I(tid);
;     cf v[16], u[16];
; #pragma unroll
;     for (int q = 0; q < 8; ++q) { v[q] = z0[q]; v[q + 8] = cf{0.f, 0.f}; u[q] = z1[q]; u[q + 8] = cf{0.f, 0.f}; }
;     dft_regs<16, false>(v); dft_regs<16, false>(u);
;     float sn, cs; SINCOSPI(-(float)tid * (2.0f / 8192.0f), &sn, &cs);
;     const cf w = cf{cs, sn}; cf wp = cf{1.f, 0.f};
;     LAS cf* p0 = buf0 + PADI(tid); LAS cf* p1 = buf1 + PADI(tid);
; #pragma unroll
;     for (int p = 0; p < 16; ++p) { p0[544 * p] = cmul(v[BR16[p]], wp); p1[544 * p] = cmul(u[BR16[p]], wp); wp = cmul(wp, w); }
; }
	v_pk_fma_f32 v[94:95], v[94:95], s[28:29], v[104:105] op_sel:[1,0,0] op_sel_hi:[1,1,0] neg_lo:[0,0,1] neg_hi:[0,0,1]
	v_pk_add_f32 v[104:105], v[110:111], v[80:81]
	v_pk_add_f32 v[80:81], v[110:111], v[80:81] neg_lo:[0,1] neg_hi:[0,1]
	v_mov_b32_e32 v110, v80
	v_mov_b32_e32 v111, v81
	v_pk_add_f32 v[80:81], v[66:67], v[84:85]
	v_pk_add_f32 v[66:67], v[66:67], v[84:85] neg_lo:[0,1] neg_hi:[0,1]
	v_pk_add_f32 v[84:85], v[66:67], 0 op_sel:[1,0] op_sel_hi:[0,0] neg_hi:[1,0]
	v_pk_add_f32 v[66:67], v[112:113], v[92:93]
	v_pk_add_f32 v[92:93], v[112:113], v[92:93] neg_lo:[0,1] neg_hi:[0,1]
	v_mov_b32_e32 v112, v92
	v_mov_b32_e32 v113, v93
	v_pk_add_f32 v[92:93], v[98:99], v[88:89]
	v_pk_add_f32 v[88:89], v[98:99], v[88:89] neg_lo:[0,1] neg_hi:[0,1]
	v_pk_add_f32 v[98:99], v[88:89], 0 op_sel:[1,0] op_sel_hi:[0,0] neg_hi:[1,0]
	v_pk_add_f32 v[88:89], v[102:103], v[86:87]
	v_pk_add_f32 v[86:87], v[102:103], v[86:87] neg_lo:[0,1] neg_hi:[0,1]
	v_mov_b32_e32 v108, v86
	v_mov_b32_e32 v109, v87
	v_pk_add_f32 v[86:87], v[82:83], v[90:91]
	v_pk_add_f32 v[82:83], v[82:83], v[90:91] neg_lo:[0,1] neg_hi:[0,1]
	v_pk_add_f32 v[90:91], v[82:83], 0 op_sel:[1,0] op_sel_hi:[0,0] neg_hi:[1,0]
	v_pk_add_f32 v[82:83], v[106:107], v[96:97]
	v_pk_add_f32 v[96:97], v[106:107], v[96:97] neg_lo:[0,1] neg_hi:[0,1]
	v_mov_b32_e32 v106, v96
	v_mov_b32_e32 v107, v97
	v_pk_add_f32 v[96:97], v[100:101], v[94:95]
	v_pk_add_f32 v[94:95], v[100:101], v[94:95] neg_lo:[0,1] neg_hi:[0,1]
	v_pk_add_f32 v[100:101], v[94:95], 0 op_sel:[1,0] op_sel_hi:[0,0] neg_hi:[1,0]
	v_pk_add_f32 v[94:95], v[104:105], v[80:81]
	v_pk_add_f32 v[80:81], v[104:105], v[80:81] neg_lo:[0,1] neg_hi:[0,1]
	v_mov_b32_e32 v104, v80
	v_mov_b32_e32 v105, v81
	v_pk_add_f32 v[80:81], v[110:111], v[84:85]
	v_pk_add_f32 v[84:85], v[110:111], v[84:85] neg_lo:[0,1] neg_hi:[0,1]
	v_mov_b32_e32 v110, v84
	v_mov_b32_e32 v111, v85
	v_pk_add_f32 v[84:85], v[66:67], v[92:93]
	v_pk_add_f32 v[66:67], v[66:67], v[92:93] neg_lo:[0,1] neg_hi:[0,1]
	v_mov_b32_e32 v102, v66
	v_mov_b32_e32 v103, v67
	v_pk_add_f32 v[92:93], v[112:113], v[98:99]
	v_pk_add_f32 v[66:67], v[112:113], v[98:99] neg_lo:[0,1] neg_hi:[0,1]
	v_mov_b32_e32 v112, v66
	v_mov_b32_e32 v113, v67
	v_pk_add_f32 v[98:99], v[88:89], v[86:87]
	v_pk_add_f32 v[66:67], v[88:89], v[86:87] neg_lo:[0,1] neg_hi:[0,1]
	v_mov_b32_e32 v88, v66
	v_mov_b32_e32 v89, v67
	v_pk_add_f32 v[86:87], v[108:109], v[90:91]
	v_pk_add_f32 v[66:67], v[108:109], v[90:91] neg_lo:[0,1] neg_hi:[0,1]
	v_mov_b32_e32 v108, v66
	v_mov_b32_e32 v109, v67
	v_pk_add_f32 v[90:91], v[82:83], v[96:97]
	v_pk_add_f32 v[66:67], v[82:83], v[96:97] neg_lo:[0,1] neg_hi:[0,1]
	v_mov_b32_e32 v96, v66
	v_mov_b32_e32 v97, v67
	v_pk_add_f32 v[82:83], v[106:107], v[100:101]
	v_pk_add_f32 v[66:67], v[106:107], v[100:101] neg_lo:[0,1] neg_hi:[0,1]
	v_mov_b32_e32 v106, v66
	v_mov_b32_e32 v107, v67
	s_nop 0
	v_cvt_f32_i32_e32 v66, v114
	v_mul_f32_e32 v66, 0xb9800000, v66
	v_mul_f32_e32 v66, 0.5, v66
	v_sin_f32_e32 v101, v66
	v_cos_f32_e32 v100, v66
	v_ashrrev_i32_e32 v66, 4, v114
	v_add_lshl_u32 v66, v66, v114, 3
	v_add_u32_e32 v116, 0, v66
	v_add_u32_e32 v117, s33, v66
	v_mov_b64_e32 v[66:67], s[90:91]
	v_pk_mul_f32 v[114:115], v[68:69], v[66:67] op_sel:[1,1] op_sel_hi:[1,0] neg_lo:[1,0]
	v_pk_fma_f32 v[68:69], v[68:69], v[66:67], v[114:115] op_sel_hi:[0,1,1]
	ds_write_b64 v116, v[68:69]
	v_pk_mul_f32 v[114:115], v[94:95], v[66:67] op_sel:[1,1] op_sel_hi:[1,0] neg_lo:[1,0]
	v_pk_fma_f32 v[68:69], v[94:95], v[66:67], v[114:115] op_sel_hi:[0,1,1]
	ds_write_b64 v117, v[68:69]
	v_pk_mul_f32 v[68:69], v[66:67], v[100:101] op_sel:[1,1] op_sel_hi:[1,0] neg_lo:[1,0]
	v_pk_fma_f32 v[94:95], v[66:67], v[100:101], v[68:69] op_sel_hi:[0,1,1]
	v_pk_mul_f32 v[114:115], v[76:77], v[94:95] op_sel:[1,1] op_sel_hi:[1,0] neg_lo:[1,0]
	v_pk_fma_f32 v[68:69], v[76:77], v[94:95], v[114:115] op_sel_hi:[0,1,1]
	ds_write_b64 v116, v[68:69] offset:4352
	v_pk_mul_f32 v[76:77], v[98:99], v[94:95] op_sel:[1,1] op_sel_hi:[1,0] neg_lo:[1,0]
	v_pk_fma_f32 v[68:69], v[98:99], v[94:95], v[76:77] op_sel_hi:[0,1,1]
	ds_write_b64 v117, v[68:69] offset:4352
	v_pk_mul_f32 v[68:69], v[94:95], v[100:101] op_sel:[1,1] op_sel_hi:[1,0] neg_lo:[1,0]
	v_pk_fma_f32 v[76:77], v[94:95], v[100:101], v[68:69] op_sel_hi:[0,1,1]
	v_pk_mul_f32 v[94:95], v[70:71], v[76:77] op_sel:[1,1] op_sel_hi:[1,0] neg_lo:[1,0]
	v_pk_fma_f32 v[68:69], v[70:71], v[76:77], v[94:95] op_sel_hi:[0,1,1]
	ds_write_b64 v116, v[68:69] offset:8704
	v_pk_mul_f32 v[70:71], v[84:85], v[76:77] op_sel:[1,1] op_sel_hi:[1,0] neg_lo:[1,0]
	v_pk_fma_f32 v[68:69], v[84:85], v[76:77], v[70:71] op_sel_hi:[0,1,1]
	ds_write_b64 v117, v[68:69] offset:8704
	v_pk_mul_f32 v[68:69], v[76:77], v[100:101] op_sel:[1,1] op_sel_hi:[1,0] neg_lo:[1,0]
	v_pk_fma_f32 v[70:71], v[76:77], v[100:101], v[68:69] op_sel_hi:[0,1,1]
	v_pk_mul_f32 v[76:77], v[78:79], v[70:71] op_sel:[1,1] op_sel_hi:[1,0] neg_lo:[1,0]
	v_pk_fma_f32 v[68:69], v[78:79], v[70:71], v[76:77] op_sel_hi:[0,1,1]
	ds_write_b64 v116, v[68:69] offset:13056
	v_pk_mul_f32 v[76:77], v[90:91], v[70:71] op_sel:[1,1] op_sel_hi:[1,0] neg_lo:[1,0]
	v_pk_fma_f32 v[68:69], v[90:91], v[70:71], v[76:77] op_sel_hi:[0,1,1]
	ds_write_b64 v117, v[68:69] offset:13056
	v_pk_mul_f32 v[68:69], v[70:71], v[100:101] op_sel:[1,1] op_sel_hi:[1,0] neg_lo:[1,0]
	v_pk_fma_f32 v[70:71], v[70:71], v[100:101], v[68:69] op_sel_hi:[0,1,1]
	v_pk_mul_f32 v[68:69], v[16:17], v[70:71] op_sel:[1,1] op_sel_hi:[1,0] neg_lo:[1,0]
	v_pk_fma_f32 v[16:17], v[16:17], v[70:71], v[68:69] op_sel_hi:[0,1,1]
	ds_write_b64 v116, v[16:17] offset:17408
	v_pk_mul_f32 v[68:69], v[80:81], v[70:71] op_sel:[1,1] op_sel_hi:[1,0] neg_lo:[1,0]
; #define LAS __attribute__((address_space(3)))
; #define SINCOSPI(x, s, c) do { const float hx_ = 0.5f * (x); *(s) = __builtin_amdgcn_sinf(hx_); *(c) = __builtin_amdgcn_cosf(hx_); } while (0)
; DEV void fft_f1x2(LAS cf* buf0, LAS cf* buf1, const cf (&z0)[8], const cf (&z1)[8], int tid) {
;     ...
;     float sn, cs; SINCOSPI(-(float)tid * (2.0f / 8192.0f), &sn, &cs);
;     const cf w = cf{cs, sn}; cf wp = cf{1.f, 0.f};
;     LAS cf* p0 = buf0 + PADI(tid); LAS cf* p1 = buf1 + PADI(tid);
; #pragma unroll
;     for (int p = 0; p < 16; ++p) { p0[544 * p] = cmul(v[BR16[p]], wp); p1[544 * p] = cmul(u[BR16[p]], wp); wp = cmul(wp, w); }
; }
	v_pk_fma_f32 v[16:17], v[80:81], v[70:71], v[68:69] op_sel_hi:[0,1,1]
	ds_write_b64 v117, v[16:17] offset:17408
	v_pk_mul_f32 v[16:17], v[70:71], v[100:101] op_sel:[1,1] op_sel_hi:[1,0] neg_lo:[1,0]
	v_pk_fma_f32 v[68:69], v[70:71], v[100:101], v[16:17] op_sel_hi:[0,1,1]
	v_pk_mul_f32 v[70:71], v[72:73], v[68:69] op_sel:[1,1] op_sel_hi:[1,0] neg_lo:[1,0]
	v_pk_fma_f32 v[16:17], v[72:73], v[68:69], v[70:71] op_sel_hi:[0,1,1]
	ds_write_b64 v116, v[16:17] offset:21760
	v_pk_mul_f32 v[70:71], v[86:87], v[68:69] op_sel:[1,1] op_sel_hi:[1,0] neg_lo:[1,0]
	v_pk_fma_f32 v[16:17], v[86:87], v[68:69], v[70:71] op_sel_hi:[0,1,1]
	ds_write_b64 v117, v[16:17] offset:21760
	v_pk_mul_f32 v[16:17], v[68:69], v[100:101] op_sel:[1,1] op_sel_hi:[1,0] neg_lo:[1,0]
	v_pk_fma_f32 v[68:69], v[68:69], v[100:101], v[16:17] op_sel_hi:[0,1,1]
	v_pk_mul_f32 v[70:71], v[18:19], v[68:69] op_sel:[1,1] op_sel_hi:[1,0] neg_lo:[1,0]
	v_pk_fma_f32 v[16:17], v[18:19], v[68:69], v[70:71] op_sel_hi:[0,1,1]
	ds_write_b64 v116, v[16:17] offset:26112
	v_pk_mul_f32 v[18:19], v[92:93], v[68:69] op_sel:[1,1] op_sel_hi:[1,0] neg_lo:[1,0]
	v_pk_fma_f32 v[16:17], v[92:93], v[68:69], v[18:19] op_sel_hi:[0,1,1]
	ds_write_b64 v117, v[16:17] offset:26112
	v_pk_mul_f32 v[16:17], v[68:69], v[100:101] op_sel:[1,1] op_sel_hi:[1,0] neg_lo:[1,0]
	v_pk_fma_f32 v[18:19], v[68:69], v[100:101], v[16:17] op_sel_hi:[0,1,1]
	v_pk_mul_f32 v[68:69], v[74:75], v[18:19] op_sel:[1,1] op_sel_hi:[1,0] neg_lo:[1,0]
	v_pk_fma_f32 v[16:17], v[74:75], v[18:19], v[68:69] op_sel_hi:[0,1,1]
	ds_write_b64 v116, v[16:17] offset:30464
	v_pk_mul_f32 v[68:69], v[82:83], v[18:19] op_sel:[1,1] op_sel_hi:[1,0] neg_lo:[1,0]
	v_pk_fma_f32 v[16:17], v[82:83], v[18:19], v[68:69] op_sel_hi:[0,1,1]
	ds_write_b64 v117, v[16:17] offset:30464
	v_pk_mul_f32 v[16:17], v[18:19], v[100:101] op_sel:[1,1] op_sel_hi:[1,0] neg_lo:[1,0]
	v_pk_fma_f32 v[18:19], v[18:19], v[100:101], v[16:17] op_sel_hi:[0,1,1]
	v_pk_mul_f32 v[16:17], v[4:5], v[18:19] op_sel:[1,1] op_sel_hi:[1,0] neg_lo:[1,0]
	v_pk_fma_f32 v[4:5], v[4:5], v[18:19], v[16:17] op_sel_hi:[0,1,1]
	ds_write_b64 v116, v[4:5] offset:34816
	v_pk_mul_f32 v[16:17], v[104:105], v[18:19] op_sel:[1,1] op_sel_hi:[1,0] neg_lo:[1,0]
	v_pk_fma_f32 v[4:5], v[104:105], v[18:19], v[16:17] op_sel_hi:[0,1,1]
	ds_write_b64 v117, v[4:5] offset:34816
	v_pk_mul_f32 v[4:5], v[18:19], v[100:101] op_sel:[1,1] op_sel_hi:[1,0] neg_lo:[1,0]
	v_pk_fma_f32 v[16:17], v[18:19], v[100:101], v[4:5] op_sel_hi:[0,1,1]
	v_pk_mul_f32 v[18:19], v[12:13], v[16:17] op_sel:[1,1] op_sel_hi:[1,0] neg_lo:[1,0]
	v_pk_fma_f32 v[4:5], v[12:13], v[16:17], v[18:19] op_sel_hi:[0,1,1]
	ds_write_b64 v116, v[4:5] offset:39168
	v_pk_mul_f32 v[12:13], v[88:89], v[16:17] op_sel:[1,1] op_sel_hi:[1,0] neg_lo:[1,0]
	v_pk_fma_f32 v[4:5], v[88:89], v[16:17], v[12:13] op_sel_hi:[0,1,1]
	ds_write_b64 v117, v[4:5] offset:39168
	v_pk_mul_f32 v[4:5], v[16:17], v[100:101] op_sel:[1,1] op_sel_hi:[1,0] neg_lo:[1,0]
	v_pk_fma_f32 v[12:13], v[16:17], v[100:101], v[4:5] op_sel_hi:[0,1,1]
	v_pk_mul_f32 v[16:17], v[6:7], v[12:13] op_sel:[1,1] op_sel_hi:[1,0] neg_lo:[1,0]
	v_pk_fma_f32 v[4:5], v[6:7], v[12:13], v[16:17] op_sel_hi:[0,1,1]
	ds_write_b64 v116, v[4:5] offset:43520
	v_pk_mul_f32 v[6:7], v[102:103], v[12:13] op_sel:[1,1] op_sel_hi:[1,0] neg_lo:[1,0]
	v_pk_fma_f32 v[4:5], v[102:103], v[12:13], v[6:7] op_sel_hi:[0,1,1]
	ds_write_b64 v117, v[4:5] offset:43520
	v_pk_mul_f32 v[4:5], v[12:13], v[100:101] op_sel:[1,1] op_sel_hi:[1,0] neg_lo:[1,0]
	v_pk_fma_f32 v[6:7], v[12:13], v[100:101], v[4:5] op_sel_hi:[0,1,1]
	v_pk_mul_f32 v[12:13], v[14:15], v[6:7] op_sel:[1,1] op_sel_hi:[1,0] neg_lo:[1,0]
	v_pk_fma_f32 v[4:5], v[14:15], v[6:7], v[12:13] op_sel_hi:[0,1,1]
	ds_write_b64 v116, v[4:5] offset:47872
	v_pk_mul_f32 v[12:13], v[96:97], v[6:7] op_sel:[1,1] op_sel_hi:[1,0] neg_lo:[1,0]
	v_pk_fma_f32 v[4:5], v[96:97], v[6:7], v[12:13] op_sel_hi:[0,1,1]
	ds_write_b64 v117, v[4:5] offset:47872
	v_pk_mul_f32 v[4:5], v[6:7], v[100:101] op_sel:[1,1] op_sel_hi:[1,0] neg_lo:[1,0]
	v_pk_fma_f32 v[6:7], v[6:7], v[100:101], v[4:5] op_sel_hi:[0,1,1]
	v_pk_mul_f32 v[4:5], v[0:1], v[6:7] op_sel:[1,1] op_sel_hi:[1,0] neg_lo:[1,0]
	v_pk_fma_f32 v[0:1], v[0:1], v[6:7], v[4:5] op_sel_hi:[0,1,1]
	ds_write_b64 v116, v[0:1] offset:52224
	v_pk_mul_f32 v[4:5], v[110:111], v[6:7] op_sel:[1,1] op_sel_hi:[1,0] neg_lo:[1,0]
	v_pk_fma_f32 v[0:1], v[110:111], v[6:7], v[4:5] op_sel_hi:[0,1,1]
	ds_write_b64 v117, v[0:1] offset:52224
	v_pk_mul_f32 v[0:1], v[6:7], v[100:101] op_sel:[1,1] op_sel_hi:[1,0] neg_lo:[1,0]
	v_pk_fma_f32 v[4:5], v[6:7], v[100:101], v[0:1] op_sel_hi:[0,1,1]
	v_pk_mul_f32 v[6:7], v[8:9], v[4:5] op_sel:[1,1] op_sel_hi:[1,0] neg_lo:[1,0]
	v_pk_fma_f32 v[0:1], v[8:9], v[4:5], v[6:7] op_sel_hi:[0,1,1]
	ds_write_b64 v116, v[0:1] offset:56576
	v_pk_mul_f32 v[6:7], v[108:109], v[4:5] op_sel:[1,1] op_sel_hi:[1,0] neg_lo:[1,0]
	v_pk_fma_f32 v[0:1], v[108:109], v[4:5], v[6:7] op_sel_hi:[0,1,1]
	ds_write_b64 v117, v[0:1] offset:56576
	v_pk_mul_f32 v[0:1], v[4:5], v[100:101] op_sel:[1,1] op_sel_hi:[1,0] neg_lo:[1,0]
	v_pk_fma_f32 v[4:5], v[4:5], v[100:101], v[0:1] op_sel_hi:[0,1,1]
	v_pk_mul_f32 v[6:7], v[2:3], v[4:5] op_sel:[1,1] op_sel_hi:[1,0] neg_lo:[1,0]
	v_pk_fma_f32 v[0:1], v[2:3], v[4:5], v[6:7] op_sel_hi:[0,1,1]
	ds_write_b64 v116, v[0:1] offset:60928
	v_pk_mul_f32 v[2:3], v[112:113], v[4:5] op_sel:[1,1] op_sel_hi:[1,0] neg_lo:[1,0]
	v_pk_fma_f32 v[0:1], v[112:113], v[4:5], v[2:3] op_sel_hi:[0,1,1]
	ds_write_b64 v117, v[0:1] offset:60928
	v_pk_mul_f32 v[0:1], v[4:5], v[100:101] op_sel:[1,1] op_sel_hi:[1,0] neg_lo:[1,0]
	v_pk_fma_f32 v[2:3], v[4:5], v[100:101], v[0:1] op_sel_hi:[0,1,1]
	v_pk_mul_f32 v[4:5], v[10:11], v[2:3] op_sel:[1,1] op_sel_hi:[1,0] neg_lo:[1,0]
	v_pk_fma_f32 v[0:1], v[10:11], v[2:3], v[4:5] op_sel_hi:[0,1,1]
	ds_write_b64 v116, v[0:1] offset:65280
	v_pk_mul_f32 v[4:5], v[106:107], v[2:3] op_sel:[1,1] op_sel_hi:[1,0] neg_lo:[1,0]
	v_pk_fma_f32 v[0:1], v[106:107], v[2:3], v[4:5] op_sel_hi:[0,1,1]
	ds_write_b64 v117, v[0:1] offset:65280
	v_mov_b32_e32 v0, v160
	s_waitcnt lgkmcnt(0)
	s_barrier
; #define LAS __attribute__((address_space(3)))
; #define OPAQUE_I(x) asm volatile("" : "+v"(x))
; template <int R, bool INV> DEV void dft_regs(cf (&v)[R]) {
; #pragma unroll
;     for (int s = R; s >= 2; s >>= 1) {
;         const int h = s >> 1;
; #pragma unroll
;         for (int b = 0; b < R; b += s) {
; #pragma unroll
;             for (int k = 0; k < h; ++k) {
;                 const cf a = v[b + k], c = v[b + k + h];
;                 v[b + k] = a + c;
;                 const cf d = a - c;
;                 const int m = k * (32 / s);
;                 const float wr = tw_cos(m), wi = INV ? tw_sin(m) : -tw_sin(m);
;                 v[b + k + h] = cf{d.x * wr - d.y * wi, d.x * wi + d.y * wr};
;             }
;         }
;     }
; }
; DEV void fft_f2(LAS cf* buf, int t8) {
;     OPAQUE_I(t8);
;     LAS cf* pb = buf + (t8 >> 4) * 544 + (t8 & 15);
;     cf v[32];
; #pragma unroll
;     for (int q = 0; q < 32; ++q) v[q] = pb[17 * q];
;     dft_regs<32, false>(v);
	s_nop 0
	v_lshrrev_b32_e32 v1, 4, v0
	v_and_b32_e32 v3, 15, v0
	v_mul_lo_u32 v1, v1, s15
	v_lshlrev_b32_e32 v0, 3, v3
	v_add3_u32 v2, v159, v1, v0
	ds_read2_b64 v[4:7], v2 offset1:17
	ds_read2_b64 v[8:11], v2 offset0:34 offset1:51
	ds_read2_b64 v[12:15], v2 offset0:68 offset1:85
	ds_read2_b64 v[16:19], v2 offset0:102 offset1:119
	ds_read2_b64 v[68:71], v2 offset0:136 offset1:153
	ds_read2_b64 v[72:75], v2 offset0:170 offset1:187
	ds_read2_b64 v[76:79], v2 offset0:204 offset1:221
	ds_read2_b64 v[80:83], v2 offset0:238 offset1:255
	v_add_u32_e32 v0, 0x800, v2
	ds_read2_b64 v[84:87], v0 offset0:16 offset1:33
	ds_read2_b64 v[88:91], v0 offset0:50 offset1:67
	ds_read2_b64 v[92:95], v0 offset0:84 offset1:101
	ds_read2_b64 v[96:99], v0 offset0:118 offset1:135
	ds_read2_b64 v[100:103], v0 offset0:152 offset1:169
	ds_read2_b64 v[104:107], v0 offset0:186 offset1:203
	ds_read2_b64 v[108:111], v0 offset0:220 offset1:237
	s_waitcnt lgkmcnt(6)
	v_pk_add_f32 v[116:117], v[4:5], v[84:85]
	v_pk_add_f32 v[4:5], v[4:5], v[84:85] neg_lo:[0,1] neg_hi:[0,1]
	v_add_u32_e32 v1, 0xc00, v2
	ds_read2_b64 v[112:115], v1 offset0:126 offset1:143
	v_mov_b32_e32 v118, v4
	v_mov_b32_e32 v119, v5
	v_cvt_f32_ubyte0_e32 v3, v3
	v_pk_add_f32 v[4:5], v[6:7], v[86:87]
	v_pk_add_f32 v[6:7], v[6:7], v[86:87] neg_lo:[0,1] neg_hi:[0,1]
	v_mul_f32_e32 v3, 0xbb800000, v3
	v_pk_mul_f32 v[84:85], v[6:7], s[82:83] op_sel_hi:[1,0]
	v_mul_f32_e32 v3, 0.5, v3
	v_pk_fma_f32 v[86:87], v[6:7], s[94:95], v[84:85] op_sel:[0,0,1] op_sel_hi:[1,0,0] neg_hi:[0,0,1]
	s_waitcnt lgkmcnt(6)
	v_pk_add_f32 v[6:7], v[8:9], v[88:89]
	v_pk_add_f32 v[8:9], v[8:9], v[88:89] neg_lo:[0,1] neg_hi:[0,1]
	v_pk_mul_f32 v[84:85], v[8:9], s[84:85] op_sel_hi:[1,0]
	v_pk_fma_f32 v[88:89], v[8:9], s[16:17], v[84:85] op_sel:[0,0,1] op_sel_hi:[1,0,0] neg_hi:[0,0,1]
	v_pk_add_f32 v[8:9], v[10:11], v[90:91]
	v_pk_add_f32 v[10:11], v[10:11], v[90:91] neg_lo:[0,1] neg_hi:[0,1]
	v_pk_mul_f32 v[84:85], v[10:11], s[4:5] op_sel_hi:[1,0]
	v_pk_fma_f32 v[90:91], v[10:11], s[86:87], v[84:85] op_sel:[0,0,1] op_sel_hi:[1,0,0] neg_hi:[0,0,1]
	s_waitcnt lgkmcnt(5)
	v_pk_add_f32 v[10:11], v[12:13], v[92:93]
	v_pk_add_f32 v[12:13], v[12:13], v[92:93] neg_lo:[0,1] neg_hi:[0,1]
	v_pk_mul_f32 v[84:85], v[12:13], s[18:19] op_sel_hi:[1,0]
	v_pk_fma_f32 v[92:93], v[12:13], s[18:19], v[84:85] op_sel:[0,0,1] op_sel_hi:[1,0,0] neg_hi:[0,0,1]
	v_pk_add_f32 v[12:13], v[14:15], v[94:95]
	v_pk_add_f32 v[14:15], v[14:15], v[94:95] neg_lo:[0,1] neg_hi:[0,1]
	v_pk_mul_f32 v[84:85], v[14:15], s[86:87] op_sel_hi:[1,0]
	v_pk_fma_f32 v[94:95], v[14:15], s[4:5], v[84:85] op_sel:[0,0,1] op_sel_hi:[1,0,0] neg_hi:[0,0,1]
	s_mov_b32 s5, s86
	s_waitcnt lgkmcnt(4)
	v_pk_add_f32 v[14:15], v[16:17], v[96:97]
	v_pk_add_f32 v[16:17], v[16:17], v[96:97] neg_lo:[0,1] neg_hi:[0,1]
	v_pk_mul_f32 v[84:85], v[16:17], s[16:17] op_sel_hi:[1,0]
	v_pk_fma_f32 v[96:97], v[16:17], s[84:85], v[84:85] op_sel:[0,0,1] op_sel_hi:[1,0,0] neg_hi:[0,0,1]
	v_pk_add_f32 v[16:17], v[18:19], v[98:99]
	v_pk_add_f32 v[18:19], v[18:19], v[98:99] neg_lo:[0,1] neg_hi:[0,1]
	v_pk_mul_f32 v[84:85], v[18:19], s[94:95] op_sel_hi:[1,0]
	v_pk_fma_f32 v[98:99], v[18:19], s[82:83], v[84:85] op_sel:[0,0,1] op_sel_hi:[1,0,0] neg_hi:[0,0,1]
	s_mov_b32 s83, s94
	s_waitcnt lgkmcnt(3)
	v_pk_add_f32 v[18:19], v[68:69], v[100:101]
	v_pk_add_f32 v[68:69], v[68:69], v[100:101] neg_lo:[0,1] neg_hi:[0,1]
	v_pk_add_f32 v[84:85], v[68:69], 0 op_sel:[1,0] op_sel_hi:[0,0] neg_hi:[1,0]
	v_pk_add_f32 v[68:69], v[70:71], v[102:103]
	v_pk_add_f32 v[70:71], v[70:71], v[102:103] neg_lo:[0,1] neg_hi:[0,1]
	v_pk_mul_f32 v[100:101], v[70:71], s[82:83] op_sel_hi:[0,1]
	v_pk_fma_f32 v[70:71], v[70:71], s[94:95], v[100:101] op_sel:[1,0,0] neg_lo:[0,0,1] neg_hi:[0,0,1]
	s_waitcnt lgkmcnt(2)
	v_pk_add_f32 v[100:101], v[72:73], v[104:105]
	v_pk_add_f32 v[72:73], v[72:73], v[104:105] neg_lo:[0,1] neg_hi:[0,1]
	v_pk_mul_f32 v[102:103], v[72:73], s[84:85] op_sel_hi:[0,1]
	v_pk_fma_f32 v[72:73], v[72:73], s[30:31], v[102:103] op_sel:[1,0,0] neg_lo:[0,0,1] neg_hi:[0,0,1]
	v_pk_add_f32 v[102:103], v[74:75], v[106:107]
	v_pk_add_f32 v[74:75], v[74:75], v[106:107] neg_lo:[0,1] neg_hi:[0,1]
	v_pk_mul_f32 v[104:105], v[74:75], s[4:5] op_sel_hi:[0,1]
	v_pk_fma_f32 v[74:75], v[74:75], s[86:87], v[104:105] op_sel:[1,0,0] neg_lo:[0,0,1] neg_hi:[0,0,1]
	s_waitcnt lgkmcnt(1)
	v_pk_add_f32 v[104:105], v[76:77], v[108:109]
	v_pk_add_f32 v[76:77], v[76:77], v[108:109] neg_lo:[0,1] neg_hi:[0,1]
	v_mul_f32_e32 v106, 0x3f3504f3, v76
	v_pk_fma_f32 v[76:77], v[76:77], s[28:29], v[106:107] op_sel:[1,0,0] op_sel_hi:[1,1,0] neg_lo:[0,0,1] neg_hi:[0,0,1]
	v_pk_add_f32 v[106:107], v[78:79], v[110:111]
	v_pk_add_f32 v[78:79], v[78:79], v[110:111] neg_lo:[0,1] neg_hi:[0,1]
	v_pk_mul_f32 v[108:109], v[78:79], s[2:3] op_sel_hi:[0,1]
	v_pk_fma_f32 v[78:79], v[78:79], s[10:11], v[108:109] op_sel:[1,0,0] neg_lo:[0,0,1] neg_hi:[0,0,1]
	s_waitcnt lgkmcnt(0)
; #define LAS __attribute__((address_space(3)))
; #define OPAQUE_I(x) asm volatile("" : "+v"(x))
; template <int R, bool INV> DEV void dft_regs(cf (&v)[R]) {
; #pragma unroll
;     for (int s = R; s >= 2; s >>= 1) {
;         const int h = s >> 1;
; #pragma unroll
;         for (int b = 0; b < R; b += s) {
; #pragma unroll
;             for (int k = 0; k < h; ++k) {
;                 const cf a = v[b + k], c = v[b + k + h];
;                 v[b + k] = a + c;
;                 const cf d = a - c;
;                 const int m = k * (32 / s);
;                 const float wr = tw_cos(m), wi = INV ? tw_sin(m) : -tw_sin(m);
;                 v[b + k + h] = cf{d.x * wr - d.y * wi, d.x * wi + d.y * wr};
;             }
;         }
;     }
; }
; DEV void fft_f2(LAS cf* buf, int t8) {
;     OPAQUE_I(t8);
;     LAS cf* pb = buf + (t8 >> 4) * 544 + (t8 & 15);
;     cf v[32];
; #pragma unroll
;     for (int q = 0; q < 32; ++q) v[q] = pb[17 * q];
;     dft_regs<32, false>(v);
	v_pk_add_f32 v[108:109], v[80:81], v[112:113]
	v_pk_add_f32 v[80:81], v[80:81], v[112:113] neg_lo:[0,1] neg_hi:[0,1]
	v_pk_mul_f32 v[110:111], v[80:81], s[24:25] op_sel_hi:[0,1]
	v_pk_fma_f32 v[80:81], v[80:81], s[34:35], v[110:111] op_sel:[1,0,0] neg_lo:[0,0,1] neg_hi:[0,0,1]
	v_pk_add_f32 v[110:111], v[82:83], v[114:115]
	v_pk_add_f32 v[82:83], v[82:83], v[114:115] neg_lo:[0,1] neg_hi:[0,1]
	v_pk_mul_f32 v[112:113], v[82:83], s[6:7] op_sel_hi:[0,1]
	v_pk_fma_f32 v[82:83], v[82:83], s[8:9], v[112:113] op_sel:[1,0,0] neg_lo:[0,0,1] neg_hi:[0,0,1]
	v_pk_add_f32 v[112:113], v[116:117], v[18:19]
	v_pk_add_f32 v[18:19], v[116:117], v[18:19] neg_lo:[0,1] neg_hi:[0,1]
	v_mov_b32_e32 v116, v18
	v_mov_b32_e32 v117, v19
	v_pk_add_f32 v[18:19], v[4:5], v[68:69]
	v_pk_add_f32 v[4:5], v[4:5], v[68:69] neg_lo:[0,1] neg_hi:[0,1]
	v_pk_mul_f32 v[68:69], v[4:5], s[84:85] op_sel_hi:[1,0]
	v_pk_fma_f32 v[114:115], v[4:5], s[16:17], v[68:69] op_sel:[0,0,1] op_sel_hi:[1,0,0] neg_hi:[0,0,1]
	v_pk_add_f32 v[4:5], v[6:7], v[100:101]
	v_pk_add_f32 v[6:7], v[6:7], v[100:101] neg_lo:[0,1] neg_hi:[0,1]
	v_pk_mul_f32 v[68:69], v[6:7], s[18:19] op_sel_hi:[1,0]
	v_pk_fma_f32 v[100:101], v[6:7], s[18:19], v[68:69] op_sel:[0,0,1] op_sel_hi:[1,0,0] neg_hi:[0,0,1]
	v_pk_add_f32 v[6:7], v[8:9], v[102:103]
	v_pk_add_f32 v[8:9], v[8:9], v[102:103] neg_lo:[0,1] neg_hi:[0,1]
	v_pk_mul_f32 v[68:69], v[8:9], s[16:17] op_sel_hi:[1,0]
	v_pk_fma_f32 v[102:103], v[8:9], s[84:85], v[68:69] op_sel:[0,0,1] op_sel_hi:[1,0,0] neg_hi:[0,0,1]
	v_pk_add_f32 v[8:9], v[10:11], v[104:105]
	v_pk_add_f32 v[10:11], v[10:11], v[104:105] neg_lo:[0,1] neg_hi:[0,1]
	v_pk_add_f32 v[68:69], v[10:11], 0 op_sel:[1,0] op_sel_hi:[0,0] neg_hi:[1,0]
	v_pk_add_f32 v[10:11], v[12:13], v[106:107]
	v_pk_add_f32 v[12:13], v[12:13], v[106:107] neg_lo:[0,1] neg_hi:[0,1]
	v_pk_mul_f32 v[104:105], v[12:13], s[84:85] op_sel_hi:[0,1]
	v_pk_fma_f32 v[12:13], v[12:13], s[30:31], v[104:105] op_sel:[1,0,0] neg_lo:[0,0,1] neg_hi:[0,0,1]
	v_pk_add_f32 v[104:105], v[14:15], v[108:109]
	v_pk_add_f32 v[14:15], v[14:15], v[108:109] neg_lo:[0,1] neg_hi:[0,1]
	v_mul_f32_e32 v106, 0x3f3504f3, v14
	v_pk_fma_f32 v[14:15], v[14:15], s[28:29], v[106:107] op_sel:[1,0,0] op_sel_hi:[1,1,0] neg_lo:[0,0,1] neg_hi:[0,0,1]
	v_pk_add_f32 v[106:107], v[16:17], v[110:111]
	v_pk_add_f32 v[16:17], v[16:17], v[110:111] neg_lo:[0,1] neg_hi:[0,1]
	v_pk_mul_f32 v[108:109], v[16:17], s[24:25] op_sel_hi:[0,1]
	v_pk_fma_f32 v[16:17], v[16:17], s[34:35], v[108:109] op_sel:[1,0,0] neg_lo:[0,0,1] neg_hi:[0,0,1]
	v_pk_add_f32 v[108:109], v[118:119], v[84:85]
	v_pk_add_f32 v[84:85], v[118:119], v[84:85] neg_lo:[0,1] neg_hi:[0,1]
	v_mov_b32_e32 v118, v84
	v_mov_b32_e32 v119, v85
	v_pk_add_f32 v[84:85], v[86:87], v[70:71]
	v_pk_add_f32 v[70:71], v[86:87], v[70:71] neg_lo:[0,1] neg_hi:[0,1]
	v_pk_mul_f32 v[86:87], v[70:71], s[84:85] op_sel_hi:[1,0]
	v_pk_fma_f32 v[110:111], v[70:71], s[16:17], v[86:87] op_sel:[0,0,1] op_sel_hi:[1,0,0] neg_hi:[0,0,1]
	v_pk_add_f32 v[70:71], v[88:89], v[72:73]
	v_pk_add_f32 v[72:73], v[88:89], v[72:73] neg_lo:[0,1] neg_hi:[0,1]
	v_pk_mul_f32 v[86:87], v[72:73], s[18:19] op_sel_hi:[1,0]
	v_pk_fma_f32 v[88:89], v[72:73], s[18:19], v[86:87] op_sel:[0,0,1] op_sel_hi:[1,0,0] neg_hi:[0,0,1]
	v_pk_add_f32 v[72:73], v[90:91], v[74:75]
	v_pk_add_f32 v[74:75], v[90:91], v[74:75] neg_lo:[0,1] neg_hi:[0,1]
	v_pk_mul_f32 v[86:87], v[74:75], s[16:17] op_sel_hi:[1,0]
	v_pk_fma_f32 v[90:91], v[74:75], s[84:85], v[86:87] op_sel:[0,0,1] op_sel_hi:[1,0,0] neg_hi:[0,0,1]
	v_pk_add_f32 v[74:75], v[92:93], v[76:77]
	v_pk_add_f32 v[76:77], v[92:93], v[76:77] neg_lo:[0,1] neg_hi:[0,1]
	v_pk_add_f32 v[86:87], v[76:77], 0 op_sel:[1,0] op_sel_hi:[0,0] neg_hi:[1,0]
	v_pk_add_f32 v[76:77], v[94:95], v[78:79]
	v_pk_add_f32 v[78:79], v[94:95], v[78:79] neg_lo:[0,1] neg_hi:[0,1]
	v_pk_mul_f32 v[92:93], v[78:79], s[84:85] op_sel_hi:[0,1]
	v_pk_fma_f32 v[78:79], v[78:79], s[30:31], v[92:93] op_sel:[1,0,0] neg_lo:[0,0,1] neg_hi:[0,0,1]
	v_pk_add_f32 v[92:93], v[96:97], v[80:81]
	v_pk_add_f32 v[80:81], v[96:97], v[80:81] neg_lo:[0,1] neg_hi:[0,1]
	v_mul_f32_e32 v94, 0x3f3504f3, v80
	v_pk_fma_f32 v[80:81], v[80:81], s[28:29], v[94:95] op_sel:[1,0,0] op_sel_hi:[1,1,0] neg_lo:[0,0,1] neg_hi:[0,0,1]
	v_pk_add_f32 v[94:95], v[98:99], v[82:83]
	v_pk_add_f32 v[82:83], v[98:99], v[82:83] neg_lo:[0,1] neg_hi:[0,1]
	v_pk_mul_f32 v[96:97], v[82:83], s[24:25] op_sel_hi:[0,1]
	v_pk_fma_f32 v[82:83], v[82:83], s[34:35], v[96:97] op_sel:[1,0,0] neg_lo:[0,0,1] neg_hi:[0,0,1]
	v_pk_add_f32 v[96:97], v[112:113], v[8:9]
	v_pk_add_f32 v[8:9], v[112:113], v[8:9] neg_lo:[0,1] neg_hi:[0,1]
	v_mov_b32_e32 v112, v8
	v_mov_b32_e32 v113, v9
	v_pk_add_f32 v[8:9], v[18:19], v[10:11]
	v_pk_add_f32 v[10:11], v[18:19], v[10:11] neg_lo:[0,1] neg_hi:[0,1]
	v_pk_mul_f32 v[18:19], v[10:11], s[18:19] op_sel_hi:[1,0]
	v_pk_fma_f32 v[98:99], v[10:11], s[18:19], v[18:19] op_sel:[0,0,1] op_sel_hi:[1,0,0] neg_hi:[0,0,1]
	v_pk_add_f32 v[10:11], v[4:5], v[104:105]
	v_pk_add_f32 v[4:5], v[4:5], v[104:105] neg_lo:[0,1] neg_hi:[0,1]
	v_pk_add_f32 v[18:19], v[4:5], 0 op_sel:[1,0] op_sel_hi:[0,0] neg_hi:[1,0]
	v_pk_add_f32 v[4:5], v[6:7], v[106:107]
	v_pk_add_f32 v[6:7], v[6:7], v[106:107] neg_lo:[0,1] neg_hi:[0,1]
	v_mul_f32_e32 v104, 0x3f3504f3, v6
	v_pk_fma_f32 v[6:7], v[6:7], s[28:29], v[104:105] op_sel:[1,0,0] op_sel_hi:[1,1,0] neg_lo:[0,0,1] neg_hi:[0,0,1]
	v_pk_add_f32 v[104:105], v[116:117], v[68:69]
	v_pk_add_f32 v[68:69], v[116:117], v[68:69] neg_lo:[0,1] neg_hi:[0,1]
	v_mov_b32_e32 v116, v68
	v_mov_b32_e32 v117, v69
	v_pk_add_f32 v[68:69], v[114:115], v[12:13]
	v_pk_add_f32 v[12:13], v[114:115], v[12:13] neg_lo:[0,1] neg_hi:[0,1]
; template <int R, bool INV> DEV void dft_regs(cf (&v)[R]) {
; #pragma unroll
;     for (int s = R; s >= 2; s >>= 1) {
;         const int h = s >> 1;
; #pragma unroll
;         for (int b = 0; b < R; b += s) {
; #pragma unroll
;             for (int k = 0; k < h; ++k) {
;                 const cf a = v[b + k], c = v[b + k + h];
;                 v[b + k] = a + c;
;                 const cf d = a - c;
;                 const int m = k * (32 / s);
;                 const float wr = tw_cos(m), wi = INV ? tw_sin(m) : -tw_sin(m);
;                 v[b + k + h] = cf{d.x * wr - d.y * wi, d.x * wi + d.y * wr};
;             }
;         }
;     }
; }
	v_pk_mul_f32 v[106:107], v[12:13], s[18:19] op_sel_hi:[1,0]
	v_pk_fma_f32 v[114:115], v[12:13], s[18:19], v[106:107] op_sel:[0,0,1] op_sel_hi:[1,0,0] neg_hi:[0,0,1]
	v_pk_add_f32 v[12:13], v[100:101], v[14:15]
	v_pk_add_f32 v[14:15], v[100:101], v[14:15] neg_lo:[0,1] neg_hi:[0,1]
	v_pk_add_f32 v[100:101], v[14:15], 0 op_sel:[1,0] op_sel_hi:[0,0] neg_hi:[1,0]
	v_pk_add_f32 v[14:15], v[102:103], v[16:17]
	v_pk_add_f32 v[16:17], v[102:103], v[16:17] neg_lo:[0,1] neg_hi:[0,1]
	v_mul_f32_e32 v102, 0x3f3504f3, v16
	v_pk_fma_f32 v[16:17], v[16:17], s[28:29], v[102:103] op_sel:[1,0,0] op_sel_hi:[1,1,0] neg_lo:[0,0,1] neg_hi:[0,0,1]
	v_pk_add_f32 v[102:103], v[108:109], v[74:75]
	v_pk_add_f32 v[74:75], v[108:109], v[74:75] neg_lo:[0,1] neg_hi:[0,1]
	v_mov_b32_e32 v108, v74
	v_mov_b32_e32 v109, v75
	v_pk_add_f32 v[74:75], v[84:85], v[76:77]
	v_pk_add_f32 v[76:77], v[84:85], v[76:77] neg_lo:[0,1] neg_hi:[0,1]
	v_pk_mul_f32 v[84:85], v[76:77], s[18:19] op_sel_hi:[1,0]
	v_pk_fma_f32 v[106:107], v[76:77], s[18:19], v[84:85] op_sel:[0,0,1] op_sel_hi:[1,0,0] neg_hi:[0,0,1]
	v_pk_add_f32 v[76:77], v[70:71], v[92:93]
	v_pk_add_f32 v[70:71], v[70:71], v[92:93] neg_lo:[0,1] neg_hi:[0,1]
	v_pk_add_f32 v[84:85], v[70:71], 0 op_sel:[1,0] op_sel_hi:[0,0] neg_hi:[1,0]
	v_pk_add_f32 v[70:71], v[72:73], v[94:95]
	v_pk_add_f32 v[72:73], v[72:73], v[94:95] neg_lo:[0,1] neg_hi:[0,1]
	v_mul_f32_e32 v92, 0x3f3504f3, v72
	v_pk_fma_f32 v[72:73], v[72:73], s[28:29], v[92:93] op_sel:[1,0,0] op_sel_hi:[1,1,0] neg_lo:[0,0,1] neg_hi:[0,0,1]
	v_pk_add_f32 v[92:93], v[118:119], v[86:87]
	v_pk_add_f32 v[86:87], v[118:119], v[86:87] neg_lo:[0,1] neg_hi:[0,1]
	v_mov_b32_e32 v118, v86
	v_mov_b32_e32 v119, v87
	v_pk_add_f32 v[86:87], v[110:111], v[78:79]
	v_pk_add_f32 v[78:79], v[110:111], v[78:79] neg_lo:[0,1] neg_hi:[0,1]
	v_pk_mul_f32 v[94:95], v[78:79], s[18:19] op_sel_hi:[1,0]
	v_pk_fma_f32 v[110:111], v[78:79], s[18:19], v[94:95] op_sel:[0,0,1] op_sel_hi:[1,0,0] neg_hi:[0,0,1]
	v_pk_add_f32 v[78:79], v[88:89], v[80:81]
	v_pk_add_f32 v[80:81], v[88:89], v[80:81] neg_lo:[0,1] neg_hi:[0,1]
	v_pk_add_f32 v[88:89], v[80:81], 0 op_sel:[1,0] op_sel_hi:[0,0] neg_hi:[1,0]
	v_pk_add_f32 v[80:81], v[90:91], v[82:83]
	v_pk_add_f32 v[82:83], v[90:91], v[82:83] neg_lo:[0,1] neg_hi:[0,1]
	v_mul_f32_e32 v90, 0x3f3504f3, v82
	v_pk_fma_f32 v[82:83], v[82:83], s[28:29], v[90:91] op_sel:[1,0,0] op_sel_hi:[1,1,0] neg_lo:[0,0,1] neg_hi:[0,0,1]
	v_pk_add_f32 v[90:91], v[96:97], v[10:11]
	v_pk_add_f32 v[10:11], v[96:97], v[10:11] neg_lo:[0,1] neg_hi:[0,1]
	v_mov_b32_e32 v96, v10
	v_mov_b32_e32 v97, v11
	v_pk_add_f32 v[10:11], v[8:9], v[4:5]
	v_pk_add_f32 v[4:5], v[8:9], v[4:5] neg_lo:[0,1] neg_hi:[0,1]
	v_pk_add_f32 v[8:9], v[4:5], 0 op_sel:[1,0] op_sel_hi:[0,0] neg_hi:[1,0]
	v_pk_add_f32 v[4:5], v[112:113], v[18:19]
	v_pk_add_f32 v[18:19], v[112:113], v[18:19] neg_lo:[0,1] neg_hi:[0,1]
	v_mov_b32_e32 v112, v18
	v_mov_b32_e32 v113, v19
	v_pk_add_f32 v[18:19], v[98:99], v[6:7]
	v_pk_add_f32 v[6:7], v[98:99], v[6:7] neg_lo:[0,1] neg_hi:[0,1]
	v_pk_add_f32 v[94:95], v[6:7], 0 op_sel:[1,0] op_sel_hi:[0,0] neg_hi:[1,0]
	v_pk_add_f32 v[6:7], v[104:105], v[12:13]
	v_pk_add_f32 v[12:13], v[104:105], v[12:13] neg_lo:[0,1] neg_hi:[0,1]
	v_mov_b32_e32 v104, v12
	v_mov_b32_e32 v105, v13
	v_pk_add_f32 v[98:99], v[116:117], v[100:101] neg_lo:[0,1] neg_hi:[0,1]
	v_pk_add_f32 v[12:13], v[68:69], v[14:15]
	v_pk_add_f32 v[14:15], v[68:69], v[14:15] neg_lo:[0,1] neg_hi:[0,1]
	v_pk_add_f32 v[68:69], v[14:15], 0 op_sel:[1,0] op_sel_hi:[0,0] neg_hi:[1,0]
	v_pk_add_f32 v[14:15], v[116:117], v[100:101]
	v_mov_b32_e32 v116, v98
	v_mov_b32_e32 v117, v99
	v_pk_add_f32 v[98:99], v[114:115], v[16:17]
	v_pk_add_f32 v[16:17], v[114:115], v[16:17] neg_lo:[0,1] neg_hi:[0,1]
	v_pk_add_f32 v[100:101], v[16:17], 0 op_sel:[1,0] op_sel_hi:[0,0] neg_hi:[1,0]
	v_pk_add_f32 v[16:17], v[102:103], v[76:77]
	v_pk_add_f32 v[76:77], v[102:103], v[76:77] neg_lo:[0,1] neg_hi:[0,1]
	v_mov_b32_e32 v114, v76
	v_mov_b32_e32 v115, v77
	v_pk_add_f32 v[76:77], v[74:75], v[70:71]
	v_pk_add_f32 v[70:71], v[74:75], v[70:71] neg_lo:[0,1] neg_hi:[0,1]
	v_pk_add_f32 v[74:75], v[70:71], 0 op_sel:[1,0] op_sel_hi:[0,0] neg_hi:[1,0]
	v_pk_add_f32 v[70:71], v[108:109], v[84:85]
	v_pk_add_f32 v[84:85], v[108:109], v[84:85] neg_lo:[0,1] neg_hi:[0,1]
	v_mov_b32_e32 v108, v84
	v_mov_b32_e32 v109, v85
	v_pk_add_f32 v[84:85], v[106:107], v[72:73]
	v_pk_add_f32 v[72:73], v[106:107], v[72:73] neg_lo:[0,1] neg_hi:[0,1]
	v_pk_add_f32 v[102:103], v[72:73], 0 op_sel:[1,0] op_sel_hi:[0,0] neg_hi:[1,0]
	v_pk_add_f32 v[72:73], v[92:93], v[78:79]
	v_pk_add_f32 v[78:79], v[92:93], v[78:79] neg_lo:[0,1] neg_hi:[0,1]
	v_mov_b32_e32 v106, v78
	v_mov_b32_e32 v107, v79
	v_pk_add_f32 v[78:79], v[86:87], v[80:81]
	v_pk_add_f32 v[80:81], v[86:87], v[80:81] neg_lo:[0,1] neg_hi:[0,1]
	v_pk_add_f32 v[86:87], v[80:81], 0 op_sel:[1,0] op_sel_hi:[0,0] neg_hi:[1,0]
	v_pk_add_f32 v[80:81], v[118:119], v[88:89]
	v_pk_add_f32 v[88:89], v[118:119], v[88:89] neg_lo:[0,1] neg_hi:[0,1]
	v_mov_b32_e32 v118, v88
	v_mov_b32_e32 v119, v89
	v_pk_add_f32 v[88:89], v[110:111], v[82:83]
	v_pk_add_f32 v[82:83], v[110:111], v[82:83] neg_lo:[0,1] neg_hi:[0,1]
	v_pk_add_f32 v[92:93], v[82:83], 0 op_sel:[1,0] op_sel_hi:[0,0] neg_hi:[1,0]
	v_pk_add_f32 v[82:83], v[90:91], v[10:11]
	v_pk_add_f32 v[10:11], v[90:91], v[10:11] neg_lo:[0,1] neg_hi:[0,1]
	v_mov_b32_e32 v110, v10
	v_mov_b32_e32 v111, v11
	v_pk_add_f32 v[10:11], v[96:97], v[8:9]
	v_pk_add_f32 v[8:9], v[96:97], v[8:9] neg_lo:[0,1] neg_hi:[0,1]
	v_mov_b32_e32 v96, v8
	v_mov_b32_e32 v97, v9
	v_pk_add_f32 v[8:9], v[4:5], v[18:19]
; #define SINCOSPI(x, s, c) do { const float hx_ = 0.5f * (x); *(s) = __builtin_amdgcn_sinf(hx_); *(c) = __builtin_amdgcn_cosf(hx_); } while (0)
; template <int R, bool INV> DEV void dft_regs(cf (&v)[R]) {
; #pragma unroll
;     for (int s = R; s >= 2; s >>= 1) {
;         const int h = s >> 1;
; #pragma unroll
;         for (int b = 0; b < R; b += s) {
; #pragma unroll
;             for (int k = 0; k < h; ++k) {
;                 const cf a = v[b + k], c = v[b + k + h];
;                 v[b + k] = a + c;
;                 const cf d = a - c;
;                 const int m = k * (32 / s);
;                 const float wr = tw_cos(m), wi = INV ? tw_sin(m) : -tw_sin(m);
;                 v[b + k + h] = cf{d.x * wr - d.y * wi, d.x * wi + d.y * wr};
;             }
;         }
;     }
; }
; DEV void fft_f2(LAS cf* buf, int t8) {
;     ...
;     float sn, cs; SINCOSPI(-(float)(t8 & 15) * (2.0f / 512.0f), &sn, &cs);
;     const cf w = cf{cs, sn}; cf wp = cf{1.f, 0.f};
; #pragma unroll
;     for (int p = 0; p < 32; ++p) { pb[17 * p] = cmul(v[BR32[p]], wp); wp = cmul(wp, w); }
	v_pk_add_f32 v[4:5], v[4:5], v[18:19] neg_lo:[0,1] neg_hi:[0,1]
	v_mov_b32_e32 v90, v4
	v_mov_b32_e32 v91, v5
	v_pk_add_f32 v[18:19], v[112:113], v[94:95] neg_lo:[0,1] neg_hi:[0,1]
	v_pk_add_f32 v[4:5], v[112:113], v[94:95]
	v_mov_b32_e32 v112, v18
	v_mov_b32_e32 v113, v19
	v_pk_add_f32 v[18:19], v[6:7], v[12:13]
	v_pk_add_f32 v[6:7], v[6:7], v[12:13] neg_lo:[0,1] neg_hi:[0,1]
	v_mov_b32_e32 v94, v6
	v_mov_b32_e32 v95, v7
	v_pk_add_f32 v[12:13], v[104:105], v[68:69] neg_lo:[0,1] neg_hi:[0,1]
	v_pk_add_f32 v[6:7], v[104:105], v[68:69]
	v_mov_b32_e32 v104, v12
	v_mov_b32_e32 v105, v13
	v_pk_add_f32 v[12:13], v[14:15], v[98:99]
	v_pk_add_f32 v[14:15], v[14:15], v[98:99] neg_lo:[0,1] neg_hi:[0,1]
	v_mov_b32_e32 v98, v14
	v_mov_b32_e32 v99, v15
	v_pk_add_f32 v[68:69], v[116:117], v[100:101] neg_lo:[0,1] neg_hi:[0,1]
	v_pk_add_f32 v[14:15], v[116:117], v[100:101]
	v_mov_b32_e32 v116, v68
	v_mov_b32_e32 v117, v69
	v_pk_add_f32 v[68:69], v[16:17], v[76:77]
	v_pk_add_f32 v[16:17], v[16:17], v[76:77] neg_lo:[0,1] neg_hi:[0,1]
	v_mov_b32_e32 v100, v16
	v_mov_b32_e32 v101, v17
	v_pk_add_f32 v[16:17], v[114:115], v[74:75]
	v_pk_add_f32 v[74:75], v[114:115], v[74:75] neg_lo:[0,1] neg_hi:[0,1]
	v_mov_b32_e32 v114, v74
	v_mov_b32_e32 v115, v75
	v_pk_add_f32 v[74:75], v[70:71], v[84:85]
	v_pk_add_f32 v[70:71], v[70:71], v[84:85] neg_lo:[0,1] neg_hi:[0,1]
	v_mov_b32_e32 v84, v70
	v_mov_b32_e32 v85, v71
	v_pk_add_f32 v[76:77], v[108:109], v[102:103] neg_lo:[0,1] neg_hi:[0,1]
	v_pk_add_f32 v[70:71], v[108:109], v[102:103]
	v_mov_b32_e32 v108, v76
	v_mov_b32_e32 v109, v77
	v_pk_add_f32 v[76:77], v[72:73], v[78:79]
	v_pk_add_f32 v[72:73], v[72:73], v[78:79] neg_lo:[0,1] neg_hi:[0,1]
	v_mov_b32_e32 v102, v72
	v_mov_b32_e32 v103, v73
	v_pk_add_f32 v[78:79], v[106:107], v[86:87] neg_lo:[0,1] neg_hi:[0,1]
	v_pk_add_f32 v[72:73], v[106:107], v[86:87]
	v_mov_b32_e32 v106, v78
	v_mov_b32_e32 v107, v79
	v_pk_add_f32 v[78:79], v[80:81], v[88:89]
	v_pk_add_f32 v[80:81], v[80:81], v[88:89] neg_lo:[0,1] neg_hi:[0,1]
	v_mov_b32_e32 v88, v80
	v_mov_b32_e32 v89, v81
	v_pk_add_f32 v[86:87], v[118:119], v[92:93] neg_lo:[0,1] neg_hi:[0,1]
	v_pk_add_f32 v[80:81], v[118:119], v[92:93]
	v_mov_b32_e32 v118, v86
	v_mov_b32_e32 v119, v87
	v_pk_mul_f32 v[92:93], v[82:83], v[66:67] op_sel:[1,1] op_sel_hi:[1,0] neg_lo:[1,0]
	v_pk_fma_f32 v[82:83], v[82:83], v[66:67], v[92:93] op_sel_hi:[0,1,1]
	s_nop 0
	v_sin_f32_e32 v87, v3
	v_cos_f32_e32 v86, v3
	v_pk_mul_f32 v[92:93], v[66:67], v[86:87] op_sel:[1,1] op_sel_hi:[1,0] neg_lo:[1,0]
	v_pk_fma_f32 v[120:121], v[66:67], v[86:87], v[92:93] op_sel_hi:[0,1,1]
	v_pk_mul_f32 v[92:93], v[68:69], v[120:121] op_sel:[1,1] op_sel_hi:[1,0] neg_lo:[1,0]
	v_pk_fma_f32 v[68:69], v[68:69], v[120:121], v[92:93] op_sel_hi:[0,1,1]
	ds_write2_b64 v2, v[82:83], v[68:69] offset1:17
	v_pk_mul_f32 v[68:69], v[120:121], v[86:87] op_sel:[1,1] op_sel_hi:[1,0] neg_lo:[1,0]
	v_pk_fma_f32 v[82:83], v[120:121], v[86:87], v[68:69] op_sel_hi:[0,1,1]
	v_pk_mul_f32 v[68:69], v[18:19], v[82:83] op_sel:[1,1] op_sel_hi:[1,0] neg_lo:[1,0]
	v_pk_fma_f32 v[18:19], v[18:19], v[82:83], v[68:69] op_sel_hi:[0,1,1]
	s_nop 0
	v_pk_mul_f32 v[68:69], v[82:83], v[86:87] op_sel:[1,1] op_sel_hi:[1,0] neg_lo:[1,0]
	v_pk_fma_f32 v[82:83], v[82:83], v[86:87], v[68:69] op_sel_hi:[0,1,1]
	v_pk_mul_f32 v[92:93], v[76:77], v[82:83] op_sel:[1,1] op_sel_hi:[1,0] neg_lo:[1,0]
	v_pk_fma_f32 v[68:69], v[76:77], v[82:83], v[92:93] op_sel_hi:[0,1,1]
	ds_write2_b64 v2, v[18:19], v[68:69] offset0:34 offset1:51
	v_pk_mul_f32 v[18:19], v[82:83], v[86:87] op_sel:[1,1] op_sel_hi:[1,0] neg_lo:[1,0]
	v_pk_fma_f32 v[68:69], v[82:83], v[86:87], v[18:19] op_sel_hi:[0,1,1]
	v_pk_mul_f32 v[18:19], v[8:9], v[68:69] op_sel:[1,1] op_sel_hi:[1,0] neg_lo:[1,0]
	v_pk_fma_f32 v[8:9], v[8:9], v[68:69], v[18:19] op_sel_hi:[0,1,1]
	s_nop 0
	v_pk_mul_f32 v[18:19], v[68:69], v[86:87] op_sel:[1,1] op_sel_hi:[1,0] neg_lo:[1,0]
	v_pk_fma_f32 v[68:69], v[68:69], v[86:87], v[18:19] op_sel_hi:[0,1,1]
	v_pk_mul_f32 v[76:77], v[74:75], v[68:69] op_sel:[1,1] op_sel_hi:[1,0] neg_lo:[1,0]
	v_pk_fma_f32 v[18:19], v[74:75], v[68:69], v[76:77] op_sel_hi:[0,1,1]
	ds_write2_b64 v2, v[8:9], v[18:19] offset0:68 offset1:85
	v_pk_mul_f32 v[8:9], v[68:69], v[86:87] op_sel:[1,1] op_sel_hi:[1,0] neg_lo:[1,0]
	v_pk_fma_f32 v[18:19], v[68:69], v[86:87], v[8:9] op_sel_hi:[0,1,1]
	v_pk_mul_f32 v[68:69], v[12:13], v[18:19] op_sel:[1,1] op_sel_hi:[1,0] neg_lo:[1,0]
	v_pk_fma_f32 v[8:9], v[12:13], v[18:19], v[68:69] op_sel_hi:[0,1,1]
	v_pk_mul_f32 v[12:13], v[18:19], v[86:87] op_sel:[1,1] op_sel_hi:[1,0] neg_lo:[1,0]
	v_pk_fma_f32 v[18:19], v[18:19], v[86:87], v[12:13] op_sel_hi:[0,1,1]
	v_pk_mul_f32 v[68:69], v[78:79], v[18:19] op_sel:[1,1] op_sel_hi:[1,0] neg_lo:[1,0]
	v_pk_fma_f32 v[12:13], v[78:79], v[18:19], v[68:69] op_sel_hi:[0,1,1]
	ds_write2_b64 v2, v[8:9], v[12:13] offset0:102 offset1:119
	v_pk_mul_f32 v[8:9], v[18:19], v[86:87] op_sel:[1,1] op_sel_hi:[1,0] neg_lo:[1,0]
	v_pk_fma_f32 v[12:13], v[18:19], v[86:87], v[8:9] op_sel_hi:[0,1,1]
	v_pk_mul_f32 v[18:19], v[10:11], v[12:13] op_sel:[1,1] op_sel_hi:[1,0] neg_lo:[1,0]
	v_pk_fma_f32 v[8:9], v[10:11], v[12:13], v[18:19] op_sel_hi:[0,1,1]
	v_pk_mul_f32 v[10:11], v[12:13], v[86:87] op_sel:[1,1] op_sel_hi:[1,0] neg_lo:[1,0]
	v_pk_fma_f32 v[12:13], v[12:13], v[86:87], v[10:11] op_sel_hi:[0,1,1]
	v_pk_mul_f32 v[18:19], v[16:17], v[12:13] op_sel:[1,1] op_sel_hi:[1,0] neg_lo:[1,0]
	v_pk_fma_f32 v[10:11], v[16:17], v[12:13], v[18:19] op_sel_hi:[0,1,1]
	ds_write2_b64 v2, v[8:9], v[10:11] offset0:136 offset1:153
	v_pk_mul_f32 v[8:9], v[12:13], v[86:87] op_sel:[1,1] op_sel_hi:[1,0] neg_lo:[1,0]
; #define SINCOSPI(x, s, c) do { const float hx_ = 0.5f * (x); *(s) = __builtin_amdgcn_sinf(hx_); *(c) = __builtin_amdgcn_cosf(hx_); } while (0)
; DEV void fft_f2(LAS cf* buf, int t8) {
;     ...
;     float sn, cs; SINCOSPI(-(float)(t8 & 15) * (2.0f / 512.0f), &sn, &cs);
;     const cf w = cf{cs, sn}; cf wp = cf{1.f, 0.f};
; #pragma unroll
;     for (int p = 0; p < 32; ++p) { pb[17 * p] = cmul(v[BR32[p]], wp); wp = cmul(wp, w); }
	v_pk_fma_f32 v[10:11], v[12:13], v[86:87], v[8:9] op_sel_hi:[0,1,1]
	v_pk_mul_f32 v[8:9], v[6:7], v[10:11] op_sel:[1,1] op_sel_hi:[1,0] neg_lo:[1,0]
	v_pk_fma_f32 v[6:7], v[6:7], v[10:11], v[8:9] op_sel_hi:[0,1,1]
	s_nop 0
	v_pk_mul_f32 v[8:9], v[10:11], v[86:87] op_sel:[1,1] op_sel_hi:[1,0] neg_lo:[1,0]
	v_pk_fma_f32 v[10:11], v[10:11], v[86:87], v[8:9] op_sel_hi:[0,1,1]
	v_pk_mul_f32 v[12:13], v[72:73], v[10:11] op_sel:[1,1] op_sel_hi:[1,0] neg_lo:[1,0]
	v_pk_fma_f32 v[8:9], v[72:73], v[10:11], v[12:13] op_sel_hi:[0,1,1]
	ds_write2_b64 v2, v[6:7], v[8:9] offset0:170 offset1:187
	v_pk_mul_f32 v[6:7], v[10:11], v[86:87] op_sel:[1,1] op_sel_hi:[1,0] neg_lo:[1,0]
	v_pk_fma_f32 v[8:9], v[10:11], v[86:87], v[6:7] op_sel_hi:[0,1,1]
	v_pk_mul_f32 v[6:7], v[4:5], v[8:9] op_sel:[1,1] op_sel_hi:[1,0] neg_lo:[1,0]
	v_pk_fma_f32 v[4:5], v[4:5], v[8:9], v[6:7] op_sel_hi:[0,1,1]
	s_nop 0
	v_pk_mul_f32 v[6:7], v[8:9], v[86:87] op_sel:[1,1] op_sel_hi:[1,0] neg_lo:[1,0]
	v_pk_fma_f32 v[8:9], v[8:9], v[86:87], v[6:7] op_sel_hi:[0,1,1]
	v_pk_mul_f32 v[10:11], v[70:71], v[8:9] op_sel:[1,1] op_sel_hi:[1,0] neg_lo:[1,0]
	v_pk_fma_f32 v[6:7], v[70:71], v[8:9], v[10:11] op_sel_hi:[0,1,1]
	ds_write2_b64 v2, v[4:5], v[6:7] offset0:204 offset1:221
	v_pk_mul_f32 v[4:5], v[8:9], v[86:87] op_sel:[1,1] op_sel_hi:[1,0] neg_lo:[1,0]
	v_pk_fma_f32 v[6:7], v[8:9], v[86:87], v[4:5] op_sel_hi:[0,1,1]
	v_pk_mul_f32 v[8:9], v[14:15], v[6:7] op_sel:[1,1] op_sel_hi:[1,0] neg_lo:[1,0]
	v_pk_fma_f32 v[4:5], v[14:15], v[6:7], v[8:9] op_sel_hi:[0,1,1]
	s_nop 0
	v_pk_mul_f32 v[8:9], v[6:7], v[86:87] op_sel:[1,1] op_sel_hi:[1,0] neg_lo:[1,0]
	v_pk_fma_f32 v[6:7], v[6:7], v[86:87], v[8:9] op_sel_hi:[0,1,1]
	v_pk_mul_f32 v[10:11], v[80:81], v[6:7] op_sel:[1,1] op_sel_hi:[1,0] neg_lo:[1,0]
	v_pk_fma_f32 v[8:9], v[80:81], v[6:7], v[10:11] op_sel_hi:[0,1,1]
	ds_write2_b64 v2, v[4:5], v[8:9] offset0:238 offset1:255
	v_pk_mul_f32 v[2:3], v[6:7], v[86:87] op_sel:[1,1] op_sel_hi:[1,0] neg_lo:[1,0]
	v_pk_fma_f32 v[4:5], v[6:7], v[86:87], v[2:3] op_sel_hi:[0,1,1]
	v_pk_mul_f32 v[6:7], v[110:111], v[4:5] op_sel:[1,1] op_sel_hi:[1,0] neg_lo:[1,0]
	v_pk_fma_f32 v[2:3], v[110:111], v[4:5], v[6:7] op_sel_hi:[0,1,1]
	s_nop 0
	v_pk_mul_f32 v[6:7], v[4:5], v[86:87] op_sel:[1,1] op_sel_hi:[1,0] neg_lo:[1,0]
	v_pk_fma_f32 v[4:5], v[4:5], v[86:87], v[6:7] op_sel_hi:[0,1,1]
	v_pk_mul_f32 v[8:9], v[100:101], v[4:5] op_sel:[1,1] op_sel_hi:[1,0] neg_lo:[1,0]
	v_pk_fma_f32 v[6:7], v[100:101], v[4:5], v[8:9] op_sel_hi:[0,1,1]
	ds_write2_b64 v0, v[2:3], v[6:7] offset0:16 offset1:33
	v_pk_mul_f32 v[2:3], v[4:5], v[86:87] op_sel:[1,1] op_sel_hi:[1,0] neg_lo:[1,0]
	v_pk_fma_f32 v[4:5], v[4:5], v[86:87], v[2:3] op_sel_hi:[0,1,1]
	v_pk_mul_f32 v[6:7], v[94:95], v[4:5] op_sel:[1,1] op_sel_hi:[1,0] neg_lo:[1,0]
	v_pk_fma_f32 v[2:3], v[94:95], v[4:5], v[6:7] op_sel_hi:[0,1,1]
	s_nop 0
	v_pk_mul_f32 v[6:7], v[4:5], v[86:87] op_sel:[1,1] op_sel_hi:[1,0] neg_lo:[1,0]
	v_pk_fma_f32 v[4:5], v[4:5], v[86:87], v[6:7] op_sel_hi:[0,1,1]
	v_pk_mul_f32 v[8:9], v[102:103], v[4:5] op_sel:[1,1] op_sel_hi:[1,0] neg_lo:[1,0]
	v_pk_fma_f32 v[6:7], v[102:103], v[4:5], v[8:9] op_sel_hi:[0,1,1]
	ds_write2_b64 v0, v[2:3], v[6:7] offset0:50 offset1:67
	v_pk_mul_f32 v[2:3], v[4:5], v[86:87] op_sel:[1,1] op_sel_hi:[1,0] neg_lo:[1,0]
	v_pk_fma_f32 v[4:5], v[4:5], v[86:87], v[2:3] op_sel_hi:[0,1,1]
	v_pk_mul_f32 v[6:7], v[90:91], v[4:5] op_sel:[1,1] op_sel_hi:[1,0] neg_lo:[1,0]
	v_pk_fma_f32 v[2:3], v[90:91], v[4:5], v[6:7] op_sel_hi:[0,1,1]
	s_nop 0
	v_pk_mul_f32 v[6:7], v[4:5], v[86:87] op_sel:[1,1] op_sel_hi:[1,0] neg_lo:[1,0]
	v_pk_fma_f32 v[4:5], v[4:5], v[86:87], v[6:7] op_sel_hi:[0,1,1]
	v_pk_mul_f32 v[8:9], v[84:85], v[4:5] op_sel:[1,1] op_sel_hi:[1,0] neg_lo:[1,0]
	v_pk_fma_f32 v[6:7], v[84:85], v[4:5], v[8:9] op_sel_hi:[0,1,1]
	ds_write2_b64 v0, v[2:3], v[6:7] offset0:84 offset1:101
	v_pk_mul_f32 v[2:3], v[4:5], v[86:87] op_sel:[1,1] op_sel_hi:[1,0] neg_lo:[1,0]
	v_pk_fma_f32 v[4:5], v[4:5], v[86:87], v[2:3] op_sel_hi:[0,1,1]
	v_pk_mul_f32 v[6:7], v[98:99], v[4:5] op_sel:[1,1] op_sel_hi:[1,0] neg_lo:[1,0]
	v_pk_fma_f32 v[2:3], v[98:99], v[4:5], v[6:7] op_sel_hi:[0,1,1]
	s_nop 0
	v_pk_mul_f32 v[6:7], v[4:5], v[86:87] op_sel:[1,1] op_sel_hi:[1,0] neg_lo:[1,0]
	v_pk_fma_f32 v[4:5], v[4:5], v[86:87], v[6:7] op_sel_hi:[0,1,1]
	v_pk_mul_f32 v[8:9], v[88:89], v[4:5] op_sel:[1,1] op_sel_hi:[1,0] neg_lo:[1,0]
	v_pk_fma_f32 v[6:7], v[88:89], v[4:5], v[8:9] op_sel_hi:[0,1,1]
	ds_write2_b64 v0, v[2:3], v[6:7] offset0:118 offset1:135
	v_pk_mul_f32 v[2:3], v[4:5], v[86:87] op_sel:[1,1] op_sel_hi:[1,0] neg_lo:[1,0]
	v_pk_fma_f32 v[4:5], v[4:5], v[86:87], v[2:3] op_sel_hi:[0,1,1]
	v_pk_mul_f32 v[6:7], v[96:97], v[4:5] op_sel:[1,1] op_sel_hi:[1,0] neg_lo:[1,0]
	v_pk_fma_f32 v[2:3], v[96:97], v[4:5], v[6:7] op_sel_hi:[0,1,1]
	s_nop 0
	v_pk_mul_f32 v[6:7], v[4:5], v[86:87] op_sel:[1,1] op_sel_hi:[1,0] neg_lo:[1,0]
	v_pk_fma_f32 v[4:5], v[4:5], v[86:87], v[6:7] op_sel_hi:[0,1,1]
	v_pk_mul_f32 v[8:9], v[114:115], v[4:5] op_sel:[1,1] op_sel_hi:[1,0] neg_lo:[1,0]
	v_pk_fma_f32 v[6:7], v[114:115], v[4:5], v[8:9] op_sel_hi:[0,1,1]
	ds_write2_b64 v0, v[2:3], v[6:7] offset0:152 offset1:169
	v_pk_mul_f32 v[2:3], v[4:5], v[86:87] op_sel:[1,1] op_sel_hi:[1,0] neg_lo:[1,0]
	v_pk_fma_f32 v[4:5], v[4:5], v[86:87], v[2:3] op_sel_hi:[0,1,1]
	v_pk_mul_f32 v[6:7], v[104:105], v[4:5] op_sel:[1,1] op_sel_hi:[1,0] neg_lo:[1,0]
	v_pk_fma_f32 v[2:3], v[104:105], v[4:5], v[6:7] op_sel_hi:[0,1,1]
	s_nop 0
	v_pk_mul_f32 v[6:7], v[4:5], v[86:87] op_sel:[1,1] op_sel_hi:[1,0] neg_lo:[1,0]
	v_pk_fma_f32 v[4:5], v[4:5], v[86:87], v[6:7] op_sel_hi:[0,1,1]
; #define LAS __attribute__((address_space(3)))
; template <int R, bool INV> DEV void dft_regs(cf (&v)[R]) {
; #pragma unroll
;     for (int s = R; s >= 2; s >>= 1) {
;         const int h = s >> 1;
; #pragma unroll
;         for (int b = 0; b < R; b += s) {
; #pragma unroll
;             for (int k = 0; k < h; ++k) {
;                 const cf a = v[b + k], c = v[b + k + h];
;                 v[b + k] = a + c;
;                 const cf d = a - c;
;                 const int m = k * (32 / s);
;                 const float wr = tw_cos(m), wi = INV ? tw_sin(m) : -tw_sin(m);
;                 v[b + k + h] = cf{d.x * wr - d.y * wi, d.x * wi + d.y * wr};
;             }
;         }
;     }
; }
; DEV void fft_midx2(LAS cf* buf0, LAS cf* buf1, const unsigned* Kp, int blk) {
;     ...
;     LAS cf* p0 = buf0 + 17 * blk; LAS cf* p1 = buf1 + 17 * blk;
;     cf v[16], u[16];
; #pragma unroll
;     for (int q = 0; q < 16; ++q) { v[q] = p0[q]; u[q] = p1[q]; }
;     dft_regs<16, false>(v); dft_regs<16, false>(u);
	v_pk_mul_f32 v[8:9], v[106:107], v[4:5] op_sel:[1,1] op_sel_hi:[1,0] neg_lo:[1,0]
	v_pk_fma_f32 v[6:7], v[106:107], v[4:5], v[8:9] op_sel_hi:[0,1,1]
	ds_write2_b64 v0, v[2:3], v[6:7] offset0:186 offset1:203
	v_pk_mul_f32 v[2:3], v[4:5], v[86:87] op_sel:[1,1] op_sel_hi:[1,0] neg_lo:[1,0]
	v_pk_fma_f32 v[4:5], v[4:5], v[86:87], v[2:3] op_sel_hi:[0,1,1]
	v_pk_mul_f32 v[6:7], v[112:113], v[4:5] op_sel:[1,1] op_sel_hi:[1,0] neg_lo:[1,0]
	v_pk_fma_f32 v[2:3], v[112:113], v[4:5], v[6:7] op_sel_hi:[0,1,1]
	s_nop 0
	v_pk_mul_f32 v[6:7], v[4:5], v[86:87] op_sel:[1,1] op_sel_hi:[1,0] neg_lo:[1,0]
	v_pk_fma_f32 v[4:5], v[4:5], v[86:87], v[6:7] op_sel_hi:[0,1,1]
	v_pk_mul_f32 v[8:9], v[108:109], v[4:5] op_sel:[1,1] op_sel_hi:[1,0] neg_lo:[1,0]
	v_pk_fma_f32 v[6:7], v[108:109], v[4:5], v[8:9] op_sel_hi:[0,1,1]
	ds_write2_b64 v0, v[2:3], v[6:7] offset0:220 offset1:237
	v_pk_mul_f32 v[2:3], v[4:5], v[86:87] op_sel:[1,1] op_sel_hi:[1,0] neg_lo:[1,0]
	v_pk_fma_f32 v[4:5], v[4:5], v[86:87], v[2:3] op_sel_hi:[0,1,1]
	v_pk_mul_f32 v[6:7], v[116:117], v[4:5] op_sel:[1,1] op_sel_hi:[1,0] neg_lo:[1,0]
	v_pk_fma_f32 v[2:3], v[116:117], v[4:5], v[6:7] op_sel_hi:[0,1,1]
	s_nop 0
	v_pk_mul_f32 v[6:7], v[4:5], v[86:87] op_sel:[1,1] op_sel_hi:[1,0] neg_lo:[1,0]
	v_pk_fma_f32 v[4:5], v[4:5], v[86:87], v[6:7] op_sel_hi:[0,1,1]
	v_pk_mul_f32 v[6:7], v[118:119], v[4:5] op_sel:[1,1] op_sel_hi:[1,0] neg_lo:[1,0]
	v_pk_fma_f32 v[4:5], v[118:119], v[4:5], v[6:7] op_sel_hi:[0,1,1]
	ds_write2_b64 v1, v[2:3], v[4:5] offset0:126 offset1:143
	s_waitcnt lgkmcnt(0)
	s_barrier
	ds_read2_b64 v[68:71], v161 offset1:1
	ds_read2_b64 v[8:11], v162 offset1:1
	ds_read2_b64 v[72:75], v161 offset0:2 offset1:3
	ds_read2_b64 v[12:15], v162 offset0:2 offset1:3
	ds_read2_b64 v[76:79], v161 offset0:4 offset1:5
	ds_read2_b64 v[0:3], v162 offset0:4 offset1:5
	ds_read2_b64 v[80:83], v161 offset0:6 offset1:7
	ds_read2_b64 v[4:7], v162 offset0:6 offset1:7
	ds_read2_b64 v[84:87], v161 offset0:8 offset1:9
	ds_read2_b64 v[100:103], v162 offset0:8 offset1:9
	ds_read2_b64 v[88:91], v161 offset0:10 offset1:11
	ds_read2_b64 v[104:107], v162 offset0:10 offset1:11
	ds_read2_b64 v[92:95], v161 offset0:12 offset1:13
	ds_read2_b64 v[16:19], v162 offset0:12 offset1:13
	ds_read2_b64 v[96:99], v161 offset0:14 offset1:15
	ds_read2_b64 v[108:111], v162 offset0:14 offset1:15
	s_waitcnt lgkmcnt(7)
	v_pk_add_f32 v[112:113], v[68:69], v[84:85]
	v_pk_add_f32 v[68:69], v[68:69], v[84:85] neg_lo:[0,1] neg_hi:[0,1]
	v_mov_b32_e32 v114, v68
	v_mov_b32_e32 v115, v69
	v_pk_add_f32 v[68:69], v[70:71], v[86:87]
	v_pk_add_f32 v[70:71], v[70:71], v[86:87] neg_lo:[0,1] neg_hi:[0,1]
	v_pk_mul_f32 v[84:85], v[70:71], s[84:85] op_sel_hi:[1,0]
	v_pk_fma_f32 v[86:87], v[70:71], s[16:17], v[84:85] op_sel:[0,0,1] op_sel_hi:[1,0,0] neg_hi:[0,0,1]
	s_waitcnt lgkmcnt(5)
	v_pk_add_f32 v[70:71], v[72:73], v[88:89]
	v_pk_add_f32 v[72:73], v[72:73], v[88:89] neg_lo:[0,1] neg_hi:[0,1]
	v_pk_mul_f32 v[84:85], v[72:73], s[18:19] op_sel_hi:[1,0]
	v_pk_fma_f32 v[88:89], v[72:73], s[18:19], v[84:85] op_sel:[0,0,1] op_sel_hi:[1,0,0]
	v_pk_fma_f32 v[72:73], v[72:73], s[18:19], v[84:85] op_sel_hi:[1,0,0] neg_lo:[0,0,1] neg_hi:[0,0,1]
	v_pk_add_f32 v[84:85], v[74:75], v[90:91]
	v_pk_add_f32 v[74:75], v[74:75], v[90:91] neg_lo:[0,1] neg_hi:[0,1]
	v_mov_b32_e32 v89, v73
	v_pk_mul_f32 v[90:91], v[74:75], s[16:17] op_sel_hi:[1,0]
	v_pk_fma_f32 v[116:117], v[74:75], s[84:85], v[90:91] op_sel:[0,0,1] op_sel_hi:[1,0,0] neg_hi:[0,0,1]
	s_waitcnt lgkmcnt(3)
	v_pk_add_f32 v[74:75], v[76:77], v[92:93]
	v_pk_add_f32 v[76:77], v[76:77], v[92:93] neg_lo:[0,1] neg_hi:[0,1]
	v_pk_add_f32 v[90:91], v[76:77], 0 op_sel:[1,0] op_sel_hi:[0,0] neg_hi:[1,0]
	v_pk_add_f32 v[76:77], v[78:79], v[94:95]
	v_pk_add_f32 v[78:79], v[78:79], v[94:95] neg_lo:[0,1] neg_hi:[0,1]
	s_waitcnt lgkmcnt(1)
	v_pk_add_f32 v[94:95], v[82:83], v[98:99]
	v_pk_mul_f32 v[92:93], v[78:79], s[84:85] op_sel_hi:[0,1]
	v_pk_add_f32 v[82:83], v[82:83], v[98:99] neg_lo:[0,1] neg_hi:[0,1]
	v_pk_fma_f32 v[78:79], v[78:79], s[30:31], v[92:93] op_sel:[1,0,0] neg_lo:[0,0,1] neg_hi:[0,0,1]
	v_pk_add_f32 v[92:93], v[80:81], v[96:97]
	v_pk_add_f32 v[80:81], v[80:81], v[96:97] neg_lo:[0,1] neg_hi:[0,1]
	v_pk_mul_f32 v[96:97], v[82:83], s[24:25] op_sel_hi:[0,1]
	v_pk_fma_f32 v[82:83], v[82:83], s[34:35], v[96:97] op_sel:[1,0,0] neg_lo:[0,0,1] neg_hi:[0,0,1]
	v_pk_add_f32 v[96:97], v[112:113], v[74:75]
	v_pk_add_f32 v[74:75], v[112:113], v[74:75] neg_lo:[0,1] neg_hi:[0,1]
	v_mul_f32_e32 v72, 0x3f3504f3, v80
	v_pk_fma_f32 v[80:81], v[80:81], s[28:29], v[72:73] op_sel:[1,0,0] op_sel_hi:[1,1,0] neg_lo:[0,0,1] neg_hi:[0,0,1]
	v_mov_b32_e32 v112, v74
	v_mov_b32_e32 v113, v75
	v_pk_add_f32 v[72:73], v[88:89], v[80:81]
	v_pk_add_f32 v[74:75], v[68:69], v[76:77]
	v_pk_add_f32 v[68:69], v[68:69], v[76:77] neg_lo:[0,1] neg_hi:[0,1]
	v_pk_mul_f32 v[76:77], v[68:69], s[18:19] op_sel_hi:[1,0]
	v_pk_fma_f32 v[98:99], v[68:69], s[18:19], v[76:77] op_sel:[0,0,1] op_sel_hi:[1,0,0]
	v_pk_fma_f32 v[68:69], v[68:69], s[18:19], v[76:77] op_sel_hi:[1,0,0] neg_lo:[0,0,1] neg_hi:[0,0,1]
	v_pk_add_f32 v[76:77], v[70:71], v[92:93]
	v_pk_add_f32 v[70:71], v[70:71], v[92:93] neg_lo:[0,1] neg_hi:[0,1]
	v_mov_b32_e32 v99, v69
	v_pk_add_f32 v[92:93], v[70:71], 0 op_sel:[1,0] op_sel_hi:[0,0] neg_hi:[1,0]
	v_pk_add_f32 v[70:71], v[84:85], v[94:95]
	v_pk_add_f32 v[84:85], v[84:85], v[94:95] neg_lo:[0,1] neg_hi:[0,1]
	v_pk_add_f32 v[94:95], v[114:115], v[90:91]
	v_pk_add_f32 v[90:91], v[114:115], v[90:91] neg_lo:[0,1] neg_hi:[0,1]
	v_mul_f32_e32 v68, 0x3f3504f3, v84
	v_pk_fma_f32 v[84:85], v[84:85], s[28:29], v[68:69] op_sel:[1,0,0] op_sel_hi:[1,1,0] neg_lo:[0,0,1] neg_hi:[0,0,1]
; template <int R, bool INV> DEV void dft_regs(cf (&v)[R]) {
; #pragma unroll
;     for (int s = R; s >= 2; s >>= 1) {
;         const int h = s >> 1;
; #pragma unroll
;         for (int b = 0; b < R; b += s) {
; #pragma unroll
;             for (int k = 0; k < h; ++k) {
;                 const cf a = v[b + k], c = v[b + k + h];
;                 v[b + k] = a + c;
;                 const cf d = a - c;
;                 const int m = k * (32 / s);
;                 const float wr = tw_cos(m), wi = INV ? tw_sin(m) : -tw_sin(m);
;                 v[b + k + h] = cf{d.x * wr - d.y * wi, d.x * wi + d.y * wr};
;             }
;         }
;     }
; }
	v_mov_b32_e32 v118, v90
	v_mov_b32_e32 v119, v91
	v_pk_add_f32 v[90:91], v[86:87], v[78:79]
	v_pk_add_f32 v[78:79], v[86:87], v[78:79] neg_lo:[0,1] neg_hi:[0,1]
	v_pk_mul_f32 v[86:87], v[78:79], s[18:19] op_sel_hi:[1,0]
	v_pk_fma_f32 v[114:115], v[78:79], s[18:19], v[86:87] op_sel:[0,0,1] op_sel_hi:[1,0,0] neg_hi:[0,0,1]
	v_pk_add_f32 v[78:79], v[88:89], v[80:81] neg_lo:[0,1] neg_hi:[0,1]
	v_pk_add_f32 v[88:89], v[96:97], v[76:77]
	v_pk_add_f32 v[76:77], v[96:97], v[76:77] neg_lo:[0,1] neg_hi:[0,1]
	v_pk_add_f32 v[80:81], v[78:79], 0 op_sel:[1,0] op_sel_hi:[0,0] neg_hi:[1,0]
	v_mov_b32_e32 v96, v76
	v_mov_b32_e32 v97, v77
	v_pk_add_f32 v[76:77], v[74:75], v[70:71]
	v_pk_add_f32 v[70:71], v[74:75], v[70:71] neg_lo:[0,1] neg_hi:[0,1]
	v_pk_add_f32 v[78:79], v[116:117], v[82:83]
	v_pk_add_f32 v[74:75], v[70:71], 0 op_sel:[1,0] op_sel_hi:[0,0] neg_hi:[1,0]
	v_pk_add_f32 v[82:83], v[116:117], v[82:83] neg_lo:[0,1] neg_hi:[0,1]
	v_pk_add_f32 v[70:71], v[112:113], v[92:93] neg_lo:[0,1] neg_hi:[0,1]
	v_pk_add_f32 v[116:117], v[112:113], v[92:93]
	v_mul_f32_e32 v68, 0x3f3504f3, v82
	v_mov_b32_e32 v92, v70
	v_mov_b32_e32 v93, v71
	v_pk_fma_f32 v[82:83], v[82:83], s[28:29], v[68:69] op_sel:[1,0,0] op_sel_hi:[1,1,0] neg_lo:[0,0,1] neg_hi:[0,0,1]
	v_pk_add_f32 v[70:71], v[98:99], v[84:85] neg_lo:[0,1] neg_hi:[0,1]
	v_pk_add_f32 v[68:69], v[98:99], v[84:85]
	v_pk_add_f32 v[98:99], v[70:71], 0 op_sel:[1,0] op_sel_hi:[0,0] neg_hi:[1,0]
	v_pk_add_f32 v[112:113], v[94:95], v[72:73]
	v_pk_add_f32 v[70:71], v[94:95], v[72:73] neg_lo:[0,1] neg_hi:[0,1]
	v_pk_add_f32 v[122:123], v[118:119], v[80:81]
	v_pk_add_f32 v[124:125], v[114:115], v[82:83]
	v_mov_b32_e32 v120, v70
	v_mov_b32_e32 v121, v71
	v_pk_add_f32 v[72:73], v[90:91], v[78:79]
	v_pk_add_f32 v[70:71], v[90:91], v[78:79] neg_lo:[0,1] neg_hi:[0,1]
	v_pk_add_f32 v[86:87], v[88:89], v[76:77]
	v_pk_add_f32 v[78:79], v[70:71], 0 op_sel:[1,0] op_sel_hi:[0,0] neg_hi:[1,0]
	v_pk_add_f32 v[94:95], v[112:113], v[72:73]
	v_pk_add_f32 v[70:71], v[118:119], v[80:81] neg_lo:[0,1] neg_hi:[0,1]
	v_pk_add_f32 v[72:73], v[112:113], v[72:73] neg_lo:[0,1] neg_hi:[0,1]
	v_pk_add_f32 v[84:85], v[92:93], v[98:99]
	v_mov_b32_e32 v118, v70
	v_mov_b32_e32 v119, v71
	v_pk_add_f32 v[112:113], v[8:9], v[100:101]
	v_pk_add_f32 v[70:71], v[114:115], v[82:83] neg_lo:[0,1] neg_hi:[0,1]
	v_pk_add_f32 v[82:83], v[96:97], v[74:75]
	v_pk_add_f32 v[114:115], v[70:71], 0 op_sel:[1,0] op_sel_hi:[0,0] neg_hi:[1,0]
	v_pk_add_f32 v[74:75], v[96:97], v[74:75] neg_lo:[0,1] neg_hi:[0,1]
	v_pk_add_f32 v[70:71], v[88:89], v[76:77] neg_lo:[0,1] neg_hi:[0,1]
	v_pk_add_f32 v[88:89], v[116:117], v[68:69]
	v_pk_add_f32 v[68:69], v[116:117], v[68:69] neg_lo:[0,1] neg_hi:[0,1]
	v_mov_b32_e32 v76, v70
	v_mov_b32_e32 v77, v71
	v_mov_b32_e32 v70, v74
	v_mov_b32_e32 v71, v75
	v_mov_b32_e32 v74, v68
	v_mov_b32_e32 v75, v69
	v_pk_add_f32 v[80:81], v[92:93], v[98:99] neg_lo:[0,1] neg_hi:[0,1]
	v_pk_add_f32 v[8:9], v[8:9], v[100:101] neg_lo:[0,1] neg_hi:[0,1]
	v_mov_b32_e32 v68, v80
	v_mov_b32_e32 v69, v81
	v_mov_b32_e32 v80, v72
	v_mov_b32_e32 v81, v73
	v_pk_add_f32 v[90:91], v[120:121], v[78:79]
	v_pk_add_f32 v[78:79], v[120:121], v[78:79] neg_lo:[0,1] neg_hi:[0,1]
	v_mov_b32_e32 v72, v78
	v_mov_b32_e32 v73, v79
	v_pk_add_f32 v[92:93], v[122:123], v[124:125] neg_lo:[0,1] neg_hi:[0,1]
	v_pk_add_f32 v[96:97], v[122:123], v[124:125]
	v_mov_b32_e32 v78, v92
	v_mov_b32_e32 v79, v93
	v_pk_add_f32 v[98:99], v[118:119], v[114:115] neg_lo:[0,1] neg_hi:[0,1]
	v_pk_add_f32 v[92:93], v[118:119], v[114:115]
	v_mov_b32_e32 v114, v8
	v_mov_b32_e32 v115, v9
	v_pk_add_f32 v[8:9], v[10:11], v[102:103]
	v_pk_add_f32 v[10:11], v[10:11], v[102:103] neg_lo:[0,1] neg_hi:[0,1]
	v_pk_mul_f32 v[100:101], v[10:11], s[84:85] op_sel_hi:[1,0]
	v_pk_fma_f32 v[102:103], v[10:11], s[16:17], v[100:101] op_sel:[0,0,1] op_sel_hi:[1,0,0] neg_hi:[0,0,1]
	v_pk_add_f32 v[10:11], v[12:13], v[104:105]
	v_pk_add_f32 v[12:13], v[12:13], v[104:105] neg_lo:[0,1] neg_hi:[0,1]
	v_pk_mul_f32 v[100:101], v[12:13], s[18:19] op_sel_hi:[1,0]
	v_pk_fma_f32 v[104:105], v[12:13], s[18:19], v[100:101] op_sel:[0,0,1] op_sel_hi:[1,0,0] neg_hi:[0,0,1]
	v_pk_add_f32 v[12:13], v[14:15], v[106:107]
	v_pk_add_f32 v[14:15], v[14:15], v[106:107] neg_lo:[0,1] neg_hi:[0,1]
	v_pk_mul_f32 v[100:101], v[14:15], s[16:17] op_sel_hi:[1,0]
	v_pk_fma_f32 v[106:107], v[14:15], s[84:85], v[100:101] op_sel:[0,0,1] op_sel_hi:[1,0,0] neg_hi:[0,0,1]
	v_pk_add_f32 v[14:15], v[0:1], v[16:17]
	v_pk_add_f32 v[0:1], v[0:1], v[16:17] neg_lo:[0,1] neg_hi:[0,1]
	v_pk_add_f32 v[16:17], v[0:1], 0 op_sel:[1,0] op_sel_hi:[0,0] neg_hi:[1,0]
	v_pk_add_f32 v[0:1], v[2:3], v[18:19]
	v_pk_add_f32 v[2:3], v[2:3], v[18:19] neg_lo:[0,1] neg_hi:[0,1]
	v_pk_mul_f32 v[18:19], v[2:3], s[84:85] op_sel_hi:[0,1]
	v_pk_fma_f32 v[2:3], v[2:3], s[30:31], v[18:19] op_sel:[1,0,0] neg_lo:[0,0,1] neg_hi:[0,0,1]
	s_waitcnt lgkmcnt(0)
; template <int R, bool INV> DEV void dft_regs(cf (&v)[R]) {
; #pragma unroll
;     for (int s = R; s >= 2; s >>= 1) {
;         const int h = s >> 1;
; #pragma unroll
;         for (int b = 0; b < R; b += s) {
; #pragma unroll
;             for (int k = 0; k < h; ++k) {
;                 const cf a = v[b + k], c = v[b + k + h];
;                 v[b + k] = a + c;
;                 const cf d = a - c;
;                 const int m = k * (32 / s);
;                 const float wr = tw_cos(m), wi = INV ? tw_sin(m) : -tw_sin(m);
;                 v[b + k + h] = cf{d.x * wr - d.y * wi, d.x * wi + d.y * wr};
;             }
;         }
;     }
; }
	v_pk_add_f32 v[18:19], v[4:5], v[108:109]
	v_pk_add_f32 v[4:5], v[4:5], v[108:109] neg_lo:[0,1] neg_hi:[0,1]
	v_mul_f32_e32 v100, 0x3f3504f3, v4
	v_pk_fma_f32 v[4:5], v[4:5], s[28:29], v[100:101] op_sel:[1,0,0] op_sel_hi:[1,1,0] neg_lo:[0,0,1] neg_hi:[0,0,1]
	v_pk_add_f32 v[100:101], v[6:7], v[110:111]
	v_pk_add_f32 v[6:7], v[6:7], v[110:111] neg_lo:[0,1] neg_hi:[0,1]
	v_pk_mul_f32 v[108:109], v[6:7], s[24:25] op_sel_hi:[0,1]
	v_pk_fma_f32 v[6:7], v[6:7], s[34:35], v[108:109] op_sel:[1,0,0] neg_lo:[0,0,1] neg_hi:[0,0,1]
	v_pk_add_f32 v[108:109], v[112:113], v[14:15]
	v_pk_add_f32 v[14:15], v[112:113], v[14:15] neg_lo:[0,1] neg_hi:[0,1]
	v_mov_b32_e32 v112, v14
	v_mov_b32_e32 v113, v15
	v_pk_add_f32 v[14:15], v[8:9], v[0:1]
	v_pk_add_f32 v[0:1], v[8:9], v[0:1] neg_lo:[0,1] neg_hi:[0,1]
	v_pk_mul_f32 v[8:9], v[0:1], s[18:19] op_sel_hi:[1,0]
	v_pk_fma_f32 v[110:111], v[0:1], s[18:19], v[8:9] op_sel:[0,0,1] op_sel_hi:[1,0,0] neg_hi:[0,0,1]
	v_pk_add_f32 v[8:9], v[10:11], v[18:19] neg_lo:[0,1] neg_hi:[0,1]
	v_pk_add_f32 v[0:1], v[10:11], v[18:19]
	v_pk_add_f32 v[10:11], v[8:9], 0 op_sel:[1,0] op_sel_hi:[0,0] neg_hi:[1,0]
	v_pk_add_f32 v[8:9], v[12:13], v[100:101]
	v_pk_add_f32 v[12:13], v[12:13], v[100:101] neg_lo:[0,1] neg_hi:[0,1]
	v_mul_f32_e32 v18, 0x3f3504f3, v12
	v_pk_fma_f32 v[12:13], v[12:13], s[28:29], v[18:19] op_sel:[1,0,0] op_sel_hi:[1,1,0] neg_lo:[0,0,1] neg_hi:[0,0,1]
	v_pk_add_f32 v[18:19], v[114:115], v[16:17]
	v_pk_add_f32 v[16:17], v[114:115], v[16:17] neg_lo:[0,1] neg_hi:[0,1]
	v_mov_b32_e32 v114, v16
	v_mov_b32_e32 v115, v17
	v_pk_add_f32 v[16:17], v[102:103], v[2:3]
	v_pk_add_f32 v[2:3], v[102:103], v[2:3] neg_lo:[0,1] neg_hi:[0,1]
	v_pk_mul_f32 v[100:101], v[2:3], s[18:19] op_sel_hi:[1,0]
	v_pk_fma_f32 v[102:103], v[2:3], s[18:19], v[100:101] op_sel:[0,0,1] op_sel_hi:[1,0,0] neg_hi:[0,0,1]
	v_pk_add_f32 v[2:3], v[104:105], v[4:5]
	v_pk_add_f32 v[4:5], v[104:105], v[4:5] neg_lo:[0,1] neg_hi:[0,1]
	v_pk_add_f32 v[100:101], v[4:5], 0 op_sel:[1,0] op_sel_hi:[0,0] neg_hi:[1,0]
	v_pk_add_f32 v[4:5], v[106:107], v[6:7]
	v_pk_add_f32 v[6:7], v[106:107], v[6:7] neg_lo:[0,1] neg_hi:[0,1]
	v_mul_f32_e32 v104, 0x3f3504f3, v6
	v_pk_fma_f32 v[6:7], v[6:7], s[28:29], v[104:105] op_sel:[1,0,0] op_sel_hi:[1,1,0] neg_lo:[0,0,1] neg_hi:[0,0,1]
	v_pk_add_f32 v[104:105], v[108:109], v[0:1]
	v_pk_add_f32 v[0:1], v[108:109], v[0:1] neg_lo:[0,1] neg_hi:[0,1]
	v_pk_add_f32 v[166:167], v[102:103], v[6:7]
	v_pk_add_f32 v[6:7], v[102:103], v[6:7] neg_lo:[0,1] neg_hi:[0,1]
	v_mov_b32_e32 v108, v0
	v_mov_b32_e32 v109, v1
	v_pk_add_f32 v[168:169], v[6:7], 0 op_sel:[1,0] op_sel_hi:[0,0] neg_hi:[1,0]
	v_pk_add_f32 v[0:1], v[14:15], v[8:9]
	v_pk_add_f32 v[8:9], v[14:15], v[8:9] neg_lo:[0,1] neg_hi:[0,1]
	v_pk_add_f32 v[14:15], v[8:9], 0 op_sel:[1,0] op_sel_hi:[0,0] neg_hi:[1,0]
	v_pk_add_f32 v[122:123], v[104:105], v[0:1]
	v_pk_add_f32 v[8:9], v[112:113], v[10:11]
	v_pk_add_f32 v[10:11], v[112:113], v[10:11] neg_lo:[0,1] neg_hi:[0,1]
	v_pk_add_f32 v[0:1], v[104:105], v[0:1] neg_lo:[0,1] neg_hi:[0,1]
	v_mov_b32_e32 v116, v10
	v_mov_b32_e32 v117, v11
	v_pk_add_f32 v[10:11], v[110:111], v[12:13]
	v_pk_add_f32 v[12:13], v[110:111], v[12:13] neg_lo:[0,1] neg_hi:[0,1]
	v_mov_b32_e32 v106, v0
	v_mov_b32_e32 v107, v1
	v_pk_add_f32 v[110:111], v[12:13], 0 op_sel:[1,0] op_sel_hi:[0,0] neg_hi:[1,0]
	v_pk_add_f32 v[12:13], v[18:19], v[2:3]
	v_pk_add_f32 v[2:3], v[18:19], v[2:3] neg_lo:[0,1] neg_hi:[0,1]
	v_pk_add_f32 v[0:1], v[108:109], v[14:15] neg_lo:[0,1] neg_hi:[0,1]
	v_mov_b32_e32 v124, v2
	v_mov_b32_e32 v125, v3
	v_pk_add_f32 v[2:3], v[16:17], v[4:5]
	v_pk_add_f32 v[4:5], v[16:17], v[4:5] neg_lo:[0,1] neg_hi:[0,1]
	v_pk_add_f32 v[16:17], v[114:115], v[100:101] neg_lo:[0,1] neg_hi:[0,1]
	v_pk_add_f32 v[164:165], v[4:5], 0 op_sel:[1,0] op_sel_hi:[0,0] neg_hi:[1,0]
	v_pk_add_f32 v[4:5], v[114:115], v[100:101]
	v_mov_b32_e32 v100, v16
	v_mov_b32_e32 v101, v17
	v_mov_b32_e32 v18, v0
	v_mov_b32_e32 v19, v1
	v_pk_add_f32 v[0:1], v[8:9], v[10:11] neg_lo:[0,1] neg_hi:[0,1]
	v_pk_add_f32 v[126:127], v[12:13], v[2:3]
	v_pk_add_f32 v[112:113], v[116:117], v[110:111]
	v_mov_b32_e32 v104, v0
	v_mov_b32_e32 v105, v1
	v_pk_add_f32 v[114:115], v[108:109], v[14:15]
	v_pk_add_f32 v[0:1], v[116:117], v[110:111] neg_lo:[0,1] neg_hi:[0,1]
	v_pk_add_f32 v[116:117], v[100:101], v[168:169]
	v_pk_add_f32 v[120:121], v[8:9], v[10:11]
	v_mov_b32_e32 v16, v0
	v_mov_b32_e32 v17, v1
	v_pk_add_f32 v[118:119], v[124:125], v[164:165]
	v_pk_add_f32 v[0:1], v[12:13], v[2:3] neg_lo:[0,1] neg_hi:[0,1]
	s_mov_b32 s28, s95
	v_mov_b32_e32 v110, v0
	v_mov_b32_e32 v111, v1
	s_mov_b32 s29, s94
	v_pk_add_f32 v[0:1], v[124:125], v[164:165] neg_lo:[0,1] neg_hi:[0,1]
	v_pk_add_f32 v[124:125], v[4:5], v[166:167]
	v_mov_b32_e32 v102, v0
	v_mov_b32_e32 v103, v1
	v_pk_add_f32 v[0:1], v[4:5], v[166:167] neg_lo:[0,1] neg_hi:[0,1]
	v_mov_b32_e32 v166, v98
	v_mov_b32_e32 v167, v99
	v_mov_b32_e32 v108, v0
	v_mov_b32_e32 v109, v1
	v_pk_add_f32 v[0:1], v[100:101], v[168:169] neg_lo:[0,1] neg_hi:[0,1]
	v_mov_b32_e32 v100, v0
	v_mov_b32_e32 v101, v1
	s_nop 0
	s_waitcnt vmcnt(0)
; #define U2F(x) __uint_as_float(x)
; DEV cf kunpack(unsigned w) { return cf{U2F(w << 16), U2F(w & 0xffff0000u)}; }
; DEV void fft_midx2(LAS cf* buf0, LAS cf* buf1, const unsigned* Kp, int blk) {
;     ...
;     for (int j = 0; j < 4; ++j) kw[j] = *(const u32x4*)(Kp + base + 4 * j);
; #pragma unroll
;     for (int p = 0; p < 16; ++p) { const cf k = kunpack(kw[p >> 2][p & 3]); w[p] = cmul(v[BR16[p]], k); x[p] = cmul(u[BR16[p]], k); }
	v_lshlrev_b32_e32 v98, 16, v182
	v_and_b32_e32 v99, 0xffff0000, v182
	v_lshlrev_b32_e32 v12, 16, v183
	v_and_b32_e32 v13, 0xffff0000, v183
	v_pk_mul_f32 v[168:169], v[86:87], v[98:99] op_sel:[1,1] op_sel_hi:[1,0] neg_lo:[1,0]
	v_pk_fma_f32 v[164:165], v[86:87], v[98:99], v[168:169] op_sel_hi:[0,1,1]
	s_nop 0
	v_pk_mul_f32 v[168:169], v[122:123], v[98:99] op_sel:[1,1] op_sel_hi:[1,0] neg_lo:[1,0]
	v_pk_fma_f32 v[86:87], v[122:123], v[98:99], v[168:169] op_sel_hi:[0,1,1]
	v_pk_mul_f32 v[98:99], v[94:95], v[12:13] op_sel:[1,1] op_sel_hi:[1,0] neg_lo:[1,0]
	v_pk_fma_f32 v[94:95], v[94:95], v[12:13], v[98:99] op_sel_hi:[0,1,1]
	s_nop 0
	v_pk_mul_f32 v[98:99], v[126:127], v[12:13] op_sel:[1,1] op_sel_hi:[1,0] neg_lo:[1,0]
	v_pk_fma_f32 v[12:13], v[126:127], v[12:13], v[98:99] op_sel_hi:[0,1,1]
	s_nop 0
	v_lshlrev_b32_e32 v98, 16, v184
	v_and_b32_e32 v99, 0xffff0000, v184
	v_lshlrev_b32_e32 v14, 16, v185
	v_and_b32_e32 v15, 0xffff0000, v185
	v_pk_mul_f32 v[126:127], v[88:89], v[98:99] op_sel:[1,1] op_sel_hi:[1,0] neg_lo:[1,0]
	v_pk_fma_f32 v[122:123], v[88:89], v[98:99], v[126:127] op_sel_hi:[0,1,1]
	s_nop 0
	v_pk_mul_f32 v[126:127], v[120:121], v[98:99] op_sel:[1,1] op_sel_hi:[1,0] neg_lo:[1,0]
	v_pk_fma_f32 v[88:89], v[120:121], v[98:99], v[126:127] op_sel_hi:[0,1,1]
	v_pk_mul_f32 v[98:99], v[96:97], v[14:15] op_sel:[1,1] op_sel_hi:[1,0] neg_lo:[1,0]
	v_pk_fma_f32 v[96:97], v[96:97], v[14:15], v[98:99] op_sel_hi:[0,1,1]
	s_nop 0
	v_pk_mul_f32 v[98:99], v[124:125], v[14:15] op_sel:[1,1] op_sel_hi:[1,0] neg_lo:[1,0]
	v_pk_fma_f32 v[14:15], v[124:125], v[14:15], v[98:99] op_sel_hi:[0,1,1]
	s_nop 0
	v_lshlrev_b32_e32 v98, 16, v178
	v_and_b32_e32 v99, 0xffff0000, v178
	v_lshlrev_b32_e32 v8, 16, v179
	v_and_b32_e32 v9, 0xffff0000, v179
	v_pk_mul_f32 v[124:125], v[82:83], v[98:99] op_sel:[1,1] op_sel_hi:[1,0] neg_lo:[1,0]
	v_pk_fma_f32 v[120:121], v[82:83], v[98:99], v[124:125] op_sel_hi:[0,1,1]
	s_nop 0
	v_pk_mul_f32 v[124:125], v[114:115], v[98:99] op_sel:[1,1] op_sel_hi:[1,0] neg_lo:[1,0]
	v_pk_fma_f32 v[82:83], v[114:115], v[98:99], v[124:125] op_sel_hi:[0,1,1]
	v_pk_mul_f32 v[98:99], v[90:91], v[8:9] op_sel:[1,1] op_sel_hi:[1,0] neg_lo:[1,0]
	v_pk_fma_f32 v[90:91], v[90:91], v[8:9], v[98:99] op_sel_hi:[0,1,1]
	s_nop 0
	v_pk_mul_f32 v[98:99], v[118:119], v[8:9] op_sel:[1,1] op_sel_hi:[1,0] neg_lo:[1,0]
	v_pk_fma_f32 v[8:9], v[118:119], v[8:9], v[98:99] op_sel_hi:[0,1,1]
	s_nop 0
	v_lshlrev_b32_e32 v98, 16, v180
	v_and_b32_e32 v99, 0xffff0000, v180
	v_lshlrev_b32_e32 v10, 16, v181
	v_and_b32_e32 v11, 0xffff0000, v181
	v_pk_mul_f32 v[118:119], v[84:85], v[98:99] op_sel:[1,1] op_sel_hi:[1,0] neg_lo:[1,0]
	v_pk_fma_f32 v[114:115], v[84:85], v[98:99], v[118:119] op_sel_hi:[0,1,1]
	s_nop 0
	v_pk_mul_f32 v[118:119], v[112:113], v[98:99] op_sel:[1,1] op_sel_hi:[1,0] neg_lo:[1,0]
	v_pk_fma_f32 v[84:85], v[112:113], v[98:99], v[118:119] op_sel_hi:[0,1,1]
	v_pk_mul_f32 v[98:99], v[92:93], v[10:11] op_sel:[1,1] op_sel_hi:[1,0] neg_lo:[1,0]
	v_pk_fma_f32 v[92:93], v[92:93], v[10:11], v[98:99] op_sel_hi:[0,1,1]
	s_nop 0
	v_pk_mul_f32 v[98:99], v[116:117], v[10:11] op_sel:[1,1] op_sel_hi:[1,0] neg_lo:[1,0]
	v_pk_fma_f32 v[10:11], v[116:117], v[10:11], v[98:99] op_sel_hi:[0,1,1]
	s_nop 0
	v_lshlrev_b32_e32 v98, 16, v174
	v_and_b32_e32 v99, 0xffff0000, v174
	v_pk_mul_f32 v[112:113], v[76:77], v[98:99] op_sel:[1,1] op_sel_hi:[1,0] neg_lo:[1,0]
	v_pk_fma_f32 v[76:77], v[76:77], v[98:99], v[112:113] op_sel_hi:[0,1,1]
	v_lshlrev_b32_e32 v4, 16, v175
	v_pk_mul_f32 v[112:113], v[106:107], v[98:99] op_sel:[1,1] op_sel_hi:[1,0] neg_lo:[1,0]
	v_pk_fma_f32 v[98:99], v[106:107], v[98:99], v[112:113] op_sel_hi:[0,1,1]
	v_and_b32_e32 v5, 0xffff0000, v175
	v_pk_mul_f32 v[106:107], v[80:81], v[4:5] op_sel:[1,1] op_sel_hi:[1,0] neg_lo:[1,0]
	v_pk_fma_f32 v[80:81], v[80:81], v[4:5], v[106:107] op_sel_hi:[0,1,1]
	s_nop 0
	v_pk_mul_f32 v[112:113], v[110:111], v[4:5] op_sel:[1,1] op_sel_hi:[1,0] neg_lo:[1,0]
	v_pk_fma_f32 v[106:107], v[110:111], v[4:5], v[112:113] op_sel_hi:[0,1,1]
	v_lshlrev_b32_e32 v4, 16, v176
	v_and_b32_e32 v5, 0xffff0000, v176
	v_pk_mul_f32 v[110:111], v[74:75], v[4:5] op_sel:[1,1] op_sel_hi:[1,0] neg_lo:[1,0]
	v_pk_fma_f32 v[74:75], v[74:75], v[4:5], v[110:111] op_sel_hi:[0,1,1]
	s_nop 0
	v_pk_mul_f32 v[110:111], v[104:105], v[4:5] op_sel:[1,1] op_sel_hi:[1,0] neg_lo:[1,0]
	v_pk_fma_f32 v[104:105], v[104:105], v[4:5], v[110:111] op_sel_hi:[0,1,1]
	v_lshlrev_b32_e32 v4, 16, v177
	v_and_b32_e32 v5, 0xffff0000, v177
	v_pk_mul_f32 v[110:111], v[78:79], v[4:5] op_sel:[1,1] op_sel_hi:[1,0] neg_lo:[1,0]
	v_pk_fma_f32 v[6:7], v[78:79], v[4:5], v[110:111] op_sel_hi:[0,1,1]
	v_pk_mul_f32 v[78:79], v[108:109], v[4:5] op_sel:[1,1] op_sel_hi:[1,0] neg_lo:[1,0]
	v_pk_fma_f32 v[108:109], v[108:109], v[4:5], v[78:79] op_sel_hi:[0,1,1]
	v_lshlrev_b32_e32 v4, 16, v170
	v_and_b32_e32 v5, 0xffff0000, v170
	v_lshlrev_b32_e32 v0, 16, v171
	v_and_b32_e32 v1, 0xffff0000, v171
	v_pk_mul_f32 v[78:79], v[70:71], v[4:5] op_sel:[1,1] op_sel_hi:[1,0] neg_lo:[1,0]
	v_pk_fma_f32 v[70:71], v[70:71], v[4:5], v[78:79] op_sel_hi:[0,1,1]
	s_nop 0
	v_pk_mul_f32 v[78:79], v[18:19], v[4:5] op_sel:[1,1] op_sel_hi:[1,0] neg_lo:[1,0]
	v_pk_fma_f32 v[110:111], v[18:19], v[4:5], v[78:79] op_sel_hi:[0,1,1]
	v_pk_mul_f32 v[18:19], v[72:73], v[0:1] op_sel:[1,1] op_sel_hi:[1,0] neg_lo:[1,0]
	v_pk_fma_f32 v[4:5], v[72:73], v[0:1], v[18:19] op_sel_hi:[0,1,1]
	s_nop 0
	v_pk_mul_f32 v[18:19], v[102:103], v[0:1] op_sel:[1,1] op_sel_hi:[1,0] neg_lo:[1,0]
	v_pk_fma_f32 v[102:103], v[102:103], v[0:1], v[18:19] op_sel_hi:[0,1,1]
	v_lshlrev_b32_e32 v0, 16, v172
	v_and_b32_e32 v1, 0xffff0000, v172
; DEV cf kunpack(unsigned w) { return cf{U2F(w << 16), U2F(w & 0xffff0000u)}; }
; template <int R, bool INV> DEV void dft_regs(cf (&v)[R]) {
; #pragma unroll
;     for (int s = R; s >= 2; s >>= 1) {
;         const int h = s >> 1;
; #pragma unroll
;         for (int b = 0; b < R; b += s) {
; #pragma unroll
;             for (int k = 0; k < h; ++k) {
;                 const cf a = v[b + k], c = v[b + k + h];
;                 v[b + k] = a + c;
;                 const cf d = a - c;
;                 const int m = k * (32 / s);
;                 const float wr = tw_cos(m), wi = INV ? tw_sin(m) : -tw_sin(m);
;                 v[b + k + h] = cf{d.x * wr - d.y * wi, d.x * wi + d.y * wr};
;             }
;         }
;     }
; }
; DEV void fft_midx2(LAS cf* buf0, LAS cf* buf1, const unsigned* Kp, int blk) {
;     ...
; #pragma unroll
;     for (int p = 0; p < 16; ++p) { const cf k = kunpack(kw[p >> 2][p & 3]); w[p] = cmul(v[BR16[p]], k); x[p] = cmul(u[BR16[p]], k); }
;     dft_regs<16, true>(w); dft_regs<16, true>(x);
	v_pk_mul_f32 v[72:73], v[68:69], v[0:1] op_sel:[1,1] op_sel_hi:[1,0] neg_lo:[1,0]
	v_pk_fma_f32 v[18:19], v[68:69], v[0:1], v[72:73] op_sel_hi:[0,1,1]
	v_pk_mul_f32 v[68:69], v[16:17], v[0:1] op_sel:[1,1] op_sel_hi:[1,0] neg_lo:[1,0]
	v_pk_fma_f32 v[112:113], v[16:17], v[0:1], v[68:69] op_sel_hi:[0,1,1]
	v_lshlrev_b32_e32 v0, 16, v173
	v_and_b32_e32 v1, 0xffff0000, v173
	v_pk_mul_f32 v[16:17], v[166:167], v[0:1] op_sel:[1,1] op_sel_hi:[1,0] neg_lo:[1,0]
	v_pk_fma_f32 v[2:3], v[166:167], v[0:1], v[16:17] op_sel_hi:[0,1,1]
	s_nop 0
	v_pk_mul_f32 v[16:17], v[100:101], v[0:1] op_sel:[1,1] op_sel_hi:[1,0] neg_lo:[1,0]
	v_pk_fma_f32 v[100:101], v[100:101], v[0:1], v[16:17] op_sel_hi:[0,1,1]
	v_pk_add_f32 v[0:1], v[164:165], v[76:77]
	v_pk_add_f32 v[16:17], v[164:165], v[76:77] neg_lo:[0,1] neg_hi:[0,1]
	v_mov_b32_e32 v72, v16
	v_mov_b32_e32 v73, v17
	v_pk_add_f32 v[68:69], v[94:95], v[80:81] neg_lo:[0,1] neg_hi:[0,1]
	v_pk_mul_f32 v[76:77], v[68:69], s[84:85] op_sel_hi:[1,0]
	v_pk_add_f32 v[16:17], v[94:95], v[80:81]
	v_pk_fma_f32 v[78:79], v[68:69], s[16:17], v[76:77] op_sel:[0,0,1] op_sel_hi:[1,0,0] neg_lo:[0,0,1]
	v_pk_add_f32 v[68:69], v[122:123], v[74:75]
	v_pk_add_f32 v[74:75], v[122:123], v[74:75] neg_lo:[0,1] neg_hi:[0,1]
	v_pk_mul_f32 v[76:77], v[74:75], s[18:19] op_sel_hi:[1,0]
	v_pk_fma_f32 v[80:81], v[74:75], s[18:19], v[76:77] op_sel:[0,0,1] op_sel_hi:[1,0,0] neg_lo:[0,0,1]
	v_pk_add_f32 v[74:75], v[96:97], v[6:7]
	v_pk_add_f32 v[6:7], v[96:97], v[6:7] neg_lo:[0,1] neg_hi:[0,1]
	v_pk_mul_f32 v[76:77], v[6:7], s[16:17] op_sel_hi:[1,0]
	v_pk_fma_f32 v[94:95], v[6:7], s[84:85], v[76:77] op_sel:[0,0,1] op_sel_hi:[1,0,0] neg_lo:[0,0,1]
	v_pk_add_f32 v[6:7], v[120:121], v[70:71]
	v_pk_add_f32 v[70:71], v[120:121], v[70:71] neg_lo:[0,1] neg_hi:[0,1]
	v_pk_add_f32 v[76:77], v[70:71], 0 op_sel:[1,0] op_sel_hi:[0,0] neg_lo:[1,0]
	v_pk_add_f32 v[70:71], v[90:91], v[4:5]
	v_pk_add_f32 v[4:5], v[90:91], v[4:5] neg_lo:[0,1] neg_hi:[0,1]
	v_pk_mul_f32 v[90:91], v[4:5], s[24:25] op_sel:[1,0]
	v_pk_fma_f32 v[4:5], v[4:5], s[0:1], v[90:91] op_sel_hi:[0,1,1] neg_lo:[0,0,1] neg_hi:[0,0,1]
	v_pk_add_f32 v[90:91], v[114:115], v[18:19]
	v_pk_add_f32 v[18:19], v[114:115], v[18:19] neg_lo:[0,1] neg_hi:[0,1]
	v_mul_f32_e32 v96, 0x3f3504f3, v19
	v_pk_fma_f32 v[18:19], v[18:19], s[96:97], v[96:97] op_sel_hi:[0,1,0] neg_lo:[0,0,1] neg_hi:[0,0,1]
	v_pk_add_f32 v[96:97], v[92:93], v[2:3]
	v_pk_add_f32 v[2:3], v[92:93], v[2:3] neg_lo:[0,1] neg_hi:[0,1]
	v_pk_mul_f32 v[92:93], v[2:3], s[84:85] op_sel:[1,0]
	v_pk_fma_f32 v[2:3], v[2:3], s[88:89], v[92:93] op_sel_hi:[0,1,1] neg_lo:[0,0,1] neg_hi:[0,0,1]
	v_pk_add_f32 v[92:93], v[0:1], v[6:7]
	v_pk_add_f32 v[0:1], v[0:1], v[6:7] neg_lo:[0,1] neg_hi:[0,1]
	v_mov_b32_e32 v114, v0
	v_mov_b32_e32 v115, v1
	v_pk_add_f32 v[6:7], v[16:17], v[70:71] neg_lo:[0,1] neg_hi:[0,1]
	v_pk_add_f32 v[0:1], v[16:17], v[70:71]
	v_pk_mul_f32 v[16:17], v[6:7], s[18:19] op_sel_hi:[1,0]
	v_pk_fma_f32 v[70:71], v[6:7], s[18:19], v[16:17] op_sel:[0,0,1] op_sel_hi:[1,0,0] neg_lo:[0,0,1]
	v_pk_add_f32 v[16:17], v[68:69], v[90:91] neg_lo:[0,1] neg_hi:[0,1]
	v_pk_add_f32 v[6:7], v[68:69], v[90:91]
	v_pk_add_f32 v[68:69], v[16:17], 0 op_sel:[1,0] op_sel_hi:[0,0] neg_lo:[1,0]
	v_pk_add_f32 v[16:17], v[74:75], v[96:97]
	v_pk_add_f32 v[74:75], v[74:75], v[96:97] neg_lo:[0,1] neg_hi:[0,1]
	v_mul_f32_e32 v90, 0x3f3504f3, v75
	v_pk_fma_f32 v[74:75], v[74:75], s[96:97], v[90:91] op_sel_hi:[0,1,0] neg_lo:[0,0,1] neg_hi:[0,0,1]
	v_pk_add_f32 v[90:91], v[72:73], v[76:77]
	v_pk_add_f32 v[72:73], v[72:73], v[76:77] neg_lo:[0,1] neg_hi:[0,1]
	v_mov_b32_e32 v96, v72
	v_mov_b32_e32 v97, v73
	v_pk_add_f32 v[72:73], v[78:79], v[4:5]
	v_pk_add_f32 v[4:5], v[78:79], v[4:5] neg_lo:[0,1] neg_hi:[0,1]
	v_pk_mul_f32 v[76:77], v[4:5], s[18:19] op_sel_hi:[1,0]
	v_pk_fma_f32 v[78:79], v[4:5], s[18:19], v[76:77] op_sel:[0,0,1] op_sel_hi:[1,0,0] neg_lo:[0,0,1]
	v_pk_add_f32 v[4:5], v[80:81], v[18:19]
	v_pk_add_f32 v[18:19], v[80:81], v[18:19] neg_lo:[0,1] neg_hi:[0,1]
	v_pk_add_f32 v[116:117], v[90:91], v[4:5]
	v_pk_add_f32 v[76:77], v[18:19], 0 op_sel:[1,0] op_sel_hi:[0,0] neg_lo:[1,0]
	v_pk_add_f32 v[4:5], v[90:91], v[4:5] neg_lo:[0,1] neg_hi:[0,1]
	v_pk_add_f32 v[18:19], v[94:95], v[2:3]
	v_pk_add_f32 v[2:3], v[94:95], v[2:3] neg_lo:[0,1] neg_hi:[0,1]
	v_pk_add_f32 v[118:119], v[72:73], v[18:19]
	v_mul_f32_e32 v80, 0x3f3504f3, v3
	v_pk_fma_f32 v[2:3], v[2:3], s[96:97], v[80:81] op_sel_hi:[0,1,0] neg_lo:[0,0,1] neg_hi:[0,0,1]
	v_pk_add_f32 v[80:81], v[92:93], v[6:7]
	v_pk_add_f32 v[6:7], v[92:93], v[6:7] neg_lo:[0,1] neg_hi:[0,1]
	v_pk_add_f32 v[122:123], v[78:79], v[2:3]
	v_pk_add_f32 v[2:3], v[78:79], v[2:3] neg_lo:[0,1] neg_hi:[0,1]
	v_mov_b32_e32 v94, v6
	v_mov_b32_e32 v95, v7
	v_pk_add_f32 v[78:79], v[2:3], 0 op_sel:[1,0] op_sel_hi:[0,0] neg_lo:[1,0]
	v_pk_add_f32 v[6:7], v[0:1], v[16:17]
	v_pk_add_f32 v[0:1], v[0:1], v[16:17] neg_lo:[0,1] neg_hi:[0,1]
	v_pk_add_f32 v[16:17], v[0:1], 0 op_sel:[1,0] op_sel_hi:[0,0] neg_lo:[1,0]
	v_pk_add_f32 v[120:121], v[96:97], v[76:77]
	v_pk_add_f32 v[0:1], v[114:115], v[68:69]
	v_pk_add_f32 v[68:69], v[114:115], v[68:69] neg_lo:[0,1] neg_hi:[0,1]
	v_pk_add_f32 v[2:3], v[80:81], v[6:7] neg_lo:[0,1] neg_hi:[0,1]
	v_mov_b32_e32 v114, v68
	v_mov_b32_e32 v115, v69
	v_pk_add_f32 v[92:93], v[70:71], v[74:75]
	v_pk_add_f32 v[68:69], v[70:71], v[74:75] neg_lo:[0,1] neg_hi:[0,1]
	v_pk_add_f32 v[124:125], v[80:81], v[6:7]
	v_pk_add_f32 v[74:75], v[68:69], 0 op_sel:[1,0] op_sel_hi:[0,0] neg_lo:[1,0]
	v_pk_add_f32 v[80:81], v[94:95], v[16:17]
	v_mov_b32_e32 v90, v4
	v_mov_b32_e32 v91, v5
	v_pk_add_f32 v[4:5], v[72:73], v[18:19] neg_lo:[0,1] neg_hi:[0,1]
; template <int R, bool INV> DEV void dft_regs(cf (&v)[R]) {
; #pragma unroll
;     for (int s = R; s >= 2; s >>= 1) {
;         const int h = s >> 1;
; #pragma unroll
;         for (int b = 0; b < R; b += s) {
; #pragma unroll
;             for (int k = 0; k < h; ++k) {
;                 const cf a = v[b + k], c = v[b + k + h];
;                 v[b + k] = a + c;
;                 const cf d = a - c;
;                 const int m = k * (32 / s);
;                 const float wr = tw_cos(m), wi = INV ? tw_sin(m) : -tw_sin(m);
;                 v[b + k + h] = cf{d.x * wr - d.y * wi, d.x * wi + d.y * wr};
;             }
;         }
;     }
; }
; DEV void fft_midx2(LAS cf* buf0, LAS cf* buf1, const unsigned* Kp, int blk) {
;     ...
;     dft_regs<16, true>(w); dft_regs<16, true>(x);
	v_pk_add_f32 v[72:73], v[4:5], 0 op_sel:[1,0] op_sel_hi:[0,0] neg_lo:[1,0]
	v_pk_add_f32 v[4:5], v[96:97], v[76:77] neg_lo:[0,1] neg_hi:[0,1]
	v_pk_add_f32 v[126:127], v[90:91], v[72:73]
	v_pk_add_f32 v[72:73], v[90:91], v[72:73] neg_lo:[0,1] neg_hi:[0,1]
	v_mov_b32_e32 v96, v4
	v_mov_b32_e32 v97, v5
	v_pk_add_f32 v[90:91], v[120:121], v[122:123]
	v_pk_add_f32 v[164:165], v[96:97], v[78:79]
	v_mov_b32_e32 v18, v2
	v_mov_b32_e32 v19, v3
	v_mov_b32_e32 v68, v2
	v_mov_b32_e32 v69, v3
	v_pk_add_f32 v[4:5], v[94:95], v[16:17] neg_lo:[0,1] neg_hi:[0,1]
	v_pk_add_f32 v[94:95], v[0:1], v[92:93]
	v_pk_add_f32 v[0:1], v[0:1], v[92:93] neg_lo:[0,1] neg_hi:[0,1]
	v_mov_b32_e32 v2, v4
	v_mov_b32_e32 v3, v5
	v_pk_add_f32 v[92:93], v[114:115], v[74:75]
	v_mov_b32_e32 v16, v0
	v_mov_b32_e32 v17, v1
	v_mov_b32_e32 v70, v0
	v_mov_b32_e32 v71, v1
	v_pk_add_f32 v[6:7], v[114:115], v[74:75] neg_lo:[0,1] neg_hi:[0,1]
	v_pk_add_f32 v[114:115], v[116:117], v[118:119]
	v_pk_add_f32 v[78:79], v[96:97], v[78:79] neg_lo:[0,1] neg_hi:[0,1]
	v_mov_b32_e32 v0, v6
	v_mov_b32_e32 v1, v7
	v_pk_add_f32 v[74:75], v[116:117], v[118:119] neg_lo:[0,1] neg_hi:[0,1]
	v_mov_b32_e32 v116, v74
	v_mov_b32_e32 v117, v75
	v_mov_b32_e32 v118, v74
	v_mov_b32_e32 v119, v75
	v_mov_b32_e32 v19, v69
	v_mov_b32_e32 v74, v72
	v_mov_b32_e32 v75, v73
	v_mov_b32_e32 v76, v72
	v_mov_b32_e32 v77, v73
	v_pk_add_f32 v[72:73], v[120:121], v[122:123] neg_lo:[0,1] neg_hi:[0,1]
	v_mov_b32_e32 v117, v119
	v_mov_b32_e32 v17, v71
	v_mov_b32_e32 v122, v72
	v_mov_b32_e32 v123, v73
	v_mov_b32_e32 v120, v72
	v_mov_b32_e32 v121, v73
	v_mov_b32_e32 v72, v78
	v_mov_b32_e32 v73, v79
	v_pk_add_f32 v[96:97], v[86:87], v[98:99]
	v_pk_add_f32 v[86:87], v[86:87], v[98:99] neg_lo:[0,1] neg_hi:[0,1]
	v_mov_b32_e32 v123, v121
	v_mov_b32_e32 v166, v86
	v_mov_b32_e32 v167, v87
	v_pk_add_f32 v[86:87], v[12:13], v[106:107]
	v_pk_add_f32 v[12:13], v[12:13], v[106:107] neg_lo:[0,1] neg_hi:[0,1]
	v_mov_b32_e32 v75, v77
	v_pk_mul_f32 v[98:99], v[12:13], s[84:85] op_sel_hi:[1,0]
	v_pk_fma_f32 v[106:107], v[12:13], s[16:17], v[98:99] op_sel:[0,0,1] op_sel_hi:[1,0,0] neg_lo:[0,0,1]
	v_pk_add_f32 v[12:13], v[88:89], v[104:105]
	v_pk_add_f32 v[88:89], v[88:89], v[104:105] neg_lo:[0,1] neg_hi:[0,1]
	v_pk_mul_f32 v[98:99], v[88:89], s[18:19] op_sel_hi:[1,0]
	v_pk_fma_f32 v[104:105], v[88:89], s[18:19], v[98:99] op_sel:[0,0,1] op_sel_hi:[1,0,0] neg_lo:[0,0,1]
	v_pk_add_f32 v[88:89], v[14:15], v[108:109]
	v_pk_add_f32 v[14:15], v[14:15], v[108:109] neg_lo:[0,1] neg_hi:[0,1]
	v_pk_mul_f32 v[98:99], v[14:15], s[16:17] op_sel_hi:[1,0]
	v_pk_fma_f32 v[108:109], v[14:15], s[84:85], v[98:99] op_sel:[0,0,1] op_sel_hi:[1,0,0] neg_lo:[0,0,1]
	v_pk_add_f32 v[14:15], v[82:83], v[110:111]
	v_pk_add_f32 v[82:83], v[82:83], v[110:111] neg_lo:[0,1] neg_hi:[0,1]
	v_pk_add_f32 v[110:111], v[10:11], v[100:101]
	v_pk_add_f32 v[10:11], v[10:11], v[100:101] neg_lo:[0,1] neg_hi:[0,1]
	v_pk_add_f32 v[98:99], v[82:83], 0 op_sel:[1,0] op_sel_hi:[0,0] neg_lo:[1,0]
	v_pk_mul_f32 v[100:101], v[10:11], s[84:85] op_sel:[1,0]
	v_pk_add_f32 v[82:83], v[8:9], v[102:103]
	v_pk_add_f32 v[8:9], v[8:9], v[102:103] neg_lo:[0,1] neg_hi:[0,1]
	v_pk_fma_f32 v[10:11], v[10:11], s[88:89], v[100:101] op_sel_hi:[0,1,1] neg_lo:[0,0,1] neg_hi:[0,0,1]
	v_pk_add_f32 v[100:101], v[96:97], v[14:15]
	v_pk_add_f32 v[14:15], v[96:97], v[14:15] neg_lo:[0,1] neg_hi:[0,1]
	v_pk_mul_f32 v[102:103], v[8:9], s[24:25] op_sel:[1,0]
	v_pk_fma_f32 v[8:9], v[8:9], s[0:1], v[102:103] op_sel_hi:[0,1,1] neg_lo:[0,0,1] neg_hi:[0,0,1]
	v_pk_add_f32 v[102:103], v[84:85], v[112:113]
	v_pk_add_f32 v[84:85], v[84:85], v[112:113] neg_lo:[0,1] neg_hi:[0,1]
	v_mov_b32_e32 v112, v14
	v_mov_b32_e32 v113, v15
	v_mul_f32_e32 v4, 0x3f3504f3, v85
	v_pk_add_f32 v[14:15], v[86:87], v[82:83]
	v_pk_add_f32 v[82:83], v[86:87], v[82:83] neg_lo:[0,1] neg_hi:[0,1]
	v_pk_fma_f32 v[84:85], v[84:85], s[96:97], v[4:5] op_sel_hi:[0,1,0] neg_lo:[0,0,1] neg_hi:[0,0,1]
	v_pk_mul_f32 v[86:87], v[82:83], s[18:19] op_sel_hi:[1,0]
	v_pk_fma_f32 v[96:97], v[82:83], s[18:19], v[86:87] op_sel:[0,0,1] op_sel_hi:[1,0,0] neg_lo:[0,0,1]
	v_pk_add_f32 v[82:83], v[12:13], v[102:103]
	v_pk_add_f32 v[12:13], v[12:13], v[102:103] neg_lo:[0,1] neg_hi:[0,1]
	v_pk_add_f32 v[102:103], v[166:167], v[98:99]
	v_pk_add_f32 v[86:87], v[12:13], 0 op_sel:[1,0] op_sel_hi:[0,0] neg_lo:[1,0]
	v_pk_add_f32 v[98:99], v[166:167], v[98:99] neg_lo:[0,1] neg_hi:[0,1]
	v_pk_add_f32 v[12:13], v[88:89], v[110:111]
	v_pk_add_f32 v[88:89], v[88:89], v[110:111] neg_lo:[0,1] neg_hi:[0,1]
	v_mul_f32_e32 v4, 0x3f3504f3, v89
	v_mov_b32_e32 v166, v98
	v_mov_b32_e32 v167, v99
	v_pk_fma_f32 v[88:89], v[88:89], s[96:97], v[4:5] op_sel_hi:[0,1,0] neg_lo:[0,0,1] neg_hi:[0,0,1]
	v_pk_add_f32 v[98:99], v[106:107], v[8:9]
	v_pk_add_f32 v[8:9], v[106:107], v[8:9] neg_lo:[0,1] neg_hi:[0,1]
	v_pk_mul_f32 v[106:107], v[8:9], s[18:19] op_sel_hi:[1,0]
	v_pk_fma_f32 v[110:111], v[8:9], s[18:19], v[106:107] op_sel:[0,0,1] op_sel_hi:[1,0,0] neg_lo:[0,0,1]
	v_pk_add_f32 v[106:107], v[100:101], v[82:83]
	v_pk_add_f32 v[8:9], v[104:105], v[84:85]
	v_pk_add_f32 v[84:85], v[104:105], v[84:85] neg_lo:[0,1] neg_hi:[0,1]
	v_pk_add_f32 v[82:83], v[100:101], v[82:83] neg_lo:[0,1] neg_hi:[0,1]
	v_pk_add_f32 v[104:105], v[84:85], 0 op_sel:[1,0] op_sel_hi:[0,0] neg_lo:[1,0]
	v_pk_add_f32 v[84:85], v[108:109], v[10:11]
	v_pk_add_f32 v[10:11], v[108:109], v[10:11] neg_lo:[0,1] neg_hi:[0,1]
	v_mov_b32_e32 v108, v82
	v_mov_b32_e32 v109, v83
	v_mul_f32_e32 v4, 0x3f3504f3, v11
	v_pk_add_f32 v[82:83], v[14:15], v[12:13]
	v_pk_add_f32 v[12:13], v[14:15], v[12:13] neg_lo:[0,1] neg_hi:[0,1]
; #define LAS __attribute__((address_space(3)))
; #define SINCOSPI(x, s, c) do { const float hx_ = 0.5f * (x); *(s) = __builtin_amdgcn_sinf(hx_); *(c) = __builtin_amdgcn_cosf(hx_); } while (0)
; #define OPAQUE_I(x) asm volatile("" : "+v"(x))
; DEV void fft_midx2(LAS cf* buf0, LAS cf* buf1, const unsigned* Kp, int blk) {
;     ...
;     dft_regs<16, true>(w); dft_regs<16, true>(x);
; #pragma unroll
;     for (int q = 0; q < 16; ++q) { p0[q] = w[BR16[q]]; p1[q] = x[BR16[q]]; }
; }
; DEV void fft_i2(LAS cf* buf, int t8) {
;     OPAQUE_I(t8);
;     LAS cf* pb = buf + (t8 >> 4) * 544 + (t8 & 15);
;     float sn, cs; SINCOSPI(-(float)(t8 & 15) * (2.0f / 512.0f), &sn, &cs);
;     const cf w = cf{cs, sn}; cf wp = cf{1.f, 0.f};
;     cf v[32];
; #pragma unroll
;     for (int p = 0; p < 32; ++p) { v[p] = cmulc(pb[17 * p], wp); wp = cmul(wp, w); }
; DEV void hyena_issue_rows(const bf16_t* UT, int s, int c, u32x4 (&r)[4], int tid) {
; #pragma unroll
;     for (int b = 0; b < 4; ++b) r[b] = *(const u32x4*)(UT + ((size_t)(b * 3072 + s * 1024 + c)) * 4096 + tid * 8);
; }
	v_pk_fma_f32 v[10:11], v[10:11], s[96:97], v[4:5] op_sel_hi:[0,1,0] neg_lo:[0,0,1] neg_hi:[0,0,1]
	v_pk_add_f32 v[14:15], v[12:13], 0 op_sel:[1,0] op_sel_hi:[0,0] neg_lo:[1,0]
	v_pk_add_f32 v[12:13], v[112:113], v[86:87]
	v_pk_add_f32 v[86:87], v[112:113], v[86:87] neg_lo:[0,1] neg_hi:[0,1]
	v_mov_b32_e32 v112, v86
	v_mov_b32_e32 v113, v87
	v_pk_add_f32 v[86:87], v[96:97], v[88:89]
	v_pk_add_f32 v[88:89], v[96:97], v[88:89] neg_lo:[0,1] neg_hi:[0,1]
	v_pk_add_f32 v[96:97], v[88:89], 0 op_sel:[1,0] op_sel_hi:[0,0] neg_lo:[1,0]
	v_pk_add_f32 v[88:89], v[102:103], v[8:9]
	v_pk_add_f32 v[8:9], v[102:103], v[8:9] neg_lo:[0,1] neg_hi:[0,1]
	v_mov_b32_e32 v102, v8
	v_mov_b32_e32 v103, v9
	v_pk_add_f32 v[100:101], v[166:167], v[104:105] neg_lo:[0,1] neg_hi:[0,1]
	v_pk_add_f32 v[8:9], v[98:99], v[84:85]
	v_pk_add_f32 v[84:85], v[98:99], v[84:85] neg_lo:[0,1] neg_hi:[0,1]
	v_pk_add_f32 v[98:99], v[84:85], 0 op_sel:[1,0] op_sel_hi:[0,0] neg_lo:[1,0]
	v_pk_add_f32 v[84:85], v[166:167], v[104:105]
	v_mov_b32_e32 v166, v100
	v_mov_b32_e32 v167, v101
	v_pk_add_f32 v[100:101], v[110:111], v[10:11]
	v_pk_add_f32 v[10:11], v[110:111], v[10:11] neg_lo:[0,1] neg_hi:[0,1]
	v_pk_add_f32 v[104:105], v[10:11], 0 op_sel:[1,0] op_sel_hi:[0,0] neg_lo:[1,0]
	v_pk_add_f32 v[10:11], v[106:107], v[82:83]
	v_pk_add_f32 v[82:83], v[106:107], v[82:83] neg_lo:[0,1] neg_hi:[0,1]
	v_mov_b32_e32 v110, v82
	v_mov_b32_e32 v111, v83
	v_pk_add_f32 v[106:107], v[108:109], v[14:15]
	v_pk_add_f32 v[14:15], v[108:109], v[14:15] neg_lo:[0,1] neg_hi:[0,1]
	v_mov_b32_e32 v168, v14
	v_mov_b32_e32 v169, v15
	v_pk_add_f32 v[108:109], v[12:13], v[86:87]
	v_pk_add_f32 v[12:13], v[12:13], v[86:87] neg_lo:[0,1] neg_hi:[0,1]
	v_mov_b32_e32 v170, v12
	v_mov_b32_e32 v171, v13
	v_pk_add_f32 v[86:87], v[112:113], v[96:97]
	v_pk_add_f32 v[96:97], v[112:113], v[96:97] neg_lo:[0,1] neg_hi:[0,1]
	v_mov_b32_e32 v172, v96
	v_mov_b32_e32 v173, v97
	v_pk_add_f32 v[112:113], v[88:89], v[8:9]
	v_pk_add_f32 v[8:9], v[88:89], v[8:9] neg_lo:[0,1] neg_hi:[0,1]
	v_mov_b32_e32 v174, v8
	v_mov_b32_e32 v175, v9
	v_pk_add_f32 v[88:89], v[102:103], v[98:99]
	v_pk_add_f32 v[98:99], v[102:103], v[98:99] neg_lo:[0,1] neg_hi:[0,1]
	v_mov_b32_e32 v176, v98
	v_mov_b32_e32 v177, v99
	v_pk_add_f32 v[102:103], v[84:85], v[100:101]
	v_pk_add_f32 v[84:85], v[84:85], v[100:101] neg_lo:[0,1] neg_hi:[0,1]
	v_mov_b32_e32 v178, v84
	v_mov_b32_e32 v179, v85
	v_pk_add_f32 v[100:101], v[166:167], v[104:105]
	v_pk_add_f32 v[104:105], v[166:167], v[104:105] neg_lo:[0,1] neg_hi:[0,1]
	ds_write2_b64 v161, v[124:125], v[114:115] offset1:1
	ds_write2_b64 v162, v[10:11], v[112:113] offset1:1
	ds_write2_b64 v161, v[94:95], v[90:91] offset0:2 offset1:3
	ds_write2_b64 v162, v[108:109], v[102:103] offset0:2 offset1:3
	ds_write2_b64 v161, v[80:81], v[126:127] offset0:4 offset1:5
	ds_write2_b64 v162, v[106:107], v[88:89] offset0:4 offset1:5
	ds_write2_b64 v161, v[92:93], v[164:165] offset0:6 offset1:7
	ds_write2_b64 v162, v[86:87], v[100:101] offset0:6 offset1:7
	v_mov_b32_e32 v180, v104
	v_mov_b32_e32 v181, v105
	ds_write2_b64 v161, v[0:1], v[72:73] offset0:14 offset1:15
	v_mov_b32_e32 v0, v160
	ds_write2_b64 v161, v[18:19], v[116:117] offset0:8 offset1:9
	ds_write2_b64 v162, v[110:111], v[174:175] offset0:8 offset1:9
	ds_write2_b64 v161, v[16:17], v[122:123] offset0:10 offset1:11
	ds_write2_b64 v162, v[170:171], v[178:179] offset0:10 offset1:11
	ds_write2_b64 v161, v[2:3], v[74:75] offset0:12 offset1:13
	ds_write2_b64 v162, v[168:169], v[176:177] offset0:12 offset1:13
	ds_write2_b64 v162, v[172:173], v[180:181] offset0:14 offset1:15
	s_waitcnt lgkmcnt(0)
	s_barrier
	s_lshl_b32 s100, s19, 10
	s_add_i32 s100, s79, s100
	s_ashr_i32 s101, s100, 31
	s_lshl_b64 s[100:101], s[100:101], 13
	v_lshl_add_u64 v[218:219], v[56:57], 0, s[100:101]
	global_load_dwordx4 v[222:225], v[218:219], off
	s_add_u32 s100, s100, 0x1800000
	s_addc_u32 s101, s101, 0
	v_lshl_add_u64 v[220:221], v[56:57], 0, s[100:101]
	global_load_dwordx4 v[226:229], v[220:221], off
	s_add_u32 s100, s100, 0x1800000
	s_addc_u32 s101, s101, 0
	v_lshl_add_u64 v[218:219], v[56:57], 0, s[100:101]
	global_load_dwordx4 v[236:239], v[218:219], off
	s_add_u32 s100, s100, 0x1800000
	s_addc_u32 s101, s101, 0
	v_lshl_add_u64 v[220:221], v[56:57], 0, s[100:101]
	global_load_dwordx4 v[240:243], v[220:221], off
	s_nop 0
	v_lshrrev_b32_e32 v1, 4, v0
	v_and_b32_e32 v0, 15, v0
	v_mul_lo_u32 v1, v1, s15
	v_lshlrev_b32_e32 v2, 3, v0
	v_cvt_f32_ubyte0_e32 v0, v0
	v_add3_u32 v86, v159, v1, v2
	v_mul_f32_e32 v0, 0xbb800000, v0
	v_mul_f32_e32 v0, 0.5, v0
	v_add_u32_e32 v232, 0x800, v86
	v_add_u32_e32 v233, 0xc00, v86
	ds_read2_b64 v[166:169], v86 offset1:17
	ds_read2_b64 v[170:173], v86 offset0:34 offset1:51
	ds_read2_b64 v[174:177], v86 offset0:68 offset1:85
	ds_read2_b64 v[178:181], v86 offset0:102 offset1:119
	ds_read2_b64 v[182:185], v86 offset0:136 offset1:153
	ds_read2_b64 v[186:189], v86 offset0:170 offset1:187
	ds_read2_b64 v[190:193], v86 offset0:204 offset1:221
	ds_read2_b64 v[194:197], v86 offset0:238 offset1:255
	ds_read2_b64 v[198:201], v232 offset0:16 offset1:33
	ds_read2_b64 v[202:205], v232 offset0:50 offset1:67
	ds_read2_b64 v[208:211], v232 offset0:84 offset1:101
	ds_read2_b64 v[214:217], v232 offset0:118 offset1:135
	ds_read2_b64 v[218:221], v232 offset0:152 offset1:169
	v_sin_f32_e32 v1, v0
	v_cos_f32_e32 v0, v0
	s_waitcnt lgkmcnt(12)
; #define SINCOSPI(x, s, c) do { const float hx_ = 0.5f * (x); *(s) = __builtin_amdgcn_sinf(hx_); *(c) = __builtin_amdgcn_cosf(hx_); } while (0)
; DEV void fft_i2(LAS cf* buf, int t8) {
;     ...
;     float sn, cs; SINCOSPI(-(float)(t8 & 15) * (2.0f / 512.0f), &sn, &cs);
;     const cf w = cf{cs, sn}; cf wp = cf{1.f, 0.f};
;     cf v[32];
; #pragma unroll
;     for (int p = 0; p < 32; ++p) { v[p] = cmulc(pb[17 * p], wp); wp = cmul(wp, w); }
	v_pk_mul_f32 v[2:3], v[166:167], v[66:67] op_sel:[1,1] op_sel_hi:[1,0]
	v_pk_fma_f32 v[4:5], v[166:167], v[66:67], v[2:3] op_sel_hi:[0,1,1] neg_hi:[1,0,0]
	v_add_u32_e32 v87, 0x800, v86
	v_pk_mul_f32 v[2:3], v[66:67], v[0:1] op_sel:[1,1] op_sel_hi:[1,0] neg_lo:[1,0]
	v_pk_fma_f32 v[8:9], v[66:67], v[0:1], v[2:3] op_sel_hi:[0,1,1]
	v_pk_mul_f32 v[10:11], v[168:169], v[8:9] op_sel:[1,1] op_sel_hi:[1,0]
	v_pk_fma_f32 v[2:3], v[168:169], v[8:9], v[10:11] op_sel_hi:[0,1,1] neg_hi:[1,0,0]
	v_pk_mul_f32 v[6:7], v[8:9], v[0:1] op_sel:[1,1] op_sel_hi:[1,0] neg_lo:[1,0]
	v_pk_fma_f32 v[12:13], v[8:9], v[0:1], v[6:7] op_sel_hi:[0,1,1]
	ds_read2_b64 v[166:169], v232 offset0:186 offset1:203
	s_waitcnt lgkmcnt(12)
	v_pk_mul_f32 v[14:15], v[170:171], v[12:13] op_sel:[1,1] op_sel_hi:[1,0]
	v_pk_fma_f32 v[10:11], v[170:171], v[12:13], v[14:15] op_sel_hi:[0,1,1] neg_hi:[1,0,0]
	v_pk_mul_f32 v[6:7], v[12:13], v[0:1] op_sel:[1,1] op_sel_hi:[1,0] neg_lo:[1,0]
	v_pk_fma_f32 v[12:13], v[12:13], v[0:1], v[6:7] op_sel_hi:[0,1,1]
	v_pk_mul_f32 v[14:15], v[172:173], v[12:13] op_sel:[1,1] op_sel_hi:[1,0]
	v_pk_fma_f32 v[6:7], v[172:173], v[12:13], v[14:15] op_sel_hi:[0,1,1] neg_hi:[1,0,0]
	v_pk_mul_f32 v[8:9], v[12:13], v[0:1] op_sel:[1,1] op_sel_hi:[1,0] neg_lo:[1,0]
	v_pk_fma_f32 v[16:17], v[12:13], v[0:1], v[8:9] op_sel_hi:[0,1,1]
	ds_read2_b64 v[170:173], v232 offset0:220 offset1:237
	s_waitcnt lgkmcnt(12)
	v_pk_mul_f32 v[8:9], v[174:175], v[16:17] op_sel:[1,1] op_sel_hi:[1,0]
	v_pk_fma_f32 v[12:13], v[174:175], v[16:17], v[8:9] op_sel_hi:[0,1,1] neg_hi:[1,0,0]
	s_nop 0
	v_pk_mul_f32 v[8:9], v[16:17], v[0:1] op_sel:[1,1] op_sel_hi:[1,0] neg_lo:[1,0]
	v_pk_fma_f32 v[16:17], v[16:17], v[0:1], v[8:9] op_sel_hi:[0,1,1]
	v_pk_mul_f32 v[18:19], v[176:177], v[16:17] op_sel:[1,1] op_sel_hi:[1,0]
	v_pk_fma_f32 v[8:9], v[176:177], v[16:17], v[18:19] op_sel_hi:[0,1,1] neg_hi:[1,0,0]
	v_pk_mul_f32 v[14:15], v[16:17], v[0:1] op_sel:[1,1] op_sel_hi:[1,0] neg_lo:[1,0]
	v_pk_fma_f32 v[68:69], v[16:17], v[0:1], v[14:15] op_sel_hi:[0,1,1]
	ds_read2_b64 v[174:177], v233 offset0:126 offset1:143
	s_waitcnt lgkmcnt(12)
	v_pk_mul_f32 v[14:15], v[178:179], v[68:69] op_sel:[1,1] op_sel_hi:[1,0]
	v_pk_fma_f32 v[16:17], v[178:179], v[68:69], v[14:15] op_sel_hi:[0,1,1] neg_hi:[1,0,0]
	s_nop 0
	v_pk_mul_f32 v[14:15], v[68:69], v[0:1] op_sel:[1,1] op_sel_hi:[1,0] neg_lo:[1,0]
	v_pk_fma_f32 v[68:69], v[68:69], v[0:1], v[14:15] op_sel_hi:[0,1,1]
	v_pk_mul_f32 v[70:71], v[180:181], v[68:69] op_sel:[1,1] op_sel_hi:[1,0]
	v_pk_fma_f32 v[14:15], v[180:181], v[68:69], v[70:71] op_sel_hi:[0,1,1] neg_hi:[1,0,0]
	v_pk_mul_f32 v[18:19], v[68:69], v[0:1] op_sel:[1,1] op_sel_hi:[1,0] neg_lo:[1,0]
	v_pk_fma_f32 v[72:73], v[68:69], v[0:1], v[18:19] op_sel_hi:[0,1,1]
	s_waitcnt lgkmcnt(11)
	v_pk_mul_f32 v[18:19], v[182:183], v[72:73] op_sel:[1,1] op_sel_hi:[1,0]
	v_pk_fma_f32 v[68:69], v[182:183], v[72:73], v[18:19] op_sel_hi:[0,1,1] neg_hi:[1,0,0]
	s_nop 0
	v_pk_mul_f32 v[18:19], v[72:73], v[0:1] op_sel:[1,1] op_sel_hi:[1,0] neg_lo:[1,0]
	v_pk_fma_f32 v[72:73], v[72:73], v[0:1], v[18:19] op_sel_hi:[0,1,1]
	v_pk_mul_f32 v[74:75], v[184:185], v[72:73] op_sel:[1,1] op_sel_hi:[1,0]
	v_pk_fma_f32 v[18:19], v[184:185], v[72:73], v[74:75] op_sel_hi:[0,1,1] neg_hi:[1,0,0]
	v_pk_mul_f32 v[70:71], v[72:73], v[0:1] op_sel:[1,1] op_sel_hi:[1,0] neg_lo:[1,0]
	v_pk_fma_f32 v[76:77], v[72:73], v[0:1], v[70:71] op_sel_hi:[0,1,1]
	s_waitcnt lgkmcnt(10)
	v_pk_mul_f32 v[70:71], v[186:187], v[76:77] op_sel:[1,1] op_sel_hi:[1,0]
	v_pk_fma_f32 v[72:73], v[186:187], v[76:77], v[70:71] op_sel_hi:[0,1,1] neg_hi:[1,0,0]
	s_nop 0
	v_pk_mul_f32 v[70:71], v[76:77], v[0:1] op_sel:[1,1] op_sel_hi:[1,0] neg_lo:[1,0]
	v_pk_fma_f32 v[76:77], v[76:77], v[0:1], v[70:71] op_sel_hi:[0,1,1]
	v_pk_mul_f32 v[78:79], v[188:189], v[76:77] op_sel:[1,1] op_sel_hi:[1,0]
	v_pk_fma_f32 v[70:71], v[188:189], v[76:77], v[78:79] op_sel_hi:[0,1,1] neg_hi:[1,0,0]
	v_pk_mul_f32 v[74:75], v[76:77], v[0:1] op_sel:[1,1] op_sel_hi:[1,0] neg_lo:[1,0]
	v_pk_fma_f32 v[80:81], v[76:77], v[0:1], v[74:75] op_sel_hi:[0,1,1]
	s_waitcnt lgkmcnt(9)
	v_pk_mul_f32 v[74:75], v[190:191], v[80:81] op_sel:[1,1] op_sel_hi:[1,0]
	v_pk_fma_f32 v[76:77], v[190:191], v[80:81], v[74:75] op_sel_hi:[0,1,1] neg_hi:[1,0,0]
	s_nop 0
	v_pk_mul_f32 v[74:75], v[80:81], v[0:1] op_sel:[1,1] op_sel_hi:[1,0] neg_lo:[1,0]
	v_pk_fma_f32 v[80:81], v[80:81], v[0:1], v[74:75] op_sel_hi:[0,1,1]
	v_pk_mul_f32 v[82:83], v[192:193], v[80:81] op_sel:[1,1] op_sel_hi:[1,0]
	v_pk_fma_f32 v[74:75], v[192:193], v[80:81], v[82:83] op_sel_hi:[0,1,1] neg_hi:[1,0,0]
	v_pk_mul_f32 v[78:79], v[80:81], v[0:1] op_sel:[1,1] op_sel_hi:[1,0] neg_lo:[1,0]
	v_pk_fma_f32 v[84:85], v[80:81], v[0:1], v[78:79] op_sel_hi:[0,1,1]
	s_waitcnt lgkmcnt(8)
	v_pk_mul_f32 v[78:79], v[194:195], v[84:85] op_sel:[1,1] op_sel_hi:[1,0]
	v_pk_fma_f32 v[80:81], v[194:195], v[84:85], v[78:79] op_sel_hi:[0,1,1] neg_hi:[1,0,0]
	s_nop 0
	v_pk_mul_f32 v[78:79], v[84:85], v[0:1] op_sel:[1,1] op_sel_hi:[1,0] neg_lo:[1,0]
	v_pk_fma_f32 v[84:85], v[84:85], v[0:1], v[78:79] op_sel_hi:[0,1,1]
	v_pk_mul_f32 v[88:89], v[196:197], v[84:85] op_sel:[1,1] op_sel_hi:[1,0]
	v_pk_fma_f32 v[78:79], v[196:197], v[84:85], v[88:89] op_sel_hi:[0,1,1] neg_hi:[1,0,0]
	v_pk_mul_f32 v[82:83], v[84:85], v[0:1] op_sel:[1,1] op_sel_hi:[1,0] neg_lo:[1,0]
	v_pk_fma_f32 v[92:93], v[84:85], v[0:1], v[82:83] op_sel_hi:[0,1,1]
	s_waitcnt lgkmcnt(7)
; #define SINCOSPI(x, s, c) do { const float hx_ = 0.5f * (x); *(s) = __builtin_amdgcn_sinf(hx_); *(c) = __builtin_amdgcn_cosf(hx_); } while (0)
; DEV void fft_i2(LAS cf* buf, int t8) {
;     ...
;     float sn, cs; SINCOSPI(-(float)(t8 & 15) * (2.0f / 512.0f), &sn, &cs);
;     const cf w = cf{cs, sn}; cf wp = cf{1.f, 0.f};
;     cf v[32];
; #pragma unroll
;     for (int p = 0; p < 32; ++p) { v[p] = cmulc(pb[17 * p], wp); wp = cmul(wp, w); }
	v_pk_mul_f32 v[82:83], v[198:199], v[92:93] op_sel:[1,1] op_sel_hi:[1,0]
	v_pk_fma_f32 v[84:85], v[198:199], v[92:93], v[82:83] op_sel_hi:[0,1,1] neg_hi:[1,0,0]
	s_nop 0
	v_pk_mul_f32 v[82:83], v[92:93], v[0:1] op_sel:[1,1] op_sel_hi:[1,0] neg_lo:[1,0]
	v_pk_fma_f32 v[88:89], v[92:93], v[0:1], v[82:83] op_sel_hi:[0,1,1]
	v_pk_mul_f32 v[92:93], v[200:201], v[88:89] op_sel:[1,1] op_sel_hi:[1,0]
	v_pk_fma_f32 v[82:83], v[200:201], v[88:89], v[92:93] op_sel_hi:[0,1,1] neg_hi:[1,0,0]
	s_nop 0
	v_pk_mul_f32 v[90:91], v[88:89], v[0:1] op_sel:[1,1] op_sel_hi:[1,0] neg_lo:[1,0]
	v_pk_fma_f32 v[92:93], v[88:89], v[0:1], v[90:91] op_sel_hi:[0,1,1]
	s_waitcnt lgkmcnt(6)
	v_pk_mul_f32 v[96:97], v[202:203], v[92:93] op_sel:[1,1] op_sel_hi:[1,0]
	v_pk_fma_f32 v[94:95], v[202:203], v[92:93], v[96:97] op_sel_hi:[0,1,1] neg_hi:[1,0,0]
	v_pk_mul_f32 v[88:89], v[92:93], v[0:1] op_sel:[1,1] op_sel_hi:[1,0] neg_lo:[1,0]
	v_pk_fma_f32 v[92:93], v[92:93], v[0:1], v[88:89] op_sel_hi:[0,1,1]
	v_pk_mul_f32 v[88:89], v[204:205], v[92:93] op_sel:[1,1] op_sel_hi:[1,0]
	v_pk_fma_f32 v[96:97], v[204:205], v[92:93], v[88:89] op_sel_hi:[0,1,1] neg_hi:[1,0,0]
	s_nop 0
	v_pk_mul_f32 v[88:89], v[92:93], v[0:1] op_sel:[1,1] op_sel_hi:[1,0] neg_lo:[1,0]
	v_pk_fma_f32 v[92:93], v[92:93], v[0:1], v[88:89] op_sel_hi:[0,1,1]
	s_waitcnt lgkmcnt(5)
	v_pk_mul_f32 v[100:101], v[208:209], v[92:93] op_sel:[1,1] op_sel_hi:[1,0]
	v_pk_fma_f32 v[98:99], v[208:209], v[92:93], v[100:101] op_sel_hi:[0,1,1] neg_hi:[1,0,0]
	v_pk_mul_f32 v[88:89], v[92:93], v[0:1] op_sel:[1,1] op_sel_hi:[1,0] neg_lo:[1,0]
	v_pk_fma_f32 v[92:93], v[92:93], v[0:1], v[88:89] op_sel_hi:[0,1,1]
	v_pk_mul_f32 v[88:89], v[210:211], v[92:93] op_sel:[1,1] op_sel_hi:[1,0]
	v_pk_fma_f32 v[100:101], v[210:211], v[92:93], v[88:89] op_sel_hi:[0,1,1] neg_hi:[1,0,0]
	s_nop 0
	v_pk_mul_f32 v[88:89], v[92:93], v[0:1] op_sel:[1,1] op_sel_hi:[1,0] neg_lo:[1,0]
	v_pk_fma_f32 v[92:93], v[92:93], v[0:1], v[88:89] op_sel_hi:[0,1,1]
	s_waitcnt lgkmcnt(4)
	v_pk_mul_f32 v[104:105], v[214:215], v[92:93] op_sel:[1,1] op_sel_hi:[1,0]
	v_pk_fma_f32 v[102:103], v[214:215], v[92:93], v[104:105] op_sel_hi:[0,1,1] neg_hi:[1,0,0]
	v_pk_mul_f32 v[88:89], v[92:93], v[0:1] op_sel:[1,1] op_sel_hi:[1,0] neg_lo:[1,0]
	v_pk_fma_f32 v[92:93], v[92:93], v[0:1], v[88:89] op_sel_hi:[0,1,1]
	v_pk_mul_f32 v[88:89], v[216:217], v[92:93] op_sel:[1,1] op_sel_hi:[1,0]
	v_pk_fma_f32 v[104:105], v[216:217], v[92:93], v[88:89] op_sel_hi:[0,1,1] neg_hi:[1,0,0]
	s_nop 0
	v_pk_mul_f32 v[88:89], v[92:93], v[0:1] op_sel:[1,1] op_sel_hi:[1,0] neg_lo:[1,0]
	v_pk_fma_f32 v[92:93], v[92:93], v[0:1], v[88:89] op_sel_hi:[0,1,1]
	s_waitcnt lgkmcnt(3)
	v_pk_mul_f32 v[108:109], v[218:219], v[92:93] op_sel:[1,1] op_sel_hi:[1,0]
	v_pk_fma_f32 v[106:107], v[218:219], v[92:93], v[108:109] op_sel_hi:[0,1,1] neg_hi:[1,0,0]
	v_pk_mul_f32 v[88:89], v[92:93], v[0:1] op_sel:[1,1] op_sel_hi:[1,0] neg_lo:[1,0]
	v_pk_fma_f32 v[92:93], v[92:93], v[0:1], v[88:89] op_sel_hi:[0,1,1]
	v_pk_mul_f32 v[88:89], v[220:221], v[92:93] op_sel:[1,1] op_sel_hi:[1,0]
	v_pk_fma_f32 v[108:109], v[220:221], v[92:93], v[88:89] op_sel_hi:[0,1,1] neg_hi:[1,0,0]
	s_nop 0
	v_pk_mul_f32 v[88:89], v[92:93], v[0:1] op_sel:[1,1] op_sel_hi:[1,0] neg_lo:[1,0]
	v_pk_fma_f32 v[92:93], v[92:93], v[0:1], v[88:89] op_sel_hi:[0,1,1]
	s_waitcnt lgkmcnt(2)
	v_pk_mul_f32 v[112:113], v[166:167], v[92:93] op_sel:[1,1] op_sel_hi:[1,0]
	v_pk_fma_f32 v[110:111], v[166:167], v[92:93], v[112:113] op_sel_hi:[0,1,1] neg_hi:[1,0,0]
	v_pk_mul_f32 v[88:89], v[92:93], v[0:1] op_sel:[1,1] op_sel_hi:[1,0] neg_lo:[1,0]
	v_pk_fma_f32 v[92:93], v[92:93], v[0:1], v[88:89] op_sel_hi:[0,1,1]
	v_pk_mul_f32 v[88:89], v[168:169], v[92:93] op_sel:[1,1] op_sel_hi:[1,0]
	v_pk_fma_f32 v[112:113], v[168:169], v[92:93], v[88:89] op_sel_hi:[0,1,1] neg_hi:[1,0,0]
	s_nop 0
	v_pk_mul_f32 v[88:89], v[92:93], v[0:1] op_sel:[1,1] op_sel_hi:[1,0] neg_lo:[1,0]
	v_pk_fma_f32 v[92:93], v[92:93], v[0:1], v[88:89] op_sel_hi:[0,1,1]
	s_waitcnt lgkmcnt(1)
	v_pk_mul_f32 v[116:117], v[170:171], v[92:93] op_sel:[1,1] op_sel_hi:[1,0]
	v_pk_fma_f32 v[114:115], v[170:171], v[92:93], v[116:117] op_sel_hi:[0,1,1] neg_hi:[1,0,0]
	v_pk_mul_f32 v[88:89], v[92:93], v[0:1] op_sel:[1,1] op_sel_hi:[1,0] neg_lo:[1,0]
	v_pk_fma_f32 v[92:93], v[92:93], v[0:1], v[88:89] op_sel_hi:[0,1,1]
	v_pk_mul_f32 v[88:89], v[172:173], v[92:93] op_sel:[1,1] op_sel_hi:[1,0]
	v_pk_fma_f32 v[116:117], v[172:173], v[92:93], v[88:89] op_sel_hi:[0,1,1] neg_hi:[1,0,0]
	s_nop 0
	v_pk_mul_f32 v[88:89], v[92:93], v[0:1] op_sel:[1,1] op_sel_hi:[1,0] neg_lo:[1,0]
	v_pk_fma_f32 v[118:119], v[92:93], v[0:1], v[88:89] op_sel_hi:[0,1,1]
	s_nop 0
	v_add_u32_e32 v88, 0xc00, v86
	v_pk_mul_f32 v[120:121], v[118:119], v[0:1] op_sel:[1,1] op_sel_hi:[1,0] neg_lo:[1,0]
	v_pk_fma_f32 v[0:1], v[118:119], v[0:1], v[120:121] op_sel_hi:[0,1,1]
	s_waitcnt lgkmcnt(0)
; #define SINCOSPI(x, s, c) do { const float hx_ = 0.5f * (x); *(s) = __builtin_amdgcn_sinf(hx_); *(c) = __builtin_amdgcn_cosf(hx_); } while (0)
; template <int R, bool INV> DEV void dft_regs(cf (&v)[R]) {
; #pragma unroll
;     for (int s = R; s >= 2; s >>= 1) {
;         const int h = s >> 1;
; #pragma unroll
;         for (int b = 0; b < R; b += s) {
; #pragma unroll
;             for (int k = 0; k < h; ++k) {
;                 const cf a = v[b + k], c = v[b + k + h];
;                 v[b + k] = a + c;
;                 const cf d = a - c;
;                 const int m = k * (32 / s);
;                 const float wr = tw_cos(m), wi = INV ? tw_sin(m) : -tw_sin(m);
;                 v[b + k + h] = cf{d.x * wr - d.y * wi, d.x * wi + d.y * wr};
;             }
;         }
;     }
; }
; DEV void fft_i2(LAS cf* buf, int t8) {
;     ...
;     float sn, cs; SINCOSPI(-(float)(t8 & 15) * (2.0f / 512.0f), &sn, &cs);
;     const cf w = cf{cs, sn}; cf wp = cf{1.f, 0.f};
;     cf v[32];
; #pragma unroll
;     for (int p = 0; p < 32; ++p) { v[p] = cmulc(pb[17 * p], wp); wp = cmul(wp, w); }
;     dft_regs<32, true>(v);
	v_pk_mul_f32 v[120:121], v[174:175], v[118:119] op_sel:[1,1] op_sel_hi:[1,0]
	v_pk_fma_f32 v[90:91], v[174:175], v[118:119], v[120:121] op_sel_hi:[0,1,1] neg_hi:[1,0,0]
	v_pk_mul_f32 v[118:119], v[176:177], v[0:1] op_sel:[1,1] op_sel_hi:[1,0]
	v_pk_fma_f32 v[0:1], v[176:177], v[0:1], v[118:119] op_sel_hi:[0,1,1] neg_hi:[1,0,0]
	v_pk_add_f32 v[92:93], v[4:5], v[84:85]
	v_pk_add_f32 v[4:5], v[4:5], v[84:85] neg_lo:[0,1] neg_hi:[0,1]
	v_mov_b32_e32 v118, v4
	v_mov_b32_e32 v119, v5
	v_pk_add_f32 v[4:5], v[2:3], v[82:83]
	v_pk_add_f32 v[2:3], v[2:3], v[82:83] neg_lo:[0,1] neg_hi:[0,1]
	v_pk_mul_f32 v[82:83], v[2:3], s[82:83] op_sel_hi:[1,0]
	v_pk_fma_f32 v[84:85], v[2:3], s[94:95], v[82:83] op_sel:[0,0,1] op_sel_hi:[1,0,0] neg_lo:[0,0,1]
	v_pk_add_f32 v[2:3], v[10:11], v[94:95]
	v_pk_add_f32 v[10:11], v[10:11], v[94:95] neg_lo:[0,1] neg_hi:[0,1]
	v_pk_mul_f32 v[82:83], v[10:11], s[84:85] op_sel_hi:[1,0]
	v_pk_fma_f32 v[94:95], v[10:11], s[16:17], v[82:83] op_sel:[0,0,1] op_sel_hi:[1,0,0] neg_lo:[0,0,1]
	v_pk_add_f32 v[10:11], v[6:7], v[96:97]
	v_pk_add_f32 v[6:7], v[6:7], v[96:97] neg_lo:[0,1] neg_hi:[0,1]
	v_pk_mul_f32 v[82:83], v[6:7], s[4:5] op_sel_hi:[1,0]
	v_pk_fma_f32 v[96:97], v[6:7], s[86:87], v[82:83] op_sel:[0,0,1] op_sel_hi:[1,0,0] neg_lo:[0,0,1]
	v_pk_add_f32 v[6:7], v[12:13], v[98:99]
	v_pk_add_f32 v[12:13], v[12:13], v[98:99] neg_lo:[0,1] neg_hi:[0,1]
	v_pk_mul_f32 v[82:83], v[12:13], s[18:19] op_sel_hi:[1,0]
	v_pk_fma_f32 v[98:99], v[12:13], s[18:19], v[82:83] op_sel:[0,0,1] op_sel_hi:[1,0,0] neg_lo:[0,0,1]
	v_pk_add_f32 v[12:13], v[8:9], v[100:101]
	v_pk_add_f32 v[8:9], v[8:9], v[100:101] neg_lo:[0,1] neg_hi:[0,1]
	v_pk_mul_f32 v[82:83], v[8:9], s[86:87] op_sel_hi:[1,0]
	v_pk_fma_f32 v[100:101], v[8:9], s[4:5], v[82:83] op_sel:[0,0,1] op_sel_hi:[1,0,0] neg_lo:[0,0,1]
	v_pk_add_f32 v[8:9], v[16:17], v[102:103]
	v_pk_add_f32 v[16:17], v[16:17], v[102:103] neg_lo:[0,1] neg_hi:[0,1]
	v_pk_mul_f32 v[82:83], v[16:17], s[16:17] op_sel_hi:[1,0]
	v_pk_fma_f32 v[102:103], v[16:17], s[84:85], v[82:83] op_sel:[0,0,1] op_sel_hi:[1,0,0] neg_lo:[0,0,1]
	v_pk_add_f32 v[16:17], v[14:15], v[104:105]
	v_pk_add_f32 v[14:15], v[14:15], v[104:105] neg_lo:[0,1] neg_hi:[0,1]
	v_pk_mul_f32 v[82:83], v[14:15], s[94:95] op_sel_hi:[1,0]
	v_pk_fma_f32 v[104:105], v[14:15], s[82:83], v[82:83] op_sel:[0,0,1] op_sel_hi:[1,0,0] neg_lo:[0,0,1]
	v_pk_add_f32 v[14:15], v[68:69], v[106:107]
	v_pk_add_f32 v[68:69], v[68:69], v[106:107] neg_lo:[0,1] neg_hi:[0,1]
	v_pk_add_f32 v[82:83], v[68:69], 0 op_sel:[1,0] op_sel_hi:[0,0] neg_lo:[1,0]
	v_pk_add_f32 v[68:69], v[18:19], v[108:109]
	v_pk_add_f32 v[18:19], v[18:19], v[108:109] neg_lo:[0,1] neg_hi:[0,1]
	v_pk_mul_f32 v[106:107], v[18:19], s[6:7] op_sel:[1,0]
	s_mov_b32 s6, s87
	v_pk_fma_f32 v[18:19], v[18:19], s[28:29], v[106:107] op_sel_hi:[0,1,1] neg_lo:[0,0,1] neg_hi:[0,0,1]
	v_pk_add_f32 v[106:107], v[72:73], v[110:111]
	v_pk_add_f32 v[72:73], v[72:73], v[110:111] neg_lo:[0,1] neg_hi:[0,1]
	s_mov_b32 s7, s86
	v_pk_mul_f32 v[108:109], v[72:73], s[24:25] op_sel:[1,0]
	v_pk_fma_f32 v[72:73], v[72:73], s[0:1], v[108:109] op_sel_hi:[0,1,1] neg_lo:[0,0,1] neg_hi:[0,0,1]
	v_pk_add_f32 v[108:109], v[70:71], v[112:113]
	v_pk_add_f32 v[70:71], v[70:71], v[112:113] neg_lo:[0,1] neg_hi:[0,1]
	v_pk_mul_f32 v[110:111], v[70:71], s[2:3] op_sel:[1,0]
	s_mov_b32 s2, s11
	v_pk_fma_f32 v[70:71], v[70:71], s[6:7], v[110:111] op_sel_hi:[0,1,1] neg_lo:[0,0,1] neg_hi:[0,0,1]
	v_pk_add_f32 v[110:111], v[76:77], v[114:115]
	v_pk_add_f32 v[76:77], v[76:77], v[114:115] neg_lo:[0,1] neg_hi:[0,1]
	v_mul_f32_e32 v112, 0x3f3504f3, v77
	v_pk_fma_f32 v[76:77], v[76:77], s[96:97], v[112:113] op_sel_hi:[0,1,0] neg_lo:[0,0,1] neg_hi:[0,0,1]
	v_pk_add_f32 v[112:113], v[74:75], v[116:117]
	v_pk_add_f32 v[74:75], v[74:75], v[116:117] neg_lo:[0,1] neg_hi:[0,1]
	v_pk_mul_f32 v[114:115], v[74:75], s[4:5] op_sel:[1,0]
	s_lshl_b32 s5, s19, 10
	v_pk_fma_f32 v[74:75], v[74:75], s[2:3], v[114:115] op_sel_hi:[0,1,1] neg_lo:[0,0,1] neg_hi:[0,0,1]
	v_pk_add_f32 v[114:115], v[80:81], v[90:91]
	v_pk_add_f32 v[80:81], v[80:81], v[90:91] neg_lo:[0,1] neg_hi:[0,1]
	s_mov_b32 s2, s9
	v_pk_mul_f32 v[90:91], v[80:81], s[84:85] op_sel:[1,0]
	s_mov_b32 s3, s82
	v_pk_fma_f32 v[80:81], v[80:81], s[88:89], v[90:91] op_sel_hi:[0,1,1] neg_lo:[0,0,1] neg_hi:[0,0,1]
	v_pk_add_f32 v[90:91], v[78:79], v[0:1]
	v_pk_add_f32 v[0:1], v[78:79], v[0:1] neg_lo:[0,1] neg_hi:[0,1]
	s_add_i32 s6, s79, s5
	v_pk_mul_f32 v[78:79], v[0:1], s[82:83] op_sel:[1,0]
	s_ashr_i32 s7, s6, 31
	v_pk_fma_f32 v[0:1], v[0:1], s[2:3], v[78:79] op_sel_hi:[0,1,1] neg_lo:[0,0,1] neg_hi:[0,0,1]
	v_pk_add_f32 v[78:79], v[92:93], v[14:15]
	v_pk_add_f32 v[14:15], v[92:93], v[14:15] neg_lo:[0,1] neg_hi:[0,1]
	s_lshl_b64 s[2:3], s[6:7], 13
	v_mov_b32_e32 v116, v14
	v_mov_b32_e32 v117, v15
	v_pk_add_f32 v[14:15], v[4:5], v[68:69]
	v_pk_add_f32 v[4:5], v[4:5], v[68:69] neg_lo:[0,1] neg_hi:[0,1]
	v_pk_mul_f32 v[68:69], v[4:5], s[84:85] op_sel_hi:[1,0]
	v_pk_fma_f32 v[92:93], v[4:5], s[16:17], v[68:69] op_sel:[0,0,1] op_sel_hi:[1,0,0] neg_lo:[0,0,1]
	v_pk_add_f32 v[4:5], v[2:3], v[106:107]
	v_pk_add_f32 v[2:3], v[2:3], v[106:107] neg_lo:[0,1] neg_hi:[0,1]
	v_pk_mul_f32 v[68:69], v[2:3], s[18:19] op_sel_hi:[1,0]
	v_pk_fma_f32 v[106:107], v[2:3], s[18:19], v[68:69] op_sel:[0,0,1] op_sel_hi:[1,0,0] neg_lo:[0,0,1]
	v_pk_add_f32 v[2:3], v[10:11], v[108:109]
	v_pk_add_f32 v[10:11], v[10:11], v[108:109] neg_lo:[0,1] neg_hi:[0,1]
	v_pk_mul_f32 v[68:69], v[10:11], s[16:17] op_sel_hi:[1,0]
	v_pk_fma_f32 v[108:109], v[10:11], s[84:85], v[68:69] op_sel:[0,0,1] op_sel_hi:[1,0,0] neg_lo:[0,0,1]
	v_pk_add_f32 v[10:11], v[6:7], v[110:111]
; template <int R, bool INV> DEV void dft_regs(cf (&v)[R]) {
; #pragma unroll
;     for (int s = R; s >= 2; s >>= 1) {
;         const int h = s >> 1;
; #pragma unroll
;         for (int b = 0; b < R; b += s) {
; #pragma unroll
;             for (int k = 0; k < h; ++k) {
;                 const cf a = v[b + k], c = v[b + k + h];
;                 v[b + k] = a + c;
;                 const cf d = a - c;
;                 const int m = k * (32 / s);
;                 const float wr = tw_cos(m), wi = INV ? tw_sin(m) : -tw_sin(m);
;                 v[b + k + h] = cf{d.x * wr - d.y * wi, d.x * wi + d.y * wr};
;             }
;         }
;     }
; }
	v_pk_add_f32 v[6:7], v[6:7], v[110:111] neg_lo:[0,1] neg_hi:[0,1]
	v_pk_add_f32 v[68:69], v[6:7], 0 op_sel:[1,0] op_sel_hi:[0,0] neg_lo:[1,0]
	v_pk_add_f32 v[6:7], v[12:13], v[112:113]
	v_pk_add_f32 v[12:13], v[12:13], v[112:113] neg_lo:[0,1] neg_hi:[0,1]
	v_pk_mul_f32 v[110:111], v[12:13], s[24:25] op_sel:[1,0]
	v_pk_fma_f32 v[12:13], v[12:13], s[0:1], v[110:111] op_sel_hi:[0,1,1] neg_lo:[0,0,1] neg_hi:[0,0,1]
	v_pk_add_f32 v[110:111], v[8:9], v[114:115]
	v_pk_add_f32 v[8:9], v[8:9], v[114:115] neg_lo:[0,1] neg_hi:[0,1]
	v_mul_f32_e32 v112, 0x3f3504f3, v9
	v_pk_fma_f32 v[8:9], v[8:9], s[96:97], v[112:113] op_sel_hi:[0,1,0] neg_lo:[0,0,1] neg_hi:[0,0,1]
	v_pk_add_f32 v[112:113], v[16:17], v[90:91]
	v_pk_add_f32 v[16:17], v[16:17], v[90:91] neg_lo:[0,1] neg_hi:[0,1]
	v_pk_mul_f32 v[90:91], v[16:17], s[84:85] op_sel:[1,0]
	v_pk_fma_f32 v[16:17], v[16:17], s[88:89], v[90:91] op_sel_hi:[0,1,1] neg_lo:[0,0,1] neg_hi:[0,0,1]
	v_pk_add_f32 v[90:91], v[118:119], v[82:83]
	v_pk_add_f32 v[82:83], v[118:119], v[82:83] neg_lo:[0,1] neg_hi:[0,1]
	v_mov_b32_e32 v118, v82
	v_mov_b32_e32 v119, v83
	v_pk_add_f32 v[82:83], v[84:85], v[18:19]
	v_pk_add_f32 v[18:19], v[84:85], v[18:19] neg_lo:[0,1] neg_hi:[0,1]
	v_pk_mul_f32 v[84:85], v[18:19], s[84:85] op_sel_hi:[1,0]
	v_pk_fma_f32 v[114:115], v[18:19], s[16:17], v[84:85] op_sel:[0,0,1] op_sel_hi:[1,0,0] neg_lo:[0,0,1]
	v_pk_add_f32 v[18:19], v[94:95], v[72:73]
	v_pk_add_f32 v[72:73], v[94:95], v[72:73] neg_lo:[0,1] neg_hi:[0,1]
	v_pk_mul_f32 v[84:85], v[72:73], s[18:19] op_sel_hi:[1,0]
	v_pk_fma_f32 v[94:95], v[72:73], s[18:19], v[84:85] op_sel:[0,0,1] op_sel_hi:[1,0,0] neg_lo:[0,0,1]
	v_pk_add_f32 v[72:73], v[96:97], v[70:71]
	v_pk_add_f32 v[70:71], v[96:97], v[70:71] neg_lo:[0,1] neg_hi:[0,1]
	v_pk_mul_f32 v[84:85], v[70:71], s[16:17] op_sel_hi:[1,0]
	v_pk_fma_f32 v[96:97], v[70:71], s[84:85], v[84:85] op_sel:[0,0,1] op_sel_hi:[1,0,0] neg_lo:[0,0,1]
	v_pk_add_f32 v[70:71], v[98:99], v[76:77]
	v_pk_add_f32 v[76:77], v[98:99], v[76:77] neg_lo:[0,1] neg_hi:[0,1]
	v_pk_add_f32 v[84:85], v[76:77], 0 op_sel:[1,0] op_sel_hi:[0,0] neg_lo:[1,0]
	v_pk_add_f32 v[76:77], v[100:101], v[74:75]
	v_pk_add_f32 v[74:75], v[100:101], v[74:75] neg_lo:[0,1] neg_hi:[0,1]
	v_pk_mul_f32 v[98:99], v[74:75], s[24:25] op_sel:[1,0]
	v_pk_fma_f32 v[74:75], v[74:75], s[0:1], v[98:99] op_sel_hi:[0,1,1] neg_lo:[0,0,1] neg_hi:[0,0,1]
	v_pk_add_f32 v[98:99], v[102:103], v[80:81]
	v_pk_add_f32 v[80:81], v[102:103], v[80:81] neg_lo:[0,1] neg_hi:[0,1]
	v_mul_f32_e32 v100, 0x3f3504f3, v81
	v_pk_fma_f32 v[80:81], v[80:81], s[96:97], v[100:101] op_sel_hi:[0,1,0] neg_lo:[0,0,1] neg_hi:[0,0,1]
	v_pk_add_f32 v[100:101], v[104:105], v[0:1]
	v_pk_add_f32 v[0:1], v[104:105], v[0:1] neg_lo:[0,1] neg_hi:[0,1]
	v_pk_mul_f32 v[102:103], v[0:1], s[84:85] op_sel:[1,0]
	v_pk_fma_f32 v[0:1], v[0:1], s[88:89], v[102:103] op_sel_hi:[0,1,1] neg_lo:[0,0,1] neg_hi:[0,0,1]
	v_pk_add_f32 v[102:103], v[78:79], v[10:11]
	v_pk_add_f32 v[10:11], v[78:79], v[10:11] neg_lo:[0,1] neg_hi:[0,1]
	v_mov_b32_e32 v104, v10
	v_mov_b32_e32 v105, v11
	v_pk_add_f32 v[10:11], v[14:15], v[6:7]
	v_pk_add_f32 v[6:7], v[14:15], v[6:7] neg_lo:[0,1] neg_hi:[0,1]
	v_pk_mul_f32 v[14:15], v[6:7], s[18:19] op_sel_hi:[1,0]
	v_pk_fma_f32 v[78:79], v[6:7], s[18:19], v[14:15] op_sel:[0,0,1] op_sel_hi:[1,0,0] neg_lo:[0,0,1]
	v_pk_add_f32 v[6:7], v[4:5], v[110:111]
	v_pk_add_f32 v[4:5], v[4:5], v[110:111] neg_lo:[0,1] neg_hi:[0,1]
	v_pk_add_f32 v[14:15], v[4:5], 0 op_sel:[1,0] op_sel_hi:[0,0] neg_lo:[1,0]
	v_pk_add_f32 v[4:5], v[2:3], v[112:113]
	v_pk_add_f32 v[2:3], v[2:3], v[112:113] neg_lo:[0,1] neg_hi:[0,1]
	v_mul_f32_e32 v110, 0x3f3504f3, v3
	v_pk_fma_f32 v[2:3], v[2:3], s[96:97], v[110:111] op_sel_hi:[0,1,0] neg_lo:[0,0,1] neg_hi:[0,0,1]
	v_pk_add_f32 v[110:111], v[116:117], v[68:69]
	v_pk_add_f32 v[68:69], v[116:117], v[68:69] neg_lo:[0,1] neg_hi:[0,1]
	v_mov_b32_e32 v116, v68
	v_mov_b32_e32 v117, v69
	v_pk_add_f32 v[68:69], v[92:93], v[12:13]
	v_pk_add_f32 v[12:13], v[92:93], v[12:13] neg_lo:[0,1] neg_hi:[0,1]
	v_pk_mul_f32 v[92:93], v[12:13], s[18:19] op_sel_hi:[1,0]
	v_pk_fma_f32 v[112:113], v[12:13], s[18:19], v[92:93] op_sel:[0,0,1] op_sel_hi:[1,0,0] neg_lo:[0,0,1]
	v_pk_add_f32 v[12:13], v[106:107], v[8:9]
	v_pk_add_f32 v[8:9], v[106:107], v[8:9] neg_lo:[0,1] neg_hi:[0,1]
	v_pk_add_f32 v[92:93], v[8:9], 0 op_sel:[1,0] op_sel_hi:[0,0] neg_lo:[1,0]
	v_pk_add_f32 v[8:9], v[108:109], v[16:17]
	v_pk_add_f32 v[16:17], v[108:109], v[16:17] neg_lo:[0,1] neg_hi:[0,1]
	v_mul_f32_e32 v106, 0x3f3504f3, v17
	v_pk_fma_f32 v[16:17], v[16:17], s[96:97], v[106:107] op_sel_hi:[0,1,0] neg_lo:[0,0,1] neg_hi:[0,0,1]
	v_pk_add_f32 v[106:107], v[90:91], v[70:71]
	v_pk_add_f32 v[70:71], v[90:91], v[70:71] neg_lo:[0,1] neg_hi:[0,1]
	v_mov_b32_e32 v108, v70
	v_mov_b32_e32 v109, v71
	v_pk_add_f32 v[70:71], v[82:83], v[76:77]
	v_pk_add_f32 v[76:77], v[82:83], v[76:77] neg_lo:[0,1] neg_hi:[0,1]
	v_pk_mul_f32 v[82:83], v[76:77], s[18:19] op_sel_hi:[1,0]
	v_pk_fma_f32 v[90:91], v[76:77], s[18:19], v[82:83] op_sel:[0,0,1] op_sel_hi:[1,0,0] neg_lo:[0,0,1]
	v_pk_add_f32 v[76:77], v[18:19], v[98:99]
	v_pk_add_f32 v[18:19], v[18:19], v[98:99] neg_lo:[0,1] neg_hi:[0,1]
	v_pk_add_f32 v[82:83], v[18:19], 0 op_sel:[1,0] op_sel_hi:[0,0] neg_lo:[1,0]
	v_pk_add_f32 v[18:19], v[72:73], v[100:101]
	v_pk_add_f32 v[72:73], v[72:73], v[100:101] neg_lo:[0,1] neg_hi:[0,1]
	v_mul_f32_e32 v98, 0x3f3504f3, v73
	v_pk_fma_f32 v[72:73], v[72:73], s[96:97], v[98:99] op_sel_hi:[0,1,0] neg_lo:[0,0,1] neg_hi:[0,0,1]
	v_pk_add_f32 v[98:99], v[118:119], v[84:85]
	v_pk_add_f32 v[84:85], v[118:119], v[84:85] neg_lo:[0,1] neg_hi:[0,1]
; template <int R, bool INV> DEV void dft_regs(cf (&v)[R]) {
; #pragma unroll
;     for (int s = R; s >= 2; s >>= 1) {
;         const int h = s >> 1;
; #pragma unroll
;         for (int b = 0; b < R; b += s) {
; #pragma unroll
;             for (int k = 0; k < h; ++k) {
;                 const cf a = v[b + k], c = v[b + k + h];
;                 v[b + k] = a + c;
;                 const cf d = a - c;
;                 const int m = k * (32 / s);
;                 const float wr = tw_cos(m), wi = INV ? tw_sin(m) : -tw_sin(m);
;                 v[b + k + h] = cf{d.x * wr - d.y * wi, d.x * wi + d.y * wr};
;             }
;         }
;     }
; }
	v_mov_b32_e32 v118, v84
	v_mov_b32_e32 v119, v85
	v_pk_add_f32 v[84:85], v[114:115], v[74:75]
	v_pk_add_f32 v[74:75], v[114:115], v[74:75] neg_lo:[0,1] neg_hi:[0,1]
	v_pk_mul_f32 v[100:101], v[74:75], s[18:19] op_sel_hi:[1,0]
	v_pk_fma_f32 v[114:115], v[74:75], s[18:19], v[100:101] op_sel:[0,0,1] op_sel_hi:[1,0,0] neg_lo:[0,0,1]
	v_pk_add_f32 v[74:75], v[94:95], v[80:81]
	v_pk_add_f32 v[80:81], v[94:95], v[80:81] neg_lo:[0,1] neg_hi:[0,1]
	v_pk_add_f32 v[94:95], v[80:81], 0 op_sel:[1,0] op_sel_hi:[0,0] neg_lo:[1,0]
	v_pk_add_f32 v[80:81], v[96:97], v[0:1]
	v_pk_add_f32 v[0:1], v[96:97], v[0:1] neg_lo:[0,1] neg_hi:[0,1]
	v_mul_f32_e32 v96, 0x3f3504f3, v1
	v_pk_fma_f32 v[0:1], v[0:1], s[96:97], v[96:97] op_sel_hi:[0,1,0] neg_lo:[0,0,1] neg_hi:[0,0,1]
	v_pk_add_f32 v[96:97], v[102:103], v[6:7]
	v_pk_add_f32 v[6:7], v[102:103], v[6:7] neg_lo:[0,1] neg_hi:[0,1]
	v_mov_b32_e32 v102, v6
	v_mov_b32_e32 v103, v7
	v_pk_add_f32 v[6:7], v[10:11], v[4:5]
	v_pk_add_f32 v[4:5], v[10:11], v[4:5] neg_lo:[0,1] neg_hi:[0,1]
	v_pk_add_f32 v[10:11], v[4:5], 0 op_sel:[1,0] op_sel_hi:[0,0] neg_lo:[1,0]
	v_pk_add_f32 v[4:5], v[104:105], v[14:15]
	v_pk_add_f32 v[14:15], v[104:105], v[14:15] neg_lo:[0,1] neg_hi:[0,1]
	v_mov_b32_e32 v104, v14
	v_mov_b32_e32 v105, v15
	v_pk_add_f32 v[14:15], v[78:79], v[2:3]
	v_pk_add_f32 v[2:3], v[78:79], v[2:3] neg_lo:[0,1] neg_hi:[0,1]
	v_pk_add_f32 v[78:79], v[2:3], 0 op_sel:[1,0] op_sel_hi:[0,0] neg_lo:[1,0]
	v_pk_add_f32 v[2:3], v[110:111], v[12:13]
	v_pk_add_f32 v[12:13], v[110:111], v[12:13] neg_lo:[0,1] neg_hi:[0,1]
	v_mov_b32_e32 v110, v12
	v_mov_b32_e32 v111, v13
	v_pk_add_f32 v[12:13], v[68:69], v[8:9]
	v_pk_add_f32 v[8:9], v[68:69], v[8:9] neg_lo:[0,1] neg_hi:[0,1]
	v_pk_add_f32 v[68:69], v[8:9], 0 op_sel:[1,0] op_sel_hi:[0,0] neg_lo:[1,0]
	v_pk_add_f32 v[8:9], v[116:117], v[92:93]
	v_pk_add_f32 v[92:93], v[116:117], v[92:93] neg_lo:[0,1] neg_hi:[0,1]
	v_mov_b32_e32 v116, v92
	v_mov_b32_e32 v117, v93
	v_pk_add_f32 v[92:93], v[112:113], v[16:17]
	v_pk_add_f32 v[16:17], v[112:113], v[16:17] neg_lo:[0,1] neg_hi:[0,1]
	v_pk_add_f32 v[100:101], v[16:17], 0 op_sel:[1,0] op_sel_hi:[0,0] neg_lo:[1,0]
	v_pk_add_f32 v[16:17], v[106:107], v[76:77]
	v_pk_add_f32 v[76:77], v[106:107], v[76:77] neg_lo:[0,1] neg_hi:[0,1]
	v_mov_b32_e32 v112, v76
	v_mov_b32_e32 v113, v77
	v_pk_add_f32 v[76:77], v[70:71], v[18:19]
	v_pk_add_f32 v[18:19], v[70:71], v[18:19] neg_lo:[0,1] neg_hi:[0,1]
	v_pk_add_f32 v[70:71], v[18:19], 0 op_sel:[1,0] op_sel_hi:[0,0] neg_lo:[1,0]
	v_pk_add_f32 v[18:19], v[108:109], v[82:83]
	v_pk_add_f32 v[82:83], v[108:109], v[82:83] neg_lo:[0,1] neg_hi:[0,1]
	v_mov_b32_e32 v108, v82
	v_mov_b32_e32 v109, v83
	v_pk_add_f32 v[82:83], v[90:91], v[72:73]
	v_pk_add_f32 v[72:73], v[90:91], v[72:73] neg_lo:[0,1] neg_hi:[0,1]
	v_pk_add_f32 v[90:91], v[72:73], 0 op_sel:[1,0] op_sel_hi:[0,0] neg_lo:[1,0]
	v_pk_add_f32 v[72:73], v[98:99], v[74:75]
	v_pk_add_f32 v[74:75], v[98:99], v[74:75] neg_lo:[0,1] neg_hi:[0,1]
	v_mov_b32_e32 v106, v74
	v_mov_b32_e32 v107, v75
	v_pk_add_f32 v[74:75], v[84:85], v[80:81]
	v_pk_add_f32 v[80:81], v[84:85], v[80:81] neg_lo:[0,1] neg_hi:[0,1]
	v_pk_add_f32 v[84:85], v[80:81], 0 op_sel:[1,0] op_sel_hi:[0,0] neg_lo:[1,0]
	v_pk_add_f32 v[80:81], v[118:119], v[94:95]
	v_pk_add_f32 v[94:95], v[118:119], v[94:95] neg_lo:[0,1] neg_hi:[0,1]
	v_mov_b32_e32 v118, v94
	v_mov_b32_e32 v119, v95
	v_pk_add_f32 v[94:95], v[114:115], v[0:1]
	v_pk_add_f32 v[0:1], v[114:115], v[0:1] neg_lo:[0,1] neg_hi:[0,1]
	v_pk_add_f32 v[98:99], v[0:1], 0 op_sel:[1,0] op_sel_hi:[0,0] neg_lo:[1,0]
	v_pk_add_f32 v[0:1], v[96:97], v[6:7]
	v_pk_add_f32 v[6:7], v[96:97], v[6:7] neg_lo:[0,1] neg_hi:[0,1]
	v_mov_b32_e32 v114, v6
	v_mov_b32_e32 v115, v7
	v_pk_add_f32 v[6:7], v[102:103], v[10:11]
	v_pk_add_f32 v[10:11], v[102:103], v[10:11] neg_lo:[0,1] neg_hi:[0,1]
	v_mov_b32_e32 v102, v10
	v_mov_b32_e32 v103, v11
	v_pk_add_f32 v[10:11], v[4:5], v[14:15]
	v_pk_add_f32 v[4:5], v[4:5], v[14:15] neg_lo:[0,1] neg_hi:[0,1]
	v_mov_b32_e32 v96, v4
	v_mov_b32_e32 v97, v5
	v_pk_add_f32 v[14:15], v[104:105], v[78:79] neg_lo:[0,1] neg_hi:[0,1]
	v_pk_add_f32 v[4:5], v[104:105], v[78:79]
	v_mov_b32_e32 v104, v14
	v_mov_b32_e32 v105, v15
	v_pk_add_f32 v[14:15], v[2:3], v[12:13]
	v_pk_add_f32 v[2:3], v[2:3], v[12:13] neg_lo:[0,1] neg_hi:[0,1]
	v_mov_b32_e32 v78, v2
	v_mov_b32_e32 v79, v3
	v_pk_add_f32 v[12:13], v[110:111], v[68:69] neg_lo:[0,1] neg_hi:[0,1]
	v_pk_add_f32 v[2:3], v[110:111], v[68:69]
	v_mov_b32_e32 v110, v12
	v_mov_b32_e32 v111, v13
	v_pk_add_f32 v[12:13], v[8:9], v[92:93]
	v_pk_add_f32 v[8:9], v[8:9], v[92:93] neg_lo:[0,1] neg_hi:[0,1]
	v_mov_b32_e32 v92, v8
	v_mov_b32_e32 v93, v9
	v_pk_add_f32 v[68:69], v[116:117], v[100:101] neg_lo:[0,1] neg_hi:[0,1]
	v_pk_add_f32 v[8:9], v[116:117], v[100:101]
	v_mov_b32_e32 v116, v68
	v_mov_b32_e32 v117, v69
	v_pk_add_f32 v[68:69], v[16:17], v[76:77]
	v_pk_add_f32 v[16:17], v[16:17], v[76:77] neg_lo:[0,1] neg_hi:[0,1]
	v_mov_b32_e32 v100, v16
	v_mov_b32_e32 v101, v17
	v_pk_add_f32 v[16:17], v[112:113], v[70:71]
	v_pk_add_f32 v[70:71], v[112:113], v[70:71] neg_lo:[0,1] neg_hi:[0,1]
	v_mov_b32_e32 v112, v70
	v_mov_b32_e32 v113, v71
	v_pk_add_f32 v[70:71], v[18:19], v[82:83]
	v_pk_add_f32 v[18:19], v[18:19], v[82:83] neg_lo:[0,1] neg_hi:[0,1]
	v_mov_b32_e32 v82, v18
	v_mov_b32_e32 v83, v19
	v_pk_add_f32 v[76:77], v[108:109], v[90:91] neg_lo:[0,1] neg_hi:[0,1]
	v_pk_add_f32 v[18:19], v[108:109], v[90:91]
	v_mov_b32_e32 v108, v76
	v_mov_b32_e32 v109, v77
	v_pk_add_f32 v[76:77], v[72:73], v[74:75]
	v_pk_add_f32 v[72:73], v[72:73], v[74:75] neg_lo:[0,1] neg_hi:[0,1]
	v_mov_b32_e32 v90, v72
	v_mov_b32_e32 v91, v73
; #define LAS __attribute__((address_space(3)))
; #define SINCOSPI(x, s, c) do { const float hx_ = 0.5f * (x); *(s) = __builtin_amdgcn_sinf(hx_); *(c) = __builtin_amdgcn_cosf(hx_); } while (0)
; #define OPAQUE_I(x) asm volatile("" : "+v"(x))
; DEV void fft_i1x2(LAS cf* buf0, LAS cf* buf1, cf (&y0)[8], cf (&y1)[8], int tid) {
;     OPAQUE_I(tid);
;     float sn, cs; SINCOSPI(-(float)tid * (2.0f / 8192.0f), &sn, &cs);
;     const cf w = cf{cs, sn}; cf wp = cf{1.f, 0.f};
;     cf v[16], u[16];
;     const LAS cf* p0 = buf0 + PADI(tid); const LAS cf* p1 = buf1 + PADI(tid);
; #pragma unroll
;     for (int p = 0; p < 16; ++p) { v[p] = cmulc(p0[544 * p], wp); u[p] = cmulc(p1[544 * p], wp); wp = cmul(wp, w); }
; DEV void fft_i2(LAS cf* buf, int t8) {
;     ...
;     dft_regs<32, true>(v);
; #pragma unroll
;     for (int q = 0; q < 32; ++q) pb[17 * q] = v[BR32[q]];
	v_pk_add_f32 v[74:75], v[106:107], v[84:85] neg_lo:[0,1] neg_hi:[0,1]
	v_pk_add_f32 v[72:73], v[106:107], v[84:85]
	v_mov_b32_e32 v106, v74
	v_mov_b32_e32 v107, v75
	v_pk_add_f32 v[74:75], v[80:81], v[94:95]
	v_pk_add_f32 v[80:81], v[80:81], v[94:95] neg_lo:[0,1] neg_hi:[0,1]
	v_mov_b32_e32 v94, v80
	v_mov_b32_e32 v95, v81
	v_pk_add_f32 v[84:85], v[118:119], v[98:99] neg_lo:[0,1] neg_hi:[0,1]
	v_pk_add_f32 v[80:81], v[118:119], v[98:99]
	v_mov_b32_e32 v118, v84
	v_mov_b32_e32 v119, v85
	ds_write2_b64 v86, v[0:1], v[68:69] offset1:17
	ds_write2_b64 v86, v[14:15], v[76:77] offset0:34 offset1:51
	ds_write2_b64 v86, v[10:11], v[70:71] offset0:68 offset1:85
	ds_write2_b64 v86, v[12:13], v[74:75] offset0:102 offset1:119
	ds_write2_b64 v86, v[6:7], v[16:17] offset0:136 offset1:153
	ds_write2_b64 v86, v[2:3], v[72:73] offset0:170 offset1:187
	ds_write2_b64 v86, v[4:5], v[18:19] offset0:204 offset1:221
	ds_write2_b64 v86, v[8:9], v[80:81] offset0:238 offset1:255
	ds_write2_b64 v87, v[114:115], v[100:101] offset0:16 offset1:33
	ds_write2_b64 v87, v[78:79], v[90:91] offset0:50 offset1:67
	ds_write2_b64 v87, v[96:97], v[82:83] offset0:84 offset1:101
	ds_write2_b64 v87, v[92:93], v[94:95] offset0:118 offset1:135
	ds_write2_b64 v87, v[102:103], v[112:113] offset0:152 offset1:169
	ds_write2_b64 v87, v[110:111], v[106:107] offset0:186 offset1:203
	ds_write2_b64 v87, v[104:105], v[108:109] offset0:220 offset1:237
	ds_write2_b64 v88, v[116:117], v[118:119] offset0:126 offset1:143
	s_mov_b32 s2, 0x1800000
	s_mov_b32 s2, 0x3000000
	s_nop 0
	s_mov_b32 s2, 0x4800000
	s_nop 0
	s_waitcnt lgkmcnt(0)
	s_barrier
	s_nop 0
	v_mov_b32_e32 v16, v21
	s_andn2_b64 vcc, exec, s[26:27]
	v_cvt_f32_i32_e32 v17, v16
	v_mul_f32_e32 v17, 0xb9800000, v17
	v_mul_f32_e32 v17, 0.5, v17
	v_sin_f32_e32 v93, v17
	v_cos_f32_e32 v92, v17
	v_ashrrev_i32_e32 v17, 4, v16
	v_add_lshl_u32 v16, v17, v16, 3
	v_add_u32_e32 v163, 0, v16
	v_add_u32_e32 v164, s33, v16
	ds_read_b64 v[166:167], v163
	ds_read_b64 v[168:169], v164
	ds_read_b64 v[170:171], v163 offset:4352
	ds_read_b64 v[172:173], v164 offset:4352
	ds_read_b64 v[174:175], v163 offset:8704
	ds_read_b64 v[176:177], v164 offset:8704
	ds_read_b64 v[178:179], v163 offset:13056
	ds_read_b64 v[180:181], v164 offset:13056
	ds_read_b64 v[182:183], v163 offset:17408
	ds_read_b64 v[184:185], v164 offset:17408
	ds_read_b64 v[186:187], v163 offset:21760
	ds_read_b64 v[188:189], v164 offset:21760
	ds_read_b64 v[190:191], v163 offset:26112
	s_waitcnt lgkmcnt(12)
	v_pk_mul_f32 v[18:19], v[166:167], v[66:67] op_sel:[1,1] op_sel_hi:[1,0]
	v_pk_fma_f32 v[76:77], v[166:167], v[66:67], v[18:19] op_sel_hi:[0,1,1] neg_hi:[1,0,0]
	ds_read_b64 v[166:167], v164 offset:26112
	s_waitcnt lgkmcnt(12)
	v_pk_mul_f32 v[18:19], v[168:169], v[66:67] op_sel:[1,1] op_sel_hi:[1,0]
	v_pk_fma_f32 v[16:17], v[168:169], v[66:67], v[18:19] op_sel_hi:[0,1,1] neg_hi:[1,0,0]
	s_nop 0
	v_pk_mul_f32 v[18:19], v[66:67], v[92:93] op_sel:[1,1] op_sel_hi:[1,0] neg_lo:[1,0]
	v_pk_fma_f32 v[66:67], v[66:67], v[92:93], v[18:19] op_sel_hi:[0,1,1]
	ds_read_b64 v[168:169], v163 offset:30464
	s_waitcnt lgkmcnt(12)
	v_pk_mul_f32 v[68:69], v[170:171], v[66:67] op_sel:[1,1] op_sel_hi:[1,0]
	v_pk_fma_f32 v[78:79], v[170:171], v[66:67], v[68:69] op_sel_hi:[0,1,1] neg_hi:[1,0,0]
	ds_read_b64 v[170:171], v164 offset:30464
	s_waitcnt lgkmcnt(12)
	v_pk_mul_f32 v[68:69], v[172:173], v[66:67] op_sel:[1,1] op_sel_hi:[1,0]
	v_pk_fma_f32 v[18:19], v[172:173], v[66:67], v[68:69] op_sel_hi:[0,1,1] neg_hi:[1,0,0]
	s_nop 0
	v_pk_mul_f32 v[68:69], v[66:67], v[92:93] op_sel:[1,1] op_sel_hi:[1,0] neg_lo:[1,0]
	v_pk_fma_f32 v[70:71], v[66:67], v[92:93], v[68:69] op_sel_hi:[0,1,1]
	ds_read_b64 v[172:173], v163 offset:34816
	s_waitcnt lgkmcnt(12)
	v_pk_mul_f32 v[68:69], v[174:175], v[70:71] op_sel:[1,1] op_sel_hi:[1,0]
	v_pk_fma_f32 v[82:83], v[174:175], v[70:71], v[68:69] op_sel_hi:[0,1,1] neg_hi:[1,0,0]
	ds_read_b64 v[174:175], v164 offset:34816
	s_waitcnt lgkmcnt(12)
	v_pk_mul_f32 v[68:69], v[176:177], v[70:71] op_sel:[1,1] op_sel_hi:[1,0]
	v_pk_fma_f32 v[66:67], v[176:177], v[70:71], v[68:69] op_sel_hi:[0,1,1] neg_hi:[1,0,0]
	s_nop 0
	v_pk_mul_f32 v[68:69], v[70:71], v[92:93] op_sel:[1,1] op_sel_hi:[1,0] neg_lo:[1,0]
	v_pk_fma_f32 v[70:71], v[70:71], v[92:93], v[68:69] op_sel_hi:[0,1,1]
	ds_read_b64 v[176:177], v163 offset:39168
	s_waitcnt lgkmcnt(12)
	v_pk_mul_f32 v[72:73], v[178:179], v[70:71] op_sel:[1,1] op_sel_hi:[1,0]
	v_pk_fma_f32 v[84:85], v[178:179], v[70:71], v[72:73] op_sel_hi:[0,1,1] neg_hi:[1,0,0]
	ds_read_b64 v[178:179], v164 offset:39168
	s_waitcnt lgkmcnt(12)
	v_pk_mul_f32 v[72:73], v[180:181], v[70:71] op_sel:[1,1] op_sel_hi:[1,0]
	v_pk_fma_f32 v[68:69], v[180:181], v[70:71], v[72:73] op_sel_hi:[0,1,1] neg_hi:[1,0,0]
	s_nop 0
	v_pk_mul_f32 v[72:73], v[70:71], v[92:93] op_sel:[1,1] op_sel_hi:[1,0] neg_lo:[1,0]
	v_pk_fma_f32 v[74:75], v[70:71], v[92:93], v[72:73] op_sel_hi:[0,1,1]
	ds_read_b64 v[180:181], v163 offset:43520
	s_waitcnt lgkmcnt(12)
	v_pk_mul_f32 v[72:73], v[182:183], v[74:75] op_sel:[1,1] op_sel_hi:[1,0]
	v_pk_fma_f32 v[86:87], v[182:183], v[74:75], v[72:73] op_sel_hi:[0,1,1] neg_hi:[1,0,0]
	ds_read_b64 v[182:183], v164 offset:43520
	s_waitcnt lgkmcnt(12)
	v_pk_mul_f32 v[72:73], v[184:185], v[74:75] op_sel:[1,1] op_sel_hi:[1,0]
	v_pk_fma_f32 v[70:71], v[184:185], v[74:75], v[72:73] op_sel_hi:[0,1,1] neg_hi:[1,0,0]
	s_nop 0
	v_pk_mul_f32 v[72:73], v[74:75], v[92:93] op_sel:[1,1] op_sel_hi:[1,0] neg_lo:[1,0]
	v_pk_fma_f32 v[74:75], v[74:75], v[92:93], v[72:73] op_sel_hi:[0,1,1]
	ds_read_b64 v[184:185], v163 offset:47872
	s_waitcnt lgkmcnt(12)
; #define LAS __attribute__((address_space(3)))
; #define SYNC() __syncthreads()
; #define SINCOSPI(x, s, c) do { const float hx_ = 0.5f * (x); *(s) = __builtin_amdgcn_sinf(hx_); *(c) = __builtin_amdgcn_cosf(hx_); } while (0)
; #define OPAQUE_I(x) asm volatile("" : "+v"(x))
; DEV void fft_i1x2(LAS cf* buf0, LAS cf* buf1, cf (&y0)[8], cf (&y1)[8], int tid) {
;     OPAQUE_I(tid);
;     float sn, cs; SINCOSPI(-(float)tid * (2.0f / 8192.0f), &sn, &cs);
;     const cf w = cf{cs, sn}; cf wp = cf{1.f, 0.f};
;     cf v[16], u[16];
;     const LAS cf* p0 = buf0 + PADI(tid); const LAS cf* p1 = buf1 + PADI(tid);
; #pragma unroll
;     for (int p = 0; p < 16; ++p) { v[p] = cmulc(p0[544 * p], wp); u[p] = cmulc(p1[544 * p], wp); wp = cmul(wp, w); }
; DEV void hyena_units(int c0, int cstride, const bf16_t* UT, bf16_t* YHT, const unsigned* KF, const float* convw  , const float* convb  , const float* hyb  , LAS unsigned char* lds, int tid, bool abl = false) {
;     ...
;             } else fft_i1x2(buf0, buf1, y[0], y[1], tid);
;             SYNC();
;             hyena_commit_rows(lds, r, tid);
;             if (o == 1 && c + cstride < 1024) hyena_issue_rows(UT, 0, c + cstride, r, tid);
	v_pk_mul_f32 v[80:81], v[186:187], v[74:75] op_sel:[1,1] op_sel_hi:[1,0]
	v_pk_fma_f32 v[90:91], v[186:187], v[74:75], v[80:81] op_sel_hi:[0,1,1] neg_hi:[1,0,0]
	ds_read_b64 v[186:187], v164 offset:47872
	s_waitcnt lgkmcnt(12)
	v_pk_mul_f32 v[80:81], v[188:189], v[74:75] op_sel:[1,1] op_sel_hi:[1,0]
	v_pk_fma_f32 v[72:73], v[188:189], v[74:75], v[80:81] op_sel_hi:[0,1,1] neg_hi:[1,0,0]
	s_nop 0
	v_pk_mul_f32 v[80:81], v[74:75], v[92:93] op_sel:[1,1] op_sel_hi:[1,0] neg_lo:[1,0]
	v_pk_fma_f32 v[88:89], v[74:75], v[92:93], v[80:81] op_sel_hi:[0,1,1]
	ds_read_b64 v[188:189], v163 offset:52224
	s_waitcnt lgkmcnt(12)
	v_pk_mul_f32 v[80:81], v[190:191], v[88:89] op_sel:[1,1] op_sel_hi:[1,0]
	v_pk_fma_f32 v[94:95], v[190:191], v[88:89], v[80:81] op_sel_hi:[0,1,1] neg_hi:[1,0,0]
	ds_read_b64 v[190:191], v164 offset:52224
	s_waitcnt lgkmcnt(12)
	v_pk_mul_f32 v[80:81], v[166:167], v[88:89] op_sel:[1,1] op_sel_hi:[1,0]
	v_pk_fma_f32 v[74:75], v[166:167], v[88:89], v[80:81] op_sel_hi:[0,1,1] neg_hi:[1,0,0]
	s_nop 0
	v_pk_mul_f32 v[80:81], v[88:89], v[92:93] op_sel:[1,1] op_sel_hi:[1,0] neg_lo:[1,0]
	v_pk_fma_f32 v[88:89], v[88:89], v[92:93], v[80:81] op_sel_hi:[0,1,1]
	ds_read_b64 v[166:167], v163 offset:56576
	s_waitcnt lgkmcnt(12)
	v_pk_mul_f32 v[96:97], v[168:169], v[88:89] op_sel:[1,1] op_sel_hi:[1,0]
	v_pk_fma_f32 v[98:99], v[168:169], v[88:89], v[96:97] op_sel_hi:[0,1,1] neg_hi:[1,0,0]
	ds_read_b64 v[168:169], v164 offset:56576
	s_waitcnt lgkmcnt(12)
	v_pk_mul_f32 v[96:97], v[170:171], v[88:89] op_sel:[1,1] op_sel_hi:[1,0]
	v_pk_fma_f32 v[80:81], v[170:171], v[88:89], v[96:97] op_sel_hi:[0,1,1] neg_hi:[1,0,0]
	s_nop 0
	v_pk_mul_f32 v[96:97], v[88:89], v[92:93] op_sel:[1,1] op_sel_hi:[1,0] neg_lo:[1,0]
	v_pk_fma_f32 v[102:103], v[88:89], v[92:93], v[96:97] op_sel_hi:[0,1,1]
	ds_read_b64 v[170:171], v163 offset:60928
	s_waitcnt lgkmcnt(12)
	v_pk_mul_f32 v[96:97], v[172:173], v[102:103] op_sel:[1,1] op_sel_hi:[1,0]
	v_pk_fma_f32 v[100:101], v[172:173], v[102:103], v[96:97] op_sel_hi:[0,1,1] neg_hi:[1,0,0]
	ds_read_b64 v[172:173], v164 offset:60928
	s_waitcnt lgkmcnt(12)
	v_pk_mul_f32 v[96:97], v[174:175], v[102:103] op_sel:[1,1] op_sel_hi:[1,0]
	v_pk_fma_f32 v[88:89], v[174:175], v[102:103], v[96:97] op_sel_hi:[0,1,1] neg_hi:[1,0,0]
	s_nop 0
	v_pk_mul_f32 v[96:97], v[102:103], v[92:93] op_sel:[1,1] op_sel_hi:[1,0] neg_lo:[1,0]
	v_pk_fma_f32 v[102:103], v[102:103], v[92:93], v[96:97] op_sel_hi:[0,1,1]
	ds_read_b64 v[174:175], v163 offset:65280
	s_waitcnt lgkmcnt(12)
	v_pk_mul_f32 v[104:105], v[176:177], v[102:103] op_sel:[1,1] op_sel_hi:[1,0]
	v_pk_fma_f32 v[112:113], v[176:177], v[102:103], v[104:105] op_sel_hi:[0,1,1] neg_hi:[1,0,0]
	ds_read_b64 v[176:177], v164 offset:65280
	s_waitcnt lgkmcnt(12)
	v_pk_mul_f32 v[104:105], v[178:179], v[102:103] op_sel:[1,1] op_sel_hi:[1,0]
	v_pk_fma_f32 v[96:97], v[178:179], v[102:103], v[104:105] op_sel_hi:[0,1,1] neg_hi:[1,0,0]
	s_nop 0
	v_pk_mul_f32 v[104:105], v[102:103], v[92:93] op_sel:[1,1] op_sel_hi:[1,0] neg_lo:[1,0]
	v_pk_fma_f32 v[106:107], v[102:103], v[92:93], v[104:105] op_sel_hi:[0,1,1]
	s_waitcnt lgkmcnt(11)
	v_pk_mul_f32 v[104:105], v[180:181], v[106:107] op_sel:[1,1] op_sel_hi:[1,0]
	v_pk_fma_f32 v[116:117], v[180:181], v[106:107], v[104:105] op_sel_hi:[0,1,1] neg_hi:[1,0,0]
	s_waitcnt lgkmcnt(10)
	v_pk_mul_f32 v[104:105], v[182:183], v[106:107] op_sel:[1,1] op_sel_hi:[1,0]
	v_pk_fma_f32 v[102:103], v[182:183], v[106:107], v[104:105] op_sel_hi:[0,1,1] neg_hi:[1,0,0]
	s_nop 0
	v_pk_mul_f32 v[104:105], v[106:107], v[92:93] op_sel:[1,1] op_sel_hi:[1,0] neg_lo:[1,0]
	v_pk_fma_f32 v[106:107], v[106:107], v[92:93], v[104:105] op_sel_hi:[0,1,1]
	s_waitcnt lgkmcnt(9)
	v_pk_mul_f32 v[108:109], v[184:185], v[106:107] op_sel:[1,1] op_sel_hi:[1,0]
	v_pk_fma_f32 v[118:119], v[184:185], v[106:107], v[108:109] op_sel_hi:[0,1,1] neg_hi:[1,0,0]
	s_waitcnt lgkmcnt(8)
	v_pk_mul_f32 v[108:109], v[186:187], v[106:107] op_sel:[1,1] op_sel_hi:[1,0]
	v_pk_fma_f32 v[104:105], v[186:187], v[106:107], v[108:109] op_sel_hi:[0,1,1] neg_hi:[1,0,0]
	s_nop 0
	v_pk_mul_f32 v[108:109], v[106:107], v[92:93] op_sel:[1,1] op_sel_hi:[1,0] neg_lo:[1,0]
	v_pk_fma_f32 v[110:111], v[106:107], v[92:93], v[108:109] op_sel_hi:[0,1,1]
	s_waitcnt lgkmcnt(7)
	v_pk_mul_f32 v[108:109], v[188:189], v[110:111] op_sel:[1,1] op_sel_hi:[1,0]
	v_pk_fma_f32 v[120:121], v[188:189], v[110:111], v[108:109] op_sel_hi:[0,1,1] neg_hi:[1,0,0]
	s_waitcnt lgkmcnt(6)
	v_pk_mul_f32 v[108:109], v[190:191], v[110:111] op_sel:[1,1] op_sel_hi:[1,0]
	v_pk_fma_f32 v[106:107], v[190:191], v[110:111], v[108:109] op_sel_hi:[0,1,1] neg_hi:[1,0,0]
	s_nop 0
	v_pk_mul_f32 v[108:109], v[110:111], v[92:93] op_sel:[1,1] op_sel_hi:[1,0] neg_lo:[1,0]
	v_pk_fma_f32 v[110:111], v[110:111], v[92:93], v[108:109] op_sel_hi:[0,1,1]
	s_waitcnt lgkmcnt(5)
	v_pk_mul_f32 v[114:115], v[166:167], v[110:111] op_sel:[1,1] op_sel_hi:[1,0]
	v_pk_fma_f32 v[122:123], v[166:167], v[110:111], v[114:115] op_sel_hi:[0,1,1] neg_hi:[1,0,0]
	s_waitcnt lgkmcnt(4)
	v_pk_mul_f32 v[114:115], v[168:169], v[110:111] op_sel:[1,1] op_sel_hi:[1,0]
	v_pk_fma_f32 v[108:109], v[168:169], v[110:111], v[114:115] op_sel_hi:[0,1,1] neg_hi:[1,0,0]
	s_nop 0
	v_pk_mul_f32 v[114:115], v[110:111], v[92:93] op_sel:[1,1] op_sel_hi:[1,0] neg_lo:[1,0]
	v_pk_fma_f32 v[126:127], v[110:111], v[92:93], v[114:115] op_sel_hi:[0,1,1]
	s_waitcnt lgkmcnt(3)
	v_pk_mul_f32 v[114:115], v[170:171], v[126:127] op_sel:[1,1] op_sel_hi:[1,0]
	v_pk_fma_f32 v[124:125], v[170:171], v[126:127], v[114:115] op_sel_hi:[0,1,1] neg_hi:[1,0,0]
	s_waitcnt lgkmcnt(2)
	v_pk_mul_f32 v[114:115], v[172:173], v[126:127] op_sel:[1,1] op_sel_hi:[1,0]
	v_pk_fma_f32 v[110:111], v[172:173], v[126:127], v[114:115] op_sel_hi:[0,1,1] neg_hi:[1,0,0]
	s_nop 0
	v_pk_mul_f32 v[114:115], v[126:127], v[92:93] op_sel:[1,1] op_sel_hi:[1,0] neg_lo:[1,0]
	v_pk_fma_f32 v[126:127], v[126:127], v[92:93], v[114:115] op_sel_hi:[0,1,1]
	s_waitcnt lgkmcnt(1)
	v_pk_mul_f32 v[114:115], v[174:175], v[126:127] op_sel:[1,1] op_sel_hi:[1,0]
	v_pk_fma_f32 v[92:93], v[174:175], v[126:127], v[114:115] op_sel_hi:[0,1,1] neg_hi:[1,0,0]
	s_waitcnt lgkmcnt(0)
	v_pk_mul_f32 v[164:165], v[176:177], v[126:127] op_sel:[1,1] op_sel_hi:[1,0]
	v_pk_fma_f32 v[114:115], v[176:177], v[126:127], v[164:165] op_sel_hi:[0,1,1] neg_hi:[1,0,0]
	s_barrier
	s_waitcnt vmcnt(3)
	ds_write_b128 v128, v[222:225]
	s_waitcnt vmcnt(2)
	ds_write_b128 v128, v[226:229] offset:8192
	s_waitcnt vmcnt(1)
	ds_write_b128 v128, v[236:239] offset:16384
	s_waitcnt vmcnt(0)
	ds_write_b128 v128, v[240:243] offset:24576
	s_cbranch_vccnz .LBB0_518
	s_andn2_b64 vcc, exec, s[20:21]
	s_cbranch_vccnz .LBB0_518
	global_load_dwordx4 v[0:3], v[58:59], off
	global_load_dwordx4 v[4:7], v[60:61], off
	global_load_dwordx4 v[8:11], v[62:63], off
	global_load_dwordx4 v[12:15], v[64:65], off
	s_branch .LBB0_518
